# speedup vs baseline: 1.0025x; 1.0025x over previous
; __device__ __forceinline__ float vfma(float a, float b, float c) { float d; asm("v_fma_f32 %0, %1, %2, %3" : "=v"(d) : "v"(a), "v"(b), "v"(c)); return d; }
; __device__ __forceinline__ float step_compute(float (&S)[4], const StepOp& o) {
;     float d1 = vmul(S[0], o.kk[0]), d2 = vmul(S[0], o.wr[0]), e1 = vmul(S[1], o.kk[1]), e2 = vmul(S[1], o.wr[1]);
;     d1 = vfma(S[2], o.kk[2], d1); d2 = vfma(S[2], o.wr[2], d2); e1 = vfma(S[3], o.kk[3], e1); e2 = vfma(S[3], o.wr[3], e2);
;     d1 = vadd(d1, e1); d2 = vadd(d2, e2);
;     float t0, t1, t2, t3;
;     asm volatile(
;         "v_mul_f32 %[t0], %[s0], %[w0]\n\t"
;         "v_mul_f32 %[t1], %[s1], %[w1]\n\t"
;         "v_add_f32_dpp %[d1], %[d1], %[d1] quad_perm:[1,0,3,2] row_mask:0xf bank_mask:0xf bound_ctrl:1\n\t"
;         "v_add_f32_dpp %[d2], %[d2], %[d2] quad_perm:[1,0,3,2] row_mask:0xf bank_mask:0xf bound_ctrl:1\n\t"
;         "v_mul_f32 %[t2], %[s2], %[w2]\n\t"
;         "v_add_f32_dpp %[d1], %[d1], %[d1] quad_perm:[2,3,0,1] row_mask:0xf bank_mask:0xf bound_ctrl:1\n\t"
;         "v_add_f32_dpp %[d2], %[d2], %[d2] quad_perm:[2,3,0,1] row_mask:0xf bank_mask:0xf bound_ctrl:1\n\t"
;         "v_mul_f32 %[t3], %[s3], %[w3]\n\t"
;         "v_add_f32_dpp %[d1], %[d1], %[d1] row_half_mirror row_mask:0xf bank_mask:0xf bound_ctrl:1\n\t"
;         "v_add_f32_dpp %[d2], %[d2], %[d2] row_half_mirror row_mask:0xf bank_mask:0xf bound_ctrl:1\n\t"
;         "v_fma_f32 %[t0], %[v], %[k0], %[t0]\n\t"
;         "v_add_f32_dpp %[d1], %[d1], %[d1] row_mirror row_mask:0xf bank_mask:0xf bound_ctrl:1\n\t"
;         "v_add_f32_dpp %[d2], %[d2], %[d2] row_mirror row_mask:0xf bank_mask:0xf bound_ctrl:1\n\t"
;         "v_fma_f32 %[t1], %[v], %[k1], %[t1]\n\t"
;         "v_fma_f32 %[t2], %[v], %[k2], %[t2]\n\t"
;         "v_fma_f32 %[t3], %[v], %[k3], %[t3]"
;         : [t0] "=&v"(t0), [t1] "=&v"(t1), [t2] "=&v"(t2), [t3] "=&v"(t3), [d1] "+v"(d1), [d2] "+v"(d2)
;         : [s0] "v"(S[0]), [s1] "v"(S[1]), [s2] "v"(S[2]), [s3] "v"(S[3]), [w0] "v"(o.w[0]), [w1] "v"(o.w[1]), [w2] "v"(o.w[2]), [w3] "v"(o.w[3]),
;           [k0] "v"(o.k[0]), [k1] "v"(o.k[1]), [k2] "v"(o.k[2]), [k3] "v"(o.k[3]), [v] "v"(o.q[0]));
;     S[0] = vnfma(d1, o.b[0], t0); S[1] = vnfma(d1, o.b[1], t1); S[2] = vnfma(d1, o.b[2], t2); S[3] = vnfma(d1, o.b[3], t3);
;     return vfma(o.q[0], o.q[2], vnfma(d1, o.q[1], d2));
; }
.LBB0_774:
	v_cndmask_b32_e64 v2, 0, 1, s[50:51]
	v_cmp_ne_u32_e64 s[8:9], 1, v2
	s_andn2_b64 vcc, exec, s[50:51]
	s_mov_b64 s[78:79], -1
	s_cbranch_vccnz .LBB0_776
	s_and_b64 s[78:79], s[74:75], exec
	s_cselect_b32 s10, 0, s91
	v_add_u32_e32 v3, s10, v149
	s_cselect_b32 s10, s93, s92
	v_add_u32_e32 v4, s10, v150
	ds_read_b128 v[160:163], v3 offset:0
	ds_read_b128 v[168:171], v3 offset:256
	ds_read_b128 v[172:175], v3 offset:512
	ds_read_b128 v[180:183], v3 offset:1024
	ds_read_b128 v[184:187], v4
	ds_read_b128 v[176:179], v3 offset:768
	v_add_u32_e32 v2, s42, v148
	s_mov_b64 s[78:79], 0
	ds_read_b128 v[188:191], v3 offset:1536
	ds_read_b128 v[192:195], v3 offset:1792
	ds_read_b128 v[196:199], v3 offset:2048
	ds_read_b128 v[204:207], v3 offset:2560
	ds_read_b128 v[208:211], v4 offset:1536
	ds_read_b128 v[200:203], v3 offset:2304
	s_waitcnt lgkmcnt(6)
	v_mul_f32 v160, v38, v160
	v_mul_f32 v168, v38, v168
	v_mul_f32 v161, v39, v161
	v_mul_f32 v169, v39, v169
	v_fma_f32 v160, v40, v162, v160
	v_fma_f32 v168, v40, v170, v168
	v_fma_f32 v161, v41, v163, v161
	v_fma_f32 v169, v41, v171, v169
	v_add_f32 v160, v160, v161
	v_add_f32 v168, v168, v169
	v_mul_f32 v172, v38, v172
	v_mul_f32 v173, v39, v173
	v_add_f32_dpp v160, v160, v160 quad_perm:[1,0,3,2] row_mask:0xf bank_mask:0xf bound_ctrl:1
	v_add_f32_dpp v168, v168, v168 quad_perm:[1,0,3,2] row_mask:0xf bank_mask:0xf bound_ctrl:1
	v_mul_f32 v174, v40, v174
	v_add_f32_dpp v160, v160, v160 quad_perm:[2,3,0,1] row_mask:0xf bank_mask:0xf bound_ctrl:1
	v_add_f32_dpp v168, v168, v168 quad_perm:[2,3,0,1] row_mask:0xf bank_mask:0xf bound_ctrl:1
	v_mul_f32 v175, v41, v175
	v_add_f32_dpp v160, v160, v160 row_half_mirror row_mask:0xf bank_mask:0xf bound_ctrl:1
	v_add_f32_dpp v168, v168, v168 row_half_mirror row_mask:0xf bank_mask:0xf bound_ctrl:1
	v_fma_f32 v172, v184, v180, v172
	v_add_f32_dpp v160, v160, v160 row_mirror row_mask:0xf bank_mask:0xf bound_ctrl:1
	v_add_f32_dpp v168, v168, v168 row_mirror row_mask:0xf bank_mask:0xf bound_ctrl:1
	v_fma_f32 v173, v184, v181, v173
	v_fma_f32 v174, v184, v182, v174
	v_fma_f32 v175, v184, v183, v175
	v_fma_f32 v159, -v160, v176, v172
	v_fma_f32 v164, -v160, v177, v173
	v_fma_f32 v165, -v160, v178, v174
	v_fma_f32 v167, -v160, v179, v175
	v_fma_f32 v168, -v160, v185, v168
	v_fma_f32 v168, v184, v186, v168
	ds_write_b32 v2, v168
	ds_read_b128 v[160:163], v3 offset:3072
	ds_read_b128 v[168:171], v3 offset:3328
	ds_read_b128 v[172:175], v3 offset:3584
	ds_read_b128 v[180:183], v3 offset:4096
	ds_read_b128 v[184:187], v4 offset:3072
	ds_read_b128 v[176:179], v3 offset:3840
	s_waitcnt lgkmcnt(7)
	v_mul_f32 v188, v159, v188
	v_mul_f32 v192, v159, v192
	v_mul_f32 v189, v164, v189
	v_mul_f32 v193, v164, v193
	v_fma_f32 v188, v165, v190, v188
	v_fma_f32 v192, v165, v194, v192
	v_fma_f32 v189, v167, v191, v189
	v_fma_f32 v193, v167, v195, v193
	v_add_f32 v188, v188, v189
	v_add_f32 v192, v192, v193
	v_mul_f32 v196, v159, v196
	v_mul_f32 v197, v164, v197
	v_add_f32_dpp v188, v188, v188 quad_perm:[1,0,3,2] row_mask:0xf bank_mask:0xf bound_ctrl:1
	v_add_f32_dpp v192, v192, v192 quad_perm:[1,0,3,2] row_mask:0xf bank_mask:0xf bound_ctrl:1
	v_mul_f32 v198, v165, v198
	v_add_f32_dpp v188, v188, v188 quad_perm:[2,3,0,1] row_mask:0xf bank_mask:0xf bound_ctrl:1
	v_add_f32_dpp v192, v192, v192 quad_perm:[2,3,0,1] row_mask:0xf bank_mask:0xf bound_ctrl:1
	v_mul_f32 v199, v167, v199
	v_add_f32_dpp v188, v188, v188 row_half_mirror row_mask:0xf bank_mask:0xf bound_ctrl:1
	v_add_f32_dpp v192, v192, v192 row_half_mirror row_mask:0xf bank_mask:0xf bound_ctrl:1
	v_fma_f32 v196, v208, v204, v196
	v_add_f32_dpp v188, v188, v188 row_mirror row_mask:0xf bank_mask:0xf bound_ctrl:1
	v_add_f32_dpp v192, v192, v192 row_mirror row_mask:0xf bank_mask:0xf bound_ctrl:1
	v_fma_f32 v197, v208, v205, v197
	v_fma_f32 v198, v208, v206, v198
	v_fma_f32 v199, v208, v207, v199
	v_fma_f32 v159, -v188, v200, v196
	v_fma_f32 v164, -v188, v201, v197
	v_fma_f32 v165, -v188, v202, v198
	v_fma_f32 v167, -v188, v203, v199
	v_fma_f32 v192, -v188, v209, v192
	v_fma_f32 v192, v208, v210, v192
	ds_write_b32 v2, v192 offset:64
	ds_read_b128 v[188:191], v3 offset:4608
	ds_read_b128 v[192:195], v3 offset:4864
	ds_read_b128 v[196:199], v3 offset:5120
	ds_read_b128 v[204:207], v3 offset:5632
	ds_read_b128 v[208:211], v4 offset:4608
	ds_read_b128 v[200:203], v3 offset:5376
	s_waitcnt lgkmcnt(7)
	v_mul_f32 v160, v159, v160
	v_mul_f32 v168, v159, v168
	v_mul_f32 v161, v164, v161
	v_mul_f32 v169, v164, v169
	v_fma_f32 v160, v165, v162, v160
	v_fma_f32 v168, v165, v170, v168
	v_fma_f32 v161, v167, v163, v161
	v_fma_f32 v169, v167, v171, v169
	v_add_f32 v160, v160, v161
	v_add_f32 v168, v168, v169
	v_mul_f32 v172, v159, v172
	v_mul_f32 v173, v164, v173
	v_add_f32_dpp v160, v160, v160 quad_perm:[1,0,3,2] row_mask:0xf bank_mask:0xf bound_ctrl:1
	v_add_f32_dpp v168, v168, v168 quad_perm:[1,0,3,2] row_mask:0xf bank_mask:0xf bound_ctrl:1
	v_mul_f32 v174, v165, v174
	v_add_f32_dpp v160, v160, v160 quad_perm:[2,3,0,1] row_mask:0xf bank_mask:0xf bound_ctrl:1
	v_add_f32_dpp v168, v168, v168 quad_perm:[2,3,0,1] row_mask:0xf bank_mask:0xf bound_ctrl:1
	v_mul_f32 v175, v167, v175
	v_add_f32_dpp v160, v160, v160 row_half_mirror row_mask:0xf bank_mask:0xf bound_ctrl:1
	v_add_f32_dpp v168, v168, v168 row_half_mirror row_mask:0xf bank_mask:0xf bound_ctrl:1
	v_fma_f32 v172, v184, v180, v172
	v_add_f32_dpp v160, v160, v160 row_mirror row_mask:0xf bank_mask:0xf bound_ctrl:1
	v_add_f32_dpp v168, v168, v168 row_mirror row_mask:0xf bank_mask:0xf bound_ctrl:1
	v_fma_f32 v173, v184, v181, v173
	v_fma_f32 v174, v184, v182, v174
	v_fma_f32 v175, v184, v183, v175
	v_fma_f32 v159, -v160, v176, v172
	v_fma_f32 v164, -v160, v177, v173
	v_fma_f32 v165, -v160, v178, v174
	v_fma_f32 v167, -v160, v179, v175
	v_fma_f32 v168, -v160, v185, v168
	v_fma_f32 v168, v184, v186, v168
	ds_write_b32 v2, v168 offset:128
	ds_read_b128 v[160:163], v3 offset:6144
	ds_read_b128 v[168:171], v3 offset:6400
	ds_read_b128 v[172:175], v3 offset:6656
	ds_read_b128 v[180:183], v3 offset:7168
	ds_read_b128 v[184:187], v4 offset:6144
	ds_read_b128 v[176:179], v3 offset:6912
	s_waitcnt lgkmcnt(7)
; __device__ __forceinline__ float vfma(float a, float b, float c) { float d; asm("v_fma_f32 %0, %1, %2, %3" : "=v"(d) : "v"(a), "v"(b), "v"(c)); return d; }
; __device__ __forceinline__ float step_compute(float (&S)[4], const StepOp& o) {
;     float d1 = vmul(S[0], o.kk[0]), d2 = vmul(S[0], o.wr[0]), e1 = vmul(S[1], o.kk[1]), e2 = vmul(S[1], o.wr[1]);
;     d1 = vfma(S[2], o.kk[2], d1); d2 = vfma(S[2], o.wr[2], d2); e1 = vfma(S[3], o.kk[3], e1); e2 = vfma(S[3], o.wr[3], e2);
;     d1 = vadd(d1, e1); d2 = vadd(d2, e2);
;     float t0, t1, t2, t3;
;     asm volatile(
;         "v_mul_f32 %[t0], %[s0], %[w0]\n\t"
;         "v_mul_f32 %[t1], %[s1], %[w1]\n\t"
;         "v_add_f32_dpp %[d1], %[d1], %[d1] quad_perm:[1,0,3,2] row_mask:0xf bank_mask:0xf bound_ctrl:1\n\t"
;         "v_add_f32_dpp %[d2], %[d2], %[d2] quad_perm:[1,0,3,2] row_mask:0xf bank_mask:0xf bound_ctrl:1\n\t"
;         "v_mul_f32 %[t2], %[s2], %[w2]\n\t"
;         "v_add_f32_dpp %[d1], %[d1], %[d1] quad_perm:[2,3,0,1] row_mask:0xf bank_mask:0xf bound_ctrl:1\n\t"
;         "v_add_f32_dpp %[d2], %[d2], %[d2] quad_perm:[2,3,0,1] row_mask:0xf bank_mask:0xf bound_ctrl:1\n\t"
;         "v_mul_f32 %[t3], %[s3], %[w3]\n\t"
;         "v_add_f32_dpp %[d1], %[d1], %[d1] row_half_mirror row_mask:0xf bank_mask:0xf bound_ctrl:1\n\t"
;         "v_add_f32_dpp %[d2], %[d2], %[d2] row_half_mirror row_mask:0xf bank_mask:0xf bound_ctrl:1\n\t"
;         "v_fma_f32 %[t0], %[v], %[k0], %[t0]\n\t"
;         "v_add_f32_dpp %[d1], %[d1], %[d1] row_mirror row_mask:0xf bank_mask:0xf bound_ctrl:1\n\t"
;         "v_add_f32_dpp %[d2], %[d2], %[d2] row_mirror row_mask:0xf bank_mask:0xf bound_ctrl:1\n\t"
;         "v_fma_f32 %[t1], %[v], %[k1], %[t1]\n\t"
;         "v_fma_f32 %[t2], %[v], %[k2], %[t2]\n\t"
;         "v_fma_f32 %[t3], %[v], %[k3], %[t3]"
;         : [t0] "=&v"(t0), [t1] "=&v"(t1), [t2] "=&v"(t2), [t3] "=&v"(t3), [d1] "+v"(d1), [d2] "+v"(d2)
;         : [s0] "v"(S[0]), [s1] "v"(S[1]), [s2] "v"(S[2]), [s3] "v"(S[3]), [w0] "v"(o.w[0]), [w1] "v"(o.w[1]), [w2] "v"(o.w[2]), [w3] "v"(o.w[3]),
;           [k0] "v"(o.k[0]), [k1] "v"(o.k[1]), [k2] "v"(o.k[2]), [k3] "v"(o.k[3]), [v] "v"(o.q[0]));
;     S[0] = vnfma(d1, o.b[0], t0); S[1] = vnfma(d1, o.b[1], t1); S[2] = vnfma(d1, o.b[2], t2); S[3] = vnfma(d1, o.b[3], t3);
;     return vfma(o.q[0], o.q[2], vnfma(d1, o.q[1], d2));
; }
	v_mul_f32 v188, v159, v188
	v_mul_f32 v192, v159, v192
	v_mul_f32 v189, v164, v189
	v_mul_f32 v193, v164, v193
	v_fma_f32 v188, v165, v190, v188
	v_fma_f32 v192, v165, v194, v192
	v_fma_f32 v189, v167, v191, v189
	v_fma_f32 v193, v167, v195, v193
	v_add_f32 v188, v188, v189
	v_add_f32 v192, v192, v193
	v_mul_f32 v196, v159, v196
	v_mul_f32 v197, v164, v197
	v_add_f32_dpp v188, v188, v188 quad_perm:[1,0,3,2] row_mask:0xf bank_mask:0xf bound_ctrl:1
	v_add_f32_dpp v192, v192, v192 quad_perm:[1,0,3,2] row_mask:0xf bank_mask:0xf bound_ctrl:1
	v_mul_f32 v198, v165, v198
	v_add_f32_dpp v188, v188, v188 quad_perm:[2,3,0,1] row_mask:0xf bank_mask:0xf bound_ctrl:1
	v_add_f32_dpp v192, v192, v192 quad_perm:[2,3,0,1] row_mask:0xf bank_mask:0xf bound_ctrl:1
	v_mul_f32 v199, v167, v199
	v_add_f32_dpp v188, v188, v188 row_half_mirror row_mask:0xf bank_mask:0xf bound_ctrl:1
	v_add_f32_dpp v192, v192, v192 row_half_mirror row_mask:0xf bank_mask:0xf bound_ctrl:1
	v_fma_f32 v196, v208, v204, v196
	v_add_f32_dpp v188, v188, v188 row_mirror row_mask:0xf bank_mask:0xf bound_ctrl:1
	v_add_f32_dpp v192, v192, v192 row_mirror row_mask:0xf bank_mask:0xf bound_ctrl:1
	v_fma_f32 v197, v208, v205, v197
	v_fma_f32 v198, v208, v206, v198
	v_fma_f32 v199, v208, v207, v199
	v_fma_f32 v159, -v188, v200, v196
	v_fma_f32 v164, -v188, v201, v197
	v_fma_f32 v165, -v188, v202, v198
	v_fma_f32 v167, -v188, v203, v199
	v_fma_f32 v192, -v188, v209, v192
	v_fma_f32 v192, v208, v210, v192
	ds_write_b32 v2, v192 offset:192
	ds_read_b128 v[188:191], v3 offset:7680
	ds_read_b128 v[192:195], v3 offset:7936
	ds_read_b128 v[196:199], v3 offset:8192
	ds_read_b128 v[204:207], v3 offset:8704
	ds_read_b128 v[208:211], v4 offset:7680
	ds_read_b128 v[200:203], v3 offset:8448
	s_waitcnt lgkmcnt(7)
	v_mul_f32 v160, v159, v160
	v_mul_f32 v168, v159, v168
	v_mul_f32 v161, v164, v161
	v_mul_f32 v169, v164, v169
	v_fma_f32 v160, v165, v162, v160
	v_fma_f32 v168, v165, v170, v168
	v_fma_f32 v161, v167, v163, v161
	v_fma_f32 v169, v167, v171, v169
	v_add_f32 v160, v160, v161
	v_add_f32 v168, v168, v169
	v_mul_f32 v172, v159, v172
	v_mul_f32 v173, v164, v173
	v_add_f32_dpp v160, v160, v160 quad_perm:[1,0,3,2] row_mask:0xf bank_mask:0xf bound_ctrl:1
	v_add_f32_dpp v168, v168, v168 quad_perm:[1,0,3,2] row_mask:0xf bank_mask:0xf bound_ctrl:1
	v_mul_f32 v174, v165, v174
	v_add_f32_dpp v160, v160, v160 quad_perm:[2,3,0,1] row_mask:0xf bank_mask:0xf bound_ctrl:1
	v_add_f32_dpp v168, v168, v168 quad_perm:[2,3,0,1] row_mask:0xf bank_mask:0xf bound_ctrl:1
	v_mul_f32 v175, v167, v175
	v_add_f32_dpp v160, v160, v160 row_half_mirror row_mask:0xf bank_mask:0xf bound_ctrl:1
	v_add_f32_dpp v168, v168, v168 row_half_mirror row_mask:0xf bank_mask:0xf bound_ctrl:1
	v_fma_f32 v172, v184, v180, v172
	v_add_f32_dpp v160, v160, v160 row_mirror row_mask:0xf bank_mask:0xf bound_ctrl:1
	v_add_f32_dpp v168, v168, v168 row_mirror row_mask:0xf bank_mask:0xf bound_ctrl:1
	v_fma_f32 v173, v184, v181, v173
	v_fma_f32 v174, v184, v182, v174
	v_fma_f32 v175, v184, v183, v175
	v_fma_f32 v159, -v160, v176, v172
	v_fma_f32 v164, -v160, v177, v173
	v_fma_f32 v165, -v160, v178, v174
	v_fma_f32 v167, -v160, v179, v175
	v_fma_f32 v168, -v160, v185, v168
	v_fma_f32 v168, v184, v186, v168
	ds_write_b32 v2, v168 offset:256
	ds_read_b128 v[160:163], v3 offset:9216
	ds_read_b128 v[168:171], v3 offset:9472
	ds_read_b128 v[172:175], v3 offset:9728
	ds_read_b128 v[180:183], v3 offset:10240
	ds_read_b128 v[184:187], v4 offset:9216
	ds_read_b128 v[176:179], v3 offset:9984
	s_waitcnt lgkmcnt(7)
	v_mul_f32 v188, v159, v188
	v_mul_f32 v192, v159, v192
	v_mul_f32 v189, v164, v189
	v_mul_f32 v193, v164, v193
	v_fma_f32 v188, v165, v190, v188
	v_fma_f32 v192, v165, v194, v192
	v_fma_f32 v189, v167, v191, v189
	v_fma_f32 v193, v167, v195, v193
	v_add_f32 v188, v188, v189
	v_add_f32 v192, v192, v193
	v_mul_f32 v196, v159, v196
	v_mul_f32 v197, v164, v197
	v_add_f32_dpp v188, v188, v188 quad_perm:[1,0,3,2] row_mask:0xf bank_mask:0xf bound_ctrl:1
	v_add_f32_dpp v192, v192, v192 quad_perm:[1,0,3,2] row_mask:0xf bank_mask:0xf bound_ctrl:1
	v_mul_f32 v198, v165, v198
	v_add_f32_dpp v188, v188, v188 quad_perm:[2,3,0,1] row_mask:0xf bank_mask:0xf bound_ctrl:1
	v_add_f32_dpp v192, v192, v192 quad_perm:[2,3,0,1] row_mask:0xf bank_mask:0xf bound_ctrl:1
	v_mul_f32 v199, v167, v199
	v_add_f32_dpp v188, v188, v188 row_half_mirror row_mask:0xf bank_mask:0xf bound_ctrl:1
	v_add_f32_dpp v192, v192, v192 row_half_mirror row_mask:0xf bank_mask:0xf bound_ctrl:1
	v_fma_f32 v196, v208, v204, v196
	v_add_f32_dpp v188, v188, v188 row_mirror row_mask:0xf bank_mask:0xf bound_ctrl:1
	v_add_f32_dpp v192, v192, v192 row_mirror row_mask:0xf bank_mask:0xf bound_ctrl:1
	v_fma_f32 v197, v208, v205, v197
	v_fma_f32 v198, v208, v206, v198
	v_fma_f32 v199, v208, v207, v199
	v_fma_f32 v159, -v188, v200, v196
	v_fma_f32 v164, -v188, v201, v197
	v_fma_f32 v165, -v188, v202, v198
	v_fma_f32 v167, -v188, v203, v199
	v_fma_f32 v192, -v188, v209, v192
	v_fma_f32 v192, v208, v210, v192
	ds_write_b32 v2, v192 offset:320
	ds_read_b128 v[188:191], v3 offset:10752
	ds_read_b128 v[192:195], v3 offset:11008
	ds_read_b128 v[196:199], v3 offset:11264
	ds_read_b128 v[204:207], v3 offset:11776
	ds_read_b128 v[208:211], v4 offset:10752
	ds_read_b128 v[200:203], v3 offset:11520
	s_waitcnt lgkmcnt(7)
; __device__ __forceinline__ float vfma(float a, float b, float c) { float d; asm("v_fma_f32 %0, %1, %2, %3" : "=v"(d) : "v"(a), "v"(b), "v"(c)); return d; }
; __device__ __forceinline__ float step_compute(float (&S)[4], const StepOp& o) {
;     float d1 = vmul(S[0], o.kk[0]), d2 = vmul(S[0], o.wr[0]), e1 = vmul(S[1], o.kk[1]), e2 = vmul(S[1], o.wr[1]);
;     d1 = vfma(S[2], o.kk[2], d1); d2 = vfma(S[2], o.wr[2], d2); e1 = vfma(S[3], o.kk[3], e1); e2 = vfma(S[3], o.wr[3], e2);
;     d1 = vadd(d1, e1); d2 = vadd(d2, e2);
;     float t0, t1, t2, t3;
;     asm volatile(
;         "v_mul_f32 %[t0], %[s0], %[w0]\n\t"
;         "v_mul_f32 %[t1], %[s1], %[w1]\n\t"
;         "v_add_f32_dpp %[d1], %[d1], %[d1] quad_perm:[1,0,3,2] row_mask:0xf bank_mask:0xf bound_ctrl:1\n\t"
;         "v_add_f32_dpp %[d2], %[d2], %[d2] quad_perm:[1,0,3,2] row_mask:0xf bank_mask:0xf bound_ctrl:1\n\t"
;         "v_mul_f32 %[t2], %[s2], %[w2]\n\t"
;         "v_add_f32_dpp %[d1], %[d1], %[d1] quad_perm:[2,3,0,1] row_mask:0xf bank_mask:0xf bound_ctrl:1\n\t"
;         "v_add_f32_dpp %[d2], %[d2], %[d2] quad_perm:[2,3,0,1] row_mask:0xf bank_mask:0xf bound_ctrl:1\n\t"
;         "v_mul_f32 %[t3], %[s3], %[w3]\n\t"
;         "v_add_f32_dpp %[d1], %[d1], %[d1] row_half_mirror row_mask:0xf bank_mask:0xf bound_ctrl:1\n\t"
;         "v_add_f32_dpp %[d2], %[d2], %[d2] row_half_mirror row_mask:0xf bank_mask:0xf bound_ctrl:1\n\t"
;         "v_fma_f32 %[t0], %[v], %[k0], %[t0]\n\t"
;         "v_add_f32_dpp %[d1], %[d1], %[d1] row_mirror row_mask:0xf bank_mask:0xf bound_ctrl:1\n\t"
;         "v_add_f32_dpp %[d2], %[d2], %[d2] row_mirror row_mask:0xf bank_mask:0xf bound_ctrl:1\n\t"
;         "v_fma_f32 %[t1], %[v], %[k1], %[t1]\n\t"
;         "v_fma_f32 %[t2], %[v], %[k2], %[t2]\n\t"
;         "v_fma_f32 %[t3], %[v], %[k3], %[t3]"
;         : [t0] "=&v"(t0), [t1] "=&v"(t1), [t2] "=&v"(t2), [t3] "=&v"(t3), [d1] "+v"(d1), [d2] "+v"(d2)
;         : [s0] "v"(S[0]), [s1] "v"(S[1]), [s2] "v"(S[2]), [s3] "v"(S[3]), [w0] "v"(o.w[0]), [w1] "v"(o.w[1]), [w2] "v"(o.w[2]), [w3] "v"(o.w[3]),
;           [k0] "v"(o.k[0]), [k1] "v"(o.k[1]), [k2] "v"(o.k[2]), [k3] "v"(o.k[3]), [v] "v"(o.q[0]));
;     S[0] = vnfma(d1, o.b[0], t0); S[1] = vnfma(d1, o.b[1], t1); S[2] = vnfma(d1, o.b[2], t2); S[3] = vnfma(d1, o.b[3], t3);
;     return vfma(o.q[0], o.q[2], vnfma(d1, o.q[1], d2));
; }
	v_mul_f32 v160, v159, v160
	v_mul_f32 v168, v159, v168
	v_mul_f32 v161, v164, v161
	v_mul_f32 v169, v164, v169
	v_fma_f32 v160, v165, v162, v160
	v_fma_f32 v168, v165, v170, v168
	v_fma_f32 v161, v167, v163, v161
	v_fma_f32 v169, v167, v171, v169
	v_add_f32 v160, v160, v161
	v_add_f32 v168, v168, v169
	v_mul_f32 v172, v159, v172
	v_mul_f32 v173, v164, v173
	v_add_f32_dpp v160, v160, v160 quad_perm:[1,0,3,2] row_mask:0xf bank_mask:0xf bound_ctrl:1
	v_add_f32_dpp v168, v168, v168 quad_perm:[1,0,3,2] row_mask:0xf bank_mask:0xf bound_ctrl:1
	v_mul_f32 v174, v165, v174
	v_add_f32_dpp v160, v160, v160 quad_perm:[2,3,0,1] row_mask:0xf bank_mask:0xf bound_ctrl:1
	v_add_f32_dpp v168, v168, v168 quad_perm:[2,3,0,1] row_mask:0xf bank_mask:0xf bound_ctrl:1
	v_mul_f32 v175, v167, v175
	v_add_f32_dpp v160, v160, v160 row_half_mirror row_mask:0xf bank_mask:0xf bound_ctrl:1
	v_add_f32_dpp v168, v168, v168 row_half_mirror row_mask:0xf bank_mask:0xf bound_ctrl:1
	v_fma_f32 v172, v184, v180, v172
	v_add_f32_dpp v160, v160, v160 row_mirror row_mask:0xf bank_mask:0xf bound_ctrl:1
	v_add_f32_dpp v168, v168, v168 row_mirror row_mask:0xf bank_mask:0xf bound_ctrl:1
	v_fma_f32 v173, v184, v181, v173
	v_fma_f32 v174, v184, v182, v174
	v_fma_f32 v175, v184, v183, v175
	v_fma_f32 v159, -v160, v176, v172
	v_fma_f32 v164, -v160, v177, v173
	v_fma_f32 v165, -v160, v178, v174
	v_fma_f32 v167, -v160, v179, v175
	v_fma_f32 v168, -v160, v185, v168
	v_fma_f32 v168, v184, v186, v168
	ds_write_b32 v2, v168 offset:384
	ds_read_b128 v[160:163], v3 offset:12288
	ds_read_b128 v[168:171], v3 offset:12544
	ds_read_b128 v[172:175], v3 offset:12800
	ds_read_b128 v[180:183], v3 offset:13312
	ds_read_b128 v[184:187], v4 offset:12288
	ds_read_b128 v[176:179], v3 offset:13056
	s_waitcnt lgkmcnt(7)
	v_mul_f32 v188, v159, v188
	v_mul_f32 v192, v159, v192
	v_mul_f32 v189, v164, v189
	v_mul_f32 v193, v164, v193
	v_fma_f32 v188, v165, v190, v188
	v_fma_f32 v192, v165, v194, v192
	v_fma_f32 v189, v167, v191, v189
	v_fma_f32 v193, v167, v195, v193
	v_add_f32 v188, v188, v189
	v_add_f32 v192, v192, v193
	v_mul_f32 v196, v159, v196
	v_mul_f32 v197, v164, v197
	v_add_f32_dpp v188, v188, v188 quad_perm:[1,0,3,2] row_mask:0xf bank_mask:0xf bound_ctrl:1
	v_add_f32_dpp v192, v192, v192 quad_perm:[1,0,3,2] row_mask:0xf bank_mask:0xf bound_ctrl:1
	v_mul_f32 v198, v165, v198
	v_add_f32_dpp v188, v188, v188 quad_perm:[2,3,0,1] row_mask:0xf bank_mask:0xf bound_ctrl:1
	v_add_f32_dpp v192, v192, v192 quad_perm:[2,3,0,1] row_mask:0xf bank_mask:0xf bound_ctrl:1
	v_mul_f32 v199, v167, v199
	v_add_f32_dpp v188, v188, v188 row_half_mirror row_mask:0xf bank_mask:0xf bound_ctrl:1
	v_add_f32_dpp v192, v192, v192 row_half_mirror row_mask:0xf bank_mask:0xf bound_ctrl:1
	v_fma_f32 v196, v208, v204, v196
	v_add_f32_dpp v188, v188, v188 row_mirror row_mask:0xf bank_mask:0xf bound_ctrl:1
	v_add_f32_dpp v192, v192, v192 row_mirror row_mask:0xf bank_mask:0xf bound_ctrl:1
	v_fma_f32 v197, v208, v205, v197
	v_fma_f32 v198, v208, v206, v198
	v_fma_f32 v199, v208, v207, v199
	v_fma_f32 v159, -v188, v200, v196
	v_fma_f32 v164, -v188, v201, v197
	v_fma_f32 v165, -v188, v202, v198
	v_fma_f32 v167, -v188, v203, v199
	v_fma_f32 v192, -v188, v209, v192
	v_fma_f32 v192, v208, v210, v192
	ds_write_b32 v2, v192 offset:448
	ds_read_b128 v[188:191], v3 offset:13824
	ds_read_b128 v[192:195], v3 offset:14080
	ds_read_b128 v[196:199], v3 offset:14336
	ds_read_b128 v[204:207], v3 offset:14848
	ds_read_b128 v[208:211], v4 offset:13824
	ds_read_b128 v[200:203], v3 offset:14592
	s_waitcnt lgkmcnt(7)
	v_mul_f32 v160, v159, v160
	v_mul_f32 v168, v159, v168
	v_mul_f32 v161, v164, v161
	v_mul_f32 v169, v164, v169
	v_fma_f32 v160, v165, v162, v160
	v_fma_f32 v168, v165, v170, v168
	v_fma_f32 v161, v167, v163, v161
	v_fma_f32 v169, v167, v171, v169
	v_add_f32 v160, v160, v161
	v_add_f32 v168, v168, v169
	v_mul_f32 v172, v159, v172
	v_mul_f32 v173, v164, v173
	v_add_f32_dpp v160, v160, v160 quad_perm:[1,0,3,2] row_mask:0xf bank_mask:0xf bound_ctrl:1
	v_add_f32_dpp v168, v168, v168 quad_perm:[1,0,3,2] row_mask:0xf bank_mask:0xf bound_ctrl:1
	v_mul_f32 v174, v165, v174
	v_add_f32_dpp v160, v160, v160 quad_perm:[2,3,0,1] row_mask:0xf bank_mask:0xf bound_ctrl:1
	v_add_f32_dpp v168, v168, v168 quad_perm:[2,3,0,1] row_mask:0xf bank_mask:0xf bound_ctrl:1
	v_mul_f32 v175, v167, v175
	v_add_f32_dpp v160, v160, v160 row_half_mirror row_mask:0xf bank_mask:0xf bound_ctrl:1
	v_add_f32_dpp v168, v168, v168 row_half_mirror row_mask:0xf bank_mask:0xf bound_ctrl:1
	v_fma_f32 v172, v184, v180, v172
	v_add_f32_dpp v160, v160, v160 row_mirror row_mask:0xf bank_mask:0xf bound_ctrl:1
	v_add_f32_dpp v168, v168, v168 row_mirror row_mask:0xf bank_mask:0xf bound_ctrl:1
	v_fma_f32 v173, v184, v181, v173
	v_fma_f32 v174, v184, v182, v174
	v_fma_f32 v175, v184, v183, v175
	v_fma_f32 v159, -v160, v176, v172
	v_fma_f32 v164, -v160, v177, v173
	v_fma_f32 v165, -v160, v178, v174
	v_fma_f32 v167, -v160, v179, v175
	v_fma_f32 v168, -v160, v185, v168
	v_fma_f32 v168, v184, v186, v168
	ds_write_b32 v2, v168 offset:512
	ds_read_b128 v[160:163], v3 offset:15360
	ds_read_b128 v[168:171], v3 offset:15616
	ds_read_b128 v[172:175], v3 offset:15872
	ds_read_b128 v[180:183], v3 offset:16384
	ds_read_b128 v[184:187], v4 offset:15360
	ds_read_b128 v[176:179], v3 offset:16128
	s_waitcnt lgkmcnt(7)
; __device__ __forceinline__ float vfma(float a, float b, float c) { float d; asm("v_fma_f32 %0, %1, %2, %3" : "=v"(d) : "v"(a), "v"(b), "v"(c)); return d; }
; __device__ __forceinline__ float step_compute(float (&S)[4], const StepOp& o) {
;     float d1 = vmul(S[0], o.kk[0]), d2 = vmul(S[0], o.wr[0]), e1 = vmul(S[1], o.kk[1]), e2 = vmul(S[1], o.wr[1]);
;     d1 = vfma(S[2], o.kk[2], d1); d2 = vfma(S[2], o.wr[2], d2); e1 = vfma(S[3], o.kk[3], e1); e2 = vfma(S[3], o.wr[3], e2);
;     d1 = vadd(d1, e1); d2 = vadd(d2, e2);
;     float t0, t1, t2, t3;
;     asm volatile(
;         "v_mul_f32 %[t0], %[s0], %[w0]\n\t"
;         "v_mul_f32 %[t1], %[s1], %[w1]\n\t"
;         "v_add_f32_dpp %[d1], %[d1], %[d1] quad_perm:[1,0,3,2] row_mask:0xf bank_mask:0xf bound_ctrl:1\n\t"
;         "v_add_f32_dpp %[d2], %[d2], %[d2] quad_perm:[1,0,3,2] row_mask:0xf bank_mask:0xf bound_ctrl:1\n\t"
;         "v_mul_f32 %[t2], %[s2], %[w2]\n\t"
;         "v_add_f32_dpp %[d1], %[d1], %[d1] quad_perm:[2,3,0,1] row_mask:0xf bank_mask:0xf bound_ctrl:1\n\t"
;         "v_add_f32_dpp %[d2], %[d2], %[d2] quad_perm:[2,3,0,1] row_mask:0xf bank_mask:0xf bound_ctrl:1\n\t"
;         "v_mul_f32 %[t3], %[s3], %[w3]\n\t"
;         "v_add_f32_dpp %[d1], %[d1], %[d1] row_half_mirror row_mask:0xf bank_mask:0xf bound_ctrl:1\n\t"
;         "v_add_f32_dpp %[d2], %[d2], %[d2] row_half_mirror row_mask:0xf bank_mask:0xf bound_ctrl:1\n\t"
;         "v_fma_f32 %[t0], %[v], %[k0], %[t0]\n\t"
;         "v_add_f32_dpp %[d1], %[d1], %[d1] row_mirror row_mask:0xf bank_mask:0xf bound_ctrl:1\n\t"
;         "v_add_f32_dpp %[d2], %[d2], %[d2] row_mirror row_mask:0xf bank_mask:0xf bound_ctrl:1\n\t"
;         "v_fma_f32 %[t1], %[v], %[k1], %[t1]\n\t"
;         "v_fma_f32 %[t2], %[v], %[k2], %[t2]\n\t"
;         "v_fma_f32 %[t3], %[v], %[k3], %[t3]"
;         : [t0] "=&v"(t0), [t1] "=&v"(t1), [t2] "=&v"(t2), [t3] "=&v"(t3), [d1] "+v"(d1), [d2] "+v"(d2)
;         : [s0] "v"(S[0]), [s1] "v"(S[1]), [s2] "v"(S[2]), [s3] "v"(S[3]), [w0] "v"(o.w[0]), [w1] "v"(o.w[1]), [w2] "v"(o.w[2]), [w3] "v"(o.w[3]),
;           [k0] "v"(o.k[0]), [k1] "v"(o.k[1]), [k2] "v"(o.k[2]), [k3] "v"(o.k[3]), [v] "v"(o.q[0]));
;     S[0] = vnfma(d1, o.b[0], t0); S[1] = vnfma(d1, o.b[1], t1); S[2] = vnfma(d1, o.b[2], t2); S[3] = vnfma(d1, o.b[3], t3);
;     return vfma(o.q[0], o.q[2], vnfma(d1, o.q[1], d2));
; }
	v_mul_f32 v188, v159, v188
	v_mul_f32 v192, v159, v192
	v_mul_f32 v189, v164, v189
	v_mul_f32 v193, v164, v193
	v_fma_f32 v188, v165, v190, v188
	v_fma_f32 v192, v165, v194, v192
	v_fma_f32 v189, v167, v191, v189
	v_fma_f32 v193, v167, v195, v193
	v_add_f32 v188, v188, v189
	v_add_f32 v192, v192, v193
	v_mul_f32 v196, v159, v196
	v_mul_f32 v197, v164, v197
	v_add_f32_dpp v188, v188, v188 quad_perm:[1,0,3,2] row_mask:0xf bank_mask:0xf bound_ctrl:1
	v_add_f32_dpp v192, v192, v192 quad_perm:[1,0,3,2] row_mask:0xf bank_mask:0xf bound_ctrl:1
	v_mul_f32 v198, v165, v198
	v_add_f32_dpp v188, v188, v188 quad_perm:[2,3,0,1] row_mask:0xf bank_mask:0xf bound_ctrl:1
	v_add_f32_dpp v192, v192, v192 quad_perm:[2,3,0,1] row_mask:0xf bank_mask:0xf bound_ctrl:1
	v_mul_f32 v199, v167, v199
	v_add_f32_dpp v188, v188, v188 row_half_mirror row_mask:0xf bank_mask:0xf bound_ctrl:1
	v_add_f32_dpp v192, v192, v192 row_half_mirror row_mask:0xf bank_mask:0xf bound_ctrl:1
	v_fma_f32 v196, v208, v204, v196
	v_add_f32_dpp v188, v188, v188 row_mirror row_mask:0xf bank_mask:0xf bound_ctrl:1
	v_add_f32_dpp v192, v192, v192 row_mirror row_mask:0xf bank_mask:0xf bound_ctrl:1
	v_fma_f32 v197, v208, v205, v197
	v_fma_f32 v198, v208, v206, v198
	v_fma_f32 v199, v208, v207, v199
	v_fma_f32 v159, -v188, v200, v196
	v_fma_f32 v164, -v188, v201, v197
	v_fma_f32 v165, -v188, v202, v198
	v_fma_f32 v167, -v188, v203, v199
	v_fma_f32 v192, -v188, v209, v192
	v_fma_f32 v192, v208, v210, v192
	ds_write_b32 v2, v192 offset:576
	ds_read_b128 v[188:191], v3 offset:16896
	ds_read_b128 v[192:195], v3 offset:17152
	ds_read_b128 v[196:199], v3 offset:17408
	ds_read_b128 v[204:207], v3 offset:17920
	ds_read_b128 v[208:211], v4 offset:16896
	ds_read_b128 v[200:203], v3 offset:17664
	s_waitcnt lgkmcnt(7)
	v_mul_f32 v160, v159, v160
	v_mul_f32 v168, v159, v168
	v_mul_f32 v161, v164, v161
	v_mul_f32 v169, v164, v169
	v_fma_f32 v160, v165, v162, v160
	v_fma_f32 v168, v165, v170, v168
	v_fma_f32 v161, v167, v163, v161
	v_fma_f32 v169, v167, v171, v169
	v_add_f32 v160, v160, v161
	v_add_f32 v168, v168, v169
	v_mul_f32 v172, v159, v172
	v_mul_f32 v173, v164, v173
	v_add_f32_dpp v160, v160, v160 quad_perm:[1,0,3,2] row_mask:0xf bank_mask:0xf bound_ctrl:1
	v_add_f32_dpp v168, v168, v168 quad_perm:[1,0,3,2] row_mask:0xf bank_mask:0xf bound_ctrl:1
	v_mul_f32 v174, v165, v174
	v_add_f32_dpp v160, v160, v160 quad_perm:[2,3,0,1] row_mask:0xf bank_mask:0xf bound_ctrl:1
	v_add_f32_dpp v168, v168, v168 quad_perm:[2,3,0,1] row_mask:0xf bank_mask:0xf bound_ctrl:1
	v_mul_f32 v175, v167, v175
	v_add_f32_dpp v160, v160, v160 row_half_mirror row_mask:0xf bank_mask:0xf bound_ctrl:1
	v_add_f32_dpp v168, v168, v168 row_half_mirror row_mask:0xf bank_mask:0xf bound_ctrl:1
	v_fma_f32 v172, v184, v180, v172
	v_add_f32_dpp v160, v160, v160 row_mirror row_mask:0xf bank_mask:0xf bound_ctrl:1
	v_add_f32_dpp v168, v168, v168 row_mirror row_mask:0xf bank_mask:0xf bound_ctrl:1
	v_fma_f32 v173, v184, v181, v173
	v_fma_f32 v174, v184, v182, v174
	v_fma_f32 v175, v184, v183, v175
	v_fma_f32 v159, -v160, v176, v172
	v_fma_f32 v164, -v160, v177, v173
	v_fma_f32 v165, -v160, v178, v174
	v_fma_f32 v167, -v160, v179, v175
	v_fma_f32 v168, -v160, v185, v168
	v_fma_f32 v168, v184, v186, v168
	ds_write_b32 v2, v168 offset:640
	ds_read_b128 v[160:163], v3 offset:18432
	ds_read_b128 v[168:171], v3 offset:18688
	ds_read_b128 v[172:175], v3 offset:18944
	ds_read_b128 v[180:183], v3 offset:19456
	ds_read_b128 v[184:187], v4 offset:18432
	ds_read_b128 v[176:179], v3 offset:19200
	s_waitcnt lgkmcnt(7)
	v_mul_f32 v188, v159, v188
	v_mul_f32 v192, v159, v192
	v_mul_f32 v189, v164, v189
	v_mul_f32 v193, v164, v193
	v_fma_f32 v188, v165, v190, v188
	v_fma_f32 v192, v165, v194, v192
	v_fma_f32 v189, v167, v191, v189
	v_fma_f32 v193, v167, v195, v193
	v_add_f32 v188, v188, v189
	v_add_f32 v192, v192, v193
	v_mul_f32 v196, v159, v196
	v_mul_f32 v197, v164, v197
	v_add_f32_dpp v188, v188, v188 quad_perm:[1,0,3,2] row_mask:0xf bank_mask:0xf bound_ctrl:1
	v_add_f32_dpp v192, v192, v192 quad_perm:[1,0,3,2] row_mask:0xf bank_mask:0xf bound_ctrl:1
	v_mul_f32 v198, v165, v198
	v_add_f32_dpp v188, v188, v188 quad_perm:[2,3,0,1] row_mask:0xf bank_mask:0xf bound_ctrl:1
	v_add_f32_dpp v192, v192, v192 quad_perm:[2,3,0,1] row_mask:0xf bank_mask:0xf bound_ctrl:1
	v_mul_f32 v199, v167, v199
	v_add_f32_dpp v188, v188, v188 row_half_mirror row_mask:0xf bank_mask:0xf bound_ctrl:1
	v_add_f32_dpp v192, v192, v192 row_half_mirror row_mask:0xf bank_mask:0xf bound_ctrl:1
	v_fma_f32 v196, v208, v204, v196
	v_add_f32_dpp v188, v188, v188 row_mirror row_mask:0xf bank_mask:0xf bound_ctrl:1
	v_add_f32_dpp v192, v192, v192 row_mirror row_mask:0xf bank_mask:0xf bound_ctrl:1
	v_fma_f32 v197, v208, v205, v197
	v_fma_f32 v198, v208, v206, v198
	v_fma_f32 v199, v208, v207, v199
	v_fma_f32 v159, -v188, v200, v196
	v_fma_f32 v164, -v188, v201, v197
	v_fma_f32 v165, -v188, v202, v198
	v_fma_f32 v167, -v188, v203, v199
	v_fma_f32 v192, -v188, v209, v192
	v_fma_f32 v192, v208, v210, v192
	ds_write_b32 v2, v192 offset:704
	ds_read_b128 v[188:191], v3 offset:19968
	ds_read_b128 v[192:195], v3 offset:20224
	ds_read_b128 v[196:199], v3 offset:20480
	ds_read_b128 v[204:207], v3 offset:20992
	ds_read_b128 v[208:211], v4 offset:19968
	ds_read_b128 v[200:203], v3 offset:20736
	s_waitcnt lgkmcnt(7)
; __device__ __forceinline__ float vfma(float a, float b, float c) { float d; asm("v_fma_f32 %0, %1, %2, %3" : "=v"(d) : "v"(a), "v"(b), "v"(c)); return d; }
; __device__ __forceinline__ float step_compute(float (&S)[4], const StepOp& o) {
;     float d1 = vmul(S[0], o.kk[0]), d2 = vmul(S[0], o.wr[0]), e1 = vmul(S[1], o.kk[1]), e2 = vmul(S[1], o.wr[1]);
;     d1 = vfma(S[2], o.kk[2], d1); d2 = vfma(S[2], o.wr[2], d2); e1 = vfma(S[3], o.kk[3], e1); e2 = vfma(S[3], o.wr[3], e2);
;     d1 = vadd(d1, e1); d2 = vadd(d2, e2);
;     float t0, t1, t2, t3;
;     asm volatile(
;         "v_mul_f32 %[t0], %[s0], %[w0]\n\t"
;         "v_mul_f32 %[t1], %[s1], %[w1]\n\t"
;         "v_add_f32_dpp %[d1], %[d1], %[d1] quad_perm:[1,0,3,2] row_mask:0xf bank_mask:0xf bound_ctrl:1\n\t"
;         "v_add_f32_dpp %[d2], %[d2], %[d2] quad_perm:[1,0,3,2] row_mask:0xf bank_mask:0xf bound_ctrl:1\n\t"
;         "v_mul_f32 %[t2], %[s2], %[w2]\n\t"
;         "v_add_f32_dpp %[d1], %[d1], %[d1] quad_perm:[2,3,0,1] row_mask:0xf bank_mask:0xf bound_ctrl:1\n\t"
;         "v_add_f32_dpp %[d2], %[d2], %[d2] quad_perm:[2,3,0,1] row_mask:0xf bank_mask:0xf bound_ctrl:1\n\t"
;         "v_mul_f32 %[t3], %[s3], %[w3]\n\t"
;         "v_add_f32_dpp %[d1], %[d1], %[d1] row_half_mirror row_mask:0xf bank_mask:0xf bound_ctrl:1\n\t"
;         "v_add_f32_dpp %[d2], %[d2], %[d2] row_half_mirror row_mask:0xf bank_mask:0xf bound_ctrl:1\n\t"
;         "v_fma_f32 %[t0], %[v], %[k0], %[t0]\n\t"
;         "v_add_f32_dpp %[d1], %[d1], %[d1] row_mirror row_mask:0xf bank_mask:0xf bound_ctrl:1\n\t"
;         "v_add_f32_dpp %[d2], %[d2], %[d2] row_mirror row_mask:0xf bank_mask:0xf bound_ctrl:1\n\t"
;         "v_fma_f32 %[t1], %[v], %[k1], %[t1]\n\t"
;         "v_fma_f32 %[t2], %[v], %[k2], %[t2]\n\t"
;         "v_fma_f32 %[t3], %[v], %[k3], %[t3]"
;         : [t0] "=&v"(t0), [t1] "=&v"(t1), [t2] "=&v"(t2), [t3] "=&v"(t3), [d1] "+v"(d1), [d2] "+v"(d2)
;         : [s0] "v"(S[0]), [s1] "v"(S[1]), [s2] "v"(S[2]), [s3] "v"(S[3]), [w0] "v"(o.w[0]), [w1] "v"(o.w[1]), [w2] "v"(o.w[2]), [w3] "v"(o.w[3]),
;           [k0] "v"(o.k[0]), [k1] "v"(o.k[1]), [k2] "v"(o.k[2]), [k3] "v"(o.k[3]), [v] "v"(o.q[0]));
;     S[0] = vnfma(d1, o.b[0], t0); S[1] = vnfma(d1, o.b[1], t1); S[2] = vnfma(d1, o.b[2], t2); S[3] = vnfma(d1, o.b[3], t3);
;     return vfma(o.q[0], o.q[2], vnfma(d1, o.q[1], d2));
; }
	v_mul_f32 v160, v159, v160
	v_mul_f32 v168, v159, v168
	v_mul_f32 v161, v164, v161
	v_mul_f32 v169, v164, v169
	v_fma_f32 v160, v165, v162, v160
	v_fma_f32 v168, v165, v170, v168
	v_fma_f32 v161, v167, v163, v161
	v_fma_f32 v169, v167, v171, v169
	v_add_f32 v160, v160, v161
	v_add_f32 v168, v168, v169
	v_mul_f32 v172, v159, v172
	v_mul_f32 v173, v164, v173
	v_add_f32_dpp v160, v160, v160 quad_perm:[1,0,3,2] row_mask:0xf bank_mask:0xf bound_ctrl:1
	v_add_f32_dpp v168, v168, v168 quad_perm:[1,0,3,2] row_mask:0xf bank_mask:0xf bound_ctrl:1
	v_mul_f32 v174, v165, v174
	v_add_f32_dpp v160, v160, v160 quad_perm:[2,3,0,1] row_mask:0xf bank_mask:0xf bound_ctrl:1
	v_add_f32_dpp v168, v168, v168 quad_perm:[2,3,0,1] row_mask:0xf bank_mask:0xf bound_ctrl:1
	v_mul_f32 v175, v167, v175
	v_add_f32_dpp v160, v160, v160 row_half_mirror row_mask:0xf bank_mask:0xf bound_ctrl:1
	v_add_f32_dpp v168, v168, v168 row_half_mirror row_mask:0xf bank_mask:0xf bound_ctrl:1
	v_fma_f32 v172, v184, v180, v172
	v_add_f32_dpp v160, v160, v160 row_mirror row_mask:0xf bank_mask:0xf bound_ctrl:1
	v_add_f32_dpp v168, v168, v168 row_mirror row_mask:0xf bank_mask:0xf bound_ctrl:1
	v_fma_f32 v173, v184, v181, v173
	v_fma_f32 v174, v184, v182, v174
	v_fma_f32 v175, v184, v183, v175
	v_fma_f32 v159, -v160, v176, v172
	v_fma_f32 v164, -v160, v177, v173
	v_fma_f32 v165, -v160, v178, v174
	v_fma_f32 v167, -v160, v179, v175
	v_fma_f32 v168, -v160, v185, v168
	v_fma_f32 v168, v184, v186, v168
	ds_write_b32 v2, v168 offset:768
	ds_read_b128 v[160:163], v3 offset:21504
	ds_read_b128 v[168:171], v3 offset:21760
	ds_read_b128 v[172:175], v3 offset:22016
	ds_read_b128 v[180:183], v3 offset:22528
	ds_read_b128 v[184:187], v4 offset:21504
	ds_read_b128 v[176:179], v3 offset:22272
	s_waitcnt lgkmcnt(7)
	v_mul_f32 v188, v159, v188
	v_mul_f32 v192, v159, v192
	v_mul_f32 v189, v164, v189
	v_mul_f32 v193, v164, v193
	v_fma_f32 v188, v165, v190, v188
	v_fma_f32 v192, v165, v194, v192
	v_fma_f32 v189, v167, v191, v189
	v_fma_f32 v193, v167, v195, v193
	v_add_f32 v188, v188, v189
	v_add_f32 v192, v192, v193
	v_mul_f32 v196, v159, v196
	v_mul_f32 v197, v164, v197
	v_add_f32_dpp v188, v188, v188 quad_perm:[1,0,3,2] row_mask:0xf bank_mask:0xf bound_ctrl:1
	v_add_f32_dpp v192, v192, v192 quad_perm:[1,0,3,2] row_mask:0xf bank_mask:0xf bound_ctrl:1
	v_mul_f32 v198, v165, v198
	v_add_f32_dpp v188, v188, v188 quad_perm:[2,3,0,1] row_mask:0xf bank_mask:0xf bound_ctrl:1
	v_add_f32_dpp v192, v192, v192 quad_perm:[2,3,0,1] row_mask:0xf bank_mask:0xf bound_ctrl:1
	v_mul_f32 v199, v167, v199
	v_add_f32_dpp v188, v188, v188 row_half_mirror row_mask:0xf bank_mask:0xf bound_ctrl:1
	v_add_f32_dpp v192, v192, v192 row_half_mirror row_mask:0xf bank_mask:0xf bound_ctrl:1
	v_fma_f32 v196, v208, v204, v196
	v_add_f32_dpp v188, v188, v188 row_mirror row_mask:0xf bank_mask:0xf bound_ctrl:1
	v_add_f32_dpp v192, v192, v192 row_mirror row_mask:0xf bank_mask:0xf bound_ctrl:1
	v_fma_f32 v197, v208, v205, v197
	v_fma_f32 v198, v208, v206, v198
	v_fma_f32 v199, v208, v207, v199
	v_fma_f32 v159, -v188, v200, v196
	v_fma_f32 v164, -v188, v201, v197
	v_fma_f32 v165, -v188, v202, v198
	v_fma_f32 v167, -v188, v203, v199
	v_fma_f32 v192, -v188, v209, v192
	v_fma_f32 v192, v208, v210, v192
	ds_write_b32 v2, v192 offset:832
	ds_read_b128 v[188:191], v3 offset:23040
	ds_read_b128 v[192:195], v3 offset:23296
	ds_read_b128 v[196:199], v3 offset:23552
	ds_read_b128 v[204:207], v3 offset:24064
	ds_read_b128 v[208:211], v4 offset:23040
	ds_read_b128 v[200:203], v3 offset:23808
	s_waitcnt lgkmcnt(7)
	v_mul_f32 v160, v159, v160
	v_mul_f32 v168, v159, v168
	v_mul_f32 v161, v164, v161
	v_mul_f32 v169, v164, v169
	v_fma_f32 v160, v165, v162, v160
	v_fma_f32 v168, v165, v170, v168
	v_fma_f32 v161, v167, v163, v161
	v_fma_f32 v169, v167, v171, v169
	v_add_f32 v160, v160, v161
	v_add_f32 v168, v168, v169
	v_mul_f32 v172, v159, v172
	v_mul_f32 v173, v164, v173
	v_add_f32_dpp v160, v160, v160 quad_perm:[1,0,3,2] row_mask:0xf bank_mask:0xf bound_ctrl:1
	v_add_f32_dpp v168, v168, v168 quad_perm:[1,0,3,2] row_mask:0xf bank_mask:0xf bound_ctrl:1
	v_mul_f32 v174, v165, v174
	v_add_f32_dpp v160, v160, v160 quad_perm:[2,3,0,1] row_mask:0xf bank_mask:0xf bound_ctrl:1
	v_add_f32_dpp v168, v168, v168 quad_perm:[2,3,0,1] row_mask:0xf bank_mask:0xf bound_ctrl:1
	v_mul_f32 v175, v167, v175
	v_add_f32_dpp v160, v160, v160 row_half_mirror row_mask:0xf bank_mask:0xf bound_ctrl:1
	v_add_f32_dpp v168, v168, v168 row_half_mirror row_mask:0xf bank_mask:0xf bound_ctrl:1
	v_fma_f32 v172, v184, v180, v172
	v_add_f32_dpp v160, v160, v160 row_mirror row_mask:0xf bank_mask:0xf bound_ctrl:1
	v_add_f32_dpp v168, v168, v168 row_mirror row_mask:0xf bank_mask:0xf bound_ctrl:1
	v_fma_f32 v173, v184, v181, v173
	v_fma_f32 v174, v184, v182, v174
	v_fma_f32 v175, v184, v183, v175
	v_fma_f32 v159, -v160, v176, v172
	v_fma_f32 v164, -v160, v177, v173
	v_fma_f32 v165, -v160, v178, v174
	v_fma_f32 v167, -v160, v179, v175
	v_fma_f32 v168, -v160, v185, v168
	v_fma_f32 v168, v184, v186, v168
	ds_write_b32 v2, v168 offset:896
	ds_read_b128 v[160:163], v3 offset:24576
	ds_read_b128 v[168:171], v3 offset:24832
	ds_read_b128 v[172:175], v3 offset:25088
	ds_read_b128 v[180:183], v3 offset:25600
	ds_read_b128 v[184:187], v4 offset:24576
	ds_read_b128 v[176:179], v3 offset:25344
	s_waitcnt lgkmcnt(7)
; __device__ __forceinline__ float vfma(float a, float b, float c) { float d; asm("v_fma_f32 %0, %1, %2, %3" : "=v"(d) : "v"(a), "v"(b), "v"(c)); return d; }
; __device__ __forceinline__ float step_compute(float (&S)[4], const StepOp& o) {
;     float d1 = vmul(S[0], o.kk[0]), d2 = vmul(S[0], o.wr[0]), e1 = vmul(S[1], o.kk[1]), e2 = vmul(S[1], o.wr[1]);
;     d1 = vfma(S[2], o.kk[2], d1); d2 = vfma(S[2], o.wr[2], d2); e1 = vfma(S[3], o.kk[3], e1); e2 = vfma(S[3], o.wr[3], e2);
;     d1 = vadd(d1, e1); d2 = vadd(d2, e2);
;     float t0, t1, t2, t3;
;     asm volatile(
;         "v_mul_f32 %[t0], %[s0], %[w0]\n\t"
;         "v_mul_f32 %[t1], %[s1], %[w1]\n\t"
;         "v_add_f32_dpp %[d1], %[d1], %[d1] quad_perm:[1,0,3,2] row_mask:0xf bank_mask:0xf bound_ctrl:1\n\t"
;         "v_add_f32_dpp %[d2], %[d2], %[d2] quad_perm:[1,0,3,2] row_mask:0xf bank_mask:0xf bound_ctrl:1\n\t"
;         "v_mul_f32 %[t2], %[s2], %[w2]\n\t"
;         "v_add_f32_dpp %[d1], %[d1], %[d1] quad_perm:[2,3,0,1] row_mask:0xf bank_mask:0xf bound_ctrl:1\n\t"
;         "v_add_f32_dpp %[d2], %[d2], %[d2] quad_perm:[2,3,0,1] row_mask:0xf bank_mask:0xf bound_ctrl:1\n\t"
;         "v_mul_f32 %[t3], %[s3], %[w3]\n\t"
;         "v_add_f32_dpp %[d1], %[d1], %[d1] row_half_mirror row_mask:0xf bank_mask:0xf bound_ctrl:1\n\t"
;         "v_add_f32_dpp %[d2], %[d2], %[d2] row_half_mirror row_mask:0xf bank_mask:0xf bound_ctrl:1\n\t"
;         "v_fma_f32 %[t0], %[v], %[k0], %[t0]\n\t"
;         "v_add_f32_dpp %[d1], %[d1], %[d1] row_mirror row_mask:0xf bank_mask:0xf bound_ctrl:1\n\t"
;         "v_add_f32_dpp %[d2], %[d2], %[d2] row_mirror row_mask:0xf bank_mask:0xf bound_ctrl:1\n\t"
;         "v_fma_f32 %[t1], %[v], %[k1], %[t1]\n\t"
;         "v_fma_f32 %[t2], %[v], %[k2], %[t2]\n\t"
;         "v_fma_f32 %[t3], %[v], %[k3], %[t3]"
;         : [t0] "=&v"(t0), [t1] "=&v"(t1), [t2] "=&v"(t2), [t3] "=&v"(t3), [d1] "+v"(d1), [d2] "+v"(d2)
;         : [s0] "v"(S[0]), [s1] "v"(S[1]), [s2] "v"(S[2]), [s3] "v"(S[3]), [w0] "v"(o.w[0]), [w1] "v"(o.w[1]), [w2] "v"(o.w[2]), [w3] "v"(o.w[3]),
;           [k0] "v"(o.k[0]), [k1] "v"(o.k[1]), [k2] "v"(o.k[2]), [k3] "v"(o.k[3]), [v] "v"(o.q[0]));
;     S[0] = vnfma(d1, o.b[0], t0); S[1] = vnfma(d1, o.b[1], t1); S[2] = vnfma(d1, o.b[2], t2); S[3] = vnfma(d1, o.b[3], t3);
;     return vfma(o.q[0], o.q[2], vnfma(d1, o.q[1], d2));
; }
	v_mul_f32 v188, v159, v188
	v_mul_f32 v192, v159, v192
	v_mul_f32 v189, v164, v189
	v_mul_f32 v193, v164, v193
	v_fma_f32 v188, v165, v190, v188
	v_fma_f32 v192, v165, v194, v192
	v_fma_f32 v189, v167, v191, v189
	v_fma_f32 v193, v167, v195, v193
	v_add_f32 v188, v188, v189
	v_add_f32 v192, v192, v193
	v_mul_f32 v196, v159, v196
	v_mul_f32 v197, v164, v197
	v_add_f32_dpp v188, v188, v188 quad_perm:[1,0,3,2] row_mask:0xf bank_mask:0xf bound_ctrl:1
	v_add_f32_dpp v192, v192, v192 quad_perm:[1,0,3,2] row_mask:0xf bank_mask:0xf bound_ctrl:1
	v_mul_f32 v198, v165, v198
	v_add_f32_dpp v188, v188, v188 quad_perm:[2,3,0,1] row_mask:0xf bank_mask:0xf bound_ctrl:1
	v_add_f32_dpp v192, v192, v192 quad_perm:[2,3,0,1] row_mask:0xf bank_mask:0xf bound_ctrl:1
	v_mul_f32 v199, v167, v199
	v_add_f32_dpp v188, v188, v188 row_half_mirror row_mask:0xf bank_mask:0xf bound_ctrl:1
	v_add_f32_dpp v192, v192, v192 row_half_mirror row_mask:0xf bank_mask:0xf bound_ctrl:1
	v_fma_f32 v196, v208, v204, v196
	v_add_f32_dpp v188, v188, v188 row_mirror row_mask:0xf bank_mask:0xf bound_ctrl:1
	v_add_f32_dpp v192, v192, v192 row_mirror row_mask:0xf bank_mask:0xf bound_ctrl:1
	v_fma_f32 v197, v208, v205, v197
	v_fma_f32 v198, v208, v206, v198
	v_fma_f32 v199, v208, v207, v199
	v_fma_f32 v159, -v188, v200, v196
	v_fma_f32 v164, -v188, v201, v197
	v_fma_f32 v165, -v188, v202, v198
	v_fma_f32 v167, -v188, v203, v199
	v_fma_f32 v192, -v188, v209, v192
	v_fma_f32 v192, v208, v210, v192
	ds_write_b32 v2, v192 offset:960
	ds_read_b128 v[188:191], v3 offset:26112
	ds_read_b128 v[192:195], v3 offset:26368
	ds_read_b128 v[196:199], v3 offset:26624
	ds_read_b128 v[204:207], v3 offset:27136
	ds_read_b128 v[208:211], v4 offset:26112
	ds_read_b128 v[200:203], v3 offset:26880
	s_waitcnt lgkmcnt(7)
	v_mul_f32 v160, v159, v160
	v_mul_f32 v168, v159, v168
	v_mul_f32 v161, v164, v161
	v_mul_f32 v169, v164, v169
	v_fma_f32 v160, v165, v162, v160
	v_fma_f32 v168, v165, v170, v168
	v_fma_f32 v161, v167, v163, v161
	v_fma_f32 v169, v167, v171, v169
	v_add_f32 v160, v160, v161
	v_add_f32 v168, v168, v169
	v_mul_f32 v172, v159, v172
	v_mul_f32 v173, v164, v173
	v_add_f32_dpp v160, v160, v160 quad_perm:[1,0,3,2] row_mask:0xf bank_mask:0xf bound_ctrl:1
	v_add_f32_dpp v168, v168, v168 quad_perm:[1,0,3,2] row_mask:0xf bank_mask:0xf bound_ctrl:1
	v_mul_f32 v174, v165, v174
	v_add_f32_dpp v160, v160, v160 quad_perm:[2,3,0,1] row_mask:0xf bank_mask:0xf bound_ctrl:1
	v_add_f32_dpp v168, v168, v168 quad_perm:[2,3,0,1] row_mask:0xf bank_mask:0xf bound_ctrl:1
	v_mul_f32 v175, v167, v175
	v_add_f32_dpp v160, v160, v160 row_half_mirror row_mask:0xf bank_mask:0xf bound_ctrl:1
	v_add_f32_dpp v168, v168, v168 row_half_mirror row_mask:0xf bank_mask:0xf bound_ctrl:1
	v_fma_f32 v172, v184, v180, v172
	v_add_f32_dpp v160, v160, v160 row_mirror row_mask:0xf bank_mask:0xf bound_ctrl:1
	v_add_f32_dpp v168, v168, v168 row_mirror row_mask:0xf bank_mask:0xf bound_ctrl:1
	v_fma_f32 v173, v184, v181, v173
	v_fma_f32 v174, v184, v182, v174
	v_fma_f32 v175, v184, v183, v175
	v_fma_f32 v159, -v160, v176, v172
	v_fma_f32 v164, -v160, v177, v173
	v_fma_f32 v165, -v160, v178, v174
	v_fma_f32 v167, -v160, v179, v175
	v_fma_f32 v168, -v160, v185, v168
	v_fma_f32 v168, v184, v186, v168
	ds_write_b32 v2, v168 offset:1024
	ds_read_b128 v[160:163], v3 offset:27648
	ds_read_b128 v[168:171], v3 offset:27904
	ds_read_b128 v[172:175], v3 offset:28160
	ds_read_b128 v[180:183], v3 offset:28672
	ds_read_b128 v[184:187], v4 offset:27648
	ds_read_b128 v[176:179], v3 offset:28416
	s_waitcnt lgkmcnt(7)
	v_mul_f32 v188, v159, v188
	v_mul_f32 v192, v159, v192
	v_mul_f32 v189, v164, v189
	v_mul_f32 v193, v164, v193
	v_fma_f32 v188, v165, v190, v188
	v_fma_f32 v192, v165, v194, v192
	v_fma_f32 v189, v167, v191, v189
	v_fma_f32 v193, v167, v195, v193
	v_add_f32 v188, v188, v189
	v_add_f32 v192, v192, v193
	v_mul_f32 v196, v159, v196
	v_mul_f32 v197, v164, v197
	v_add_f32_dpp v188, v188, v188 quad_perm:[1,0,3,2] row_mask:0xf bank_mask:0xf bound_ctrl:1
	v_add_f32_dpp v192, v192, v192 quad_perm:[1,0,3,2] row_mask:0xf bank_mask:0xf bound_ctrl:1
	v_mul_f32 v198, v165, v198
	v_add_f32_dpp v188, v188, v188 quad_perm:[2,3,0,1] row_mask:0xf bank_mask:0xf bound_ctrl:1
	v_add_f32_dpp v192, v192, v192 quad_perm:[2,3,0,1] row_mask:0xf bank_mask:0xf bound_ctrl:1
	v_mul_f32 v199, v167, v199
	v_add_f32_dpp v188, v188, v188 row_half_mirror row_mask:0xf bank_mask:0xf bound_ctrl:1
	v_add_f32_dpp v192, v192, v192 row_half_mirror row_mask:0xf bank_mask:0xf bound_ctrl:1
	v_fma_f32 v196, v208, v204, v196
	v_add_f32_dpp v188, v188, v188 row_mirror row_mask:0xf bank_mask:0xf bound_ctrl:1
	v_add_f32_dpp v192, v192, v192 row_mirror row_mask:0xf bank_mask:0xf bound_ctrl:1
	v_fma_f32 v197, v208, v205, v197
	v_fma_f32 v198, v208, v206, v198
	v_fma_f32 v199, v208, v207, v199
	v_fma_f32 v159, -v188, v200, v196
	v_fma_f32 v164, -v188, v201, v197
	v_fma_f32 v165, -v188, v202, v198
	v_fma_f32 v167, -v188, v203, v199
	v_fma_f32 v192, -v188, v209, v192
	v_fma_f32 v192, v208, v210, v192
	ds_write_b32 v2, v192 offset:1088
	ds_read_b128 v[188:191], v3 offset:29184
	ds_read_b128 v[192:195], v3 offset:29440
	ds_read_b128 v[196:199], v3 offset:29696
	ds_read_b128 v[204:207], v3 offset:30208
	ds_read_b128 v[208:211], v4 offset:29184
	ds_read_b128 v[200:203], v3 offset:29952
	s_waitcnt lgkmcnt(7)
; __device__ __forceinline__ float vfma(float a, float b, float c) { float d; asm("v_fma_f32 %0, %1, %2, %3" : "=v"(d) : "v"(a), "v"(b), "v"(c)); return d; }
; __device__ __forceinline__ float step_compute(float (&S)[4], const StepOp& o) {
;     float d1 = vmul(S[0], o.kk[0]), d2 = vmul(S[0], o.wr[0]), e1 = vmul(S[1], o.kk[1]), e2 = vmul(S[1], o.wr[1]);
;     d1 = vfma(S[2], o.kk[2], d1); d2 = vfma(S[2], o.wr[2], d2); e1 = vfma(S[3], o.kk[3], e1); e2 = vfma(S[3], o.wr[3], e2);
;     d1 = vadd(d1, e1); d2 = vadd(d2, e2);
;     float t0, t1, t2, t3;
;     asm volatile(
;         "v_mul_f32 %[t0], %[s0], %[w0]\n\t"
;         "v_mul_f32 %[t1], %[s1], %[w1]\n\t"
;         "v_add_f32_dpp %[d1], %[d1], %[d1] quad_perm:[1,0,3,2] row_mask:0xf bank_mask:0xf bound_ctrl:1\n\t"
;         "v_add_f32_dpp %[d2], %[d2], %[d2] quad_perm:[1,0,3,2] row_mask:0xf bank_mask:0xf bound_ctrl:1\n\t"
;         "v_mul_f32 %[t2], %[s2], %[w2]\n\t"
;         "v_add_f32_dpp %[d1], %[d1], %[d1] quad_perm:[2,3,0,1] row_mask:0xf bank_mask:0xf bound_ctrl:1\n\t"
;         "v_add_f32_dpp %[d2], %[d2], %[d2] quad_perm:[2,3,0,1] row_mask:0xf bank_mask:0xf bound_ctrl:1\n\t"
;         "v_mul_f32 %[t3], %[s3], %[w3]\n\t"
;         "v_add_f32_dpp %[d1], %[d1], %[d1] row_half_mirror row_mask:0xf bank_mask:0xf bound_ctrl:1\n\t"
;         "v_add_f32_dpp %[d2], %[d2], %[d2] row_half_mirror row_mask:0xf bank_mask:0xf bound_ctrl:1\n\t"
;         "v_fma_f32 %[t0], %[v], %[k0], %[t0]\n\t"
;         "v_add_f32_dpp %[d1], %[d1], %[d1] row_mirror row_mask:0xf bank_mask:0xf bound_ctrl:1\n\t"
;         "v_add_f32_dpp %[d2], %[d2], %[d2] row_mirror row_mask:0xf bank_mask:0xf bound_ctrl:1\n\t"
;         "v_fma_f32 %[t1], %[v], %[k1], %[t1]\n\t"
;         "v_fma_f32 %[t2], %[v], %[k2], %[t2]\n\t"
;         "v_fma_f32 %[t3], %[v], %[k3], %[t3]"
;         : [t0] "=&v"(t0), [t1] "=&v"(t1), [t2] "=&v"(t2), [t3] "=&v"(t3), [d1] "+v"(d1), [d2] "+v"(d2)
;         : [s0] "v"(S[0]), [s1] "v"(S[1]), [s2] "v"(S[2]), [s3] "v"(S[3]), [w0] "v"(o.w[0]), [w1] "v"(o.w[1]), [w2] "v"(o.w[2]), [w3] "v"(o.w[3]),
;           [k0] "v"(o.k[0]), [k1] "v"(o.k[1]), [k2] "v"(o.k[2]), [k3] "v"(o.k[3]), [v] "v"(o.q[0]));
;     S[0] = vnfma(d1, o.b[0], t0); S[1] = vnfma(d1, o.b[1], t1); S[2] = vnfma(d1, o.b[2], t2); S[3] = vnfma(d1, o.b[3], t3);
;     return vfma(o.q[0], o.q[2], vnfma(d1, o.q[1], d2));
; }
	v_mul_f32 v160, v159, v160
	v_mul_f32 v168, v159, v168
	v_mul_f32 v161, v164, v161
	v_mul_f32 v169, v164, v169
	v_fma_f32 v160, v165, v162, v160
	v_fma_f32 v168, v165, v170, v168
	v_fma_f32 v161, v167, v163, v161
	v_fma_f32 v169, v167, v171, v169
	v_add_f32 v160, v160, v161
	v_add_f32 v168, v168, v169
	v_mul_f32 v172, v159, v172
	v_mul_f32 v173, v164, v173
	v_add_f32_dpp v160, v160, v160 quad_perm:[1,0,3,2] row_mask:0xf bank_mask:0xf bound_ctrl:1
	v_add_f32_dpp v168, v168, v168 quad_perm:[1,0,3,2] row_mask:0xf bank_mask:0xf bound_ctrl:1
	v_mul_f32 v174, v165, v174
	v_add_f32_dpp v160, v160, v160 quad_perm:[2,3,0,1] row_mask:0xf bank_mask:0xf bound_ctrl:1
	v_add_f32_dpp v168, v168, v168 quad_perm:[2,3,0,1] row_mask:0xf bank_mask:0xf bound_ctrl:1
	v_mul_f32 v175, v167, v175
	v_add_f32_dpp v160, v160, v160 row_half_mirror row_mask:0xf bank_mask:0xf bound_ctrl:1
	v_add_f32_dpp v168, v168, v168 row_half_mirror row_mask:0xf bank_mask:0xf bound_ctrl:1
	v_fma_f32 v172, v184, v180, v172
	v_add_f32_dpp v160, v160, v160 row_mirror row_mask:0xf bank_mask:0xf bound_ctrl:1
	v_add_f32_dpp v168, v168, v168 row_mirror row_mask:0xf bank_mask:0xf bound_ctrl:1
	v_fma_f32 v173, v184, v181, v173
	v_fma_f32 v174, v184, v182, v174
	v_fma_f32 v175, v184, v183, v175
	v_fma_f32 v159, -v160, v176, v172
	v_fma_f32 v164, -v160, v177, v173
	v_fma_f32 v165, -v160, v178, v174
	v_fma_f32 v167, -v160, v179, v175
	v_fma_f32 v168, -v160, v185, v168
	v_fma_f32 v168, v184, v186, v168
	ds_write_b32 v2, v168 offset:1152
	ds_read_b128 v[160:163], v3 offset:30720
	ds_read_b128 v[168:171], v3 offset:30976
	ds_read_b128 v[172:175], v3 offset:31232
	ds_read_b128 v[180:183], v3 offset:31744
	ds_read_b128 v[184:187], v4 offset:30720
	ds_read_b128 v[176:179], v3 offset:31488
	s_waitcnt lgkmcnt(7)
	v_mul_f32 v188, v159, v188
	v_mul_f32 v192, v159, v192
	v_mul_f32 v189, v164, v189
	v_mul_f32 v193, v164, v193
	v_fma_f32 v188, v165, v190, v188
	v_fma_f32 v192, v165, v194, v192
	v_fma_f32 v189, v167, v191, v189
	v_fma_f32 v193, v167, v195, v193
	v_add_f32 v188, v188, v189
	v_add_f32 v192, v192, v193
	v_mul_f32 v196, v159, v196
	v_mul_f32 v197, v164, v197
	v_add_f32_dpp v188, v188, v188 quad_perm:[1,0,3,2] row_mask:0xf bank_mask:0xf bound_ctrl:1
	v_add_f32_dpp v192, v192, v192 quad_perm:[1,0,3,2] row_mask:0xf bank_mask:0xf bound_ctrl:1
	v_mul_f32 v198, v165, v198
	v_add_f32_dpp v188, v188, v188 quad_perm:[2,3,0,1] row_mask:0xf bank_mask:0xf bound_ctrl:1
	v_add_f32_dpp v192, v192, v192 quad_perm:[2,3,0,1] row_mask:0xf bank_mask:0xf bound_ctrl:1
	v_mul_f32 v199, v167, v199
	v_add_f32_dpp v188, v188, v188 row_half_mirror row_mask:0xf bank_mask:0xf bound_ctrl:1
	v_add_f32_dpp v192, v192, v192 row_half_mirror row_mask:0xf bank_mask:0xf bound_ctrl:1
	v_fma_f32 v196, v208, v204, v196
	v_add_f32_dpp v188, v188, v188 row_mirror row_mask:0xf bank_mask:0xf bound_ctrl:1
	v_add_f32_dpp v192, v192, v192 row_mirror row_mask:0xf bank_mask:0xf bound_ctrl:1
	v_fma_f32 v197, v208, v205, v197
	v_fma_f32 v198, v208, v206, v198
	v_fma_f32 v199, v208, v207, v199
	v_fma_f32 v159, -v188, v200, v196
	v_fma_f32 v164, -v188, v201, v197
	v_fma_f32 v165, -v188, v202, v198
	v_fma_f32 v167, -v188, v203, v199
	v_fma_f32 v192, -v188, v209, v192
	v_fma_f32 v192, v208, v210, v192
	ds_write_b32 v2, v192 offset:1216
	ds_read_b128 v[188:191], v3 offset:32256
	ds_read_b128 v[192:195], v3 offset:32512
	ds_read_b128 v[196:199], v3 offset:32768
	ds_read_b128 v[204:207], v3 offset:33280
	ds_read_b128 v[208:211], v4 offset:32256
	ds_read_b128 v[200:203], v3 offset:33024
	s_waitcnt lgkmcnt(7)
	v_mul_f32 v160, v159, v160
	v_mul_f32 v168, v159, v168
	v_mul_f32 v161, v164, v161
	v_mul_f32 v169, v164, v169
	v_fma_f32 v160, v165, v162, v160
	v_fma_f32 v168, v165, v170, v168
	v_fma_f32 v161, v167, v163, v161
	v_fma_f32 v169, v167, v171, v169
	v_add_f32 v160, v160, v161
	v_add_f32 v168, v168, v169
	v_mul_f32 v172, v159, v172
	v_mul_f32 v173, v164, v173
	v_add_f32_dpp v160, v160, v160 quad_perm:[1,0,3,2] row_mask:0xf bank_mask:0xf bound_ctrl:1
	v_add_f32_dpp v168, v168, v168 quad_perm:[1,0,3,2] row_mask:0xf bank_mask:0xf bound_ctrl:1
	v_mul_f32 v174, v165, v174
	v_add_f32_dpp v160, v160, v160 quad_perm:[2,3,0,1] row_mask:0xf bank_mask:0xf bound_ctrl:1
	v_add_f32_dpp v168, v168, v168 quad_perm:[2,3,0,1] row_mask:0xf bank_mask:0xf bound_ctrl:1
	v_mul_f32 v175, v167, v175
	v_add_f32_dpp v160, v160, v160 row_half_mirror row_mask:0xf bank_mask:0xf bound_ctrl:1
	v_add_f32_dpp v168, v168, v168 row_half_mirror row_mask:0xf bank_mask:0xf bound_ctrl:1
	v_fma_f32 v172, v184, v180, v172
	v_add_f32_dpp v160, v160, v160 row_mirror row_mask:0xf bank_mask:0xf bound_ctrl:1
	v_add_f32_dpp v168, v168, v168 row_mirror row_mask:0xf bank_mask:0xf bound_ctrl:1
	v_fma_f32 v173, v184, v181, v173
	v_fma_f32 v174, v184, v182, v174
	v_fma_f32 v175, v184, v183, v175
	v_fma_f32 v159, -v160, v176, v172
	v_fma_f32 v164, -v160, v177, v173
	v_fma_f32 v165, -v160, v178, v174
	v_fma_f32 v167, -v160, v179, v175
	v_fma_f32 v168, -v160, v185, v168
	v_fma_f32 v168, v184, v186, v168
	ds_write_b32 v2, v168 offset:1280
	ds_read_b128 v[160:163], v3 offset:33792
	ds_read_b128 v[168:171], v3 offset:34048
	ds_read_b128 v[172:175], v3 offset:34304
	ds_read_b128 v[180:183], v3 offset:34816
	ds_read_b128 v[184:187], v4 offset:33792
	ds_read_b128 v[176:179], v3 offset:34560
	s_waitcnt lgkmcnt(7)
; __device__ __forceinline__ float vfma(float a, float b, float c) { float d; asm("v_fma_f32 %0, %1, %2, %3" : "=v"(d) : "v"(a), "v"(b), "v"(c)); return d; }
; __device__ __forceinline__ float step_compute(float (&S)[4], const StepOp& o) {
;     float d1 = vmul(S[0], o.kk[0]), d2 = vmul(S[0], o.wr[0]), e1 = vmul(S[1], o.kk[1]), e2 = vmul(S[1], o.wr[1]);
;     d1 = vfma(S[2], o.kk[2], d1); d2 = vfma(S[2], o.wr[2], d2); e1 = vfma(S[3], o.kk[3], e1); e2 = vfma(S[3], o.wr[3], e2);
;     d1 = vadd(d1, e1); d2 = vadd(d2, e2);
;     float t0, t1, t2, t3;
;     asm volatile(
;         "v_mul_f32 %[t0], %[s0], %[w0]\n\t"
;         "v_mul_f32 %[t1], %[s1], %[w1]\n\t"
;         "v_add_f32_dpp %[d1], %[d1], %[d1] quad_perm:[1,0,3,2] row_mask:0xf bank_mask:0xf bound_ctrl:1\n\t"
;         "v_add_f32_dpp %[d2], %[d2], %[d2] quad_perm:[1,0,3,2] row_mask:0xf bank_mask:0xf bound_ctrl:1\n\t"
;         "v_mul_f32 %[t2], %[s2], %[w2]\n\t"
;         "v_add_f32_dpp %[d1], %[d1], %[d1] quad_perm:[2,3,0,1] row_mask:0xf bank_mask:0xf bound_ctrl:1\n\t"
;         "v_add_f32_dpp %[d2], %[d2], %[d2] quad_perm:[2,3,0,1] row_mask:0xf bank_mask:0xf bound_ctrl:1\n\t"
;         "v_mul_f32 %[t3], %[s3], %[w3]\n\t"
;         "v_add_f32_dpp %[d1], %[d1], %[d1] row_half_mirror row_mask:0xf bank_mask:0xf bound_ctrl:1\n\t"
;         "v_add_f32_dpp %[d2], %[d2], %[d2] row_half_mirror row_mask:0xf bank_mask:0xf bound_ctrl:1\n\t"
;         "v_fma_f32 %[t0], %[v], %[k0], %[t0]\n\t"
;         "v_add_f32_dpp %[d1], %[d1], %[d1] row_mirror row_mask:0xf bank_mask:0xf bound_ctrl:1\n\t"
;         "v_add_f32_dpp %[d2], %[d2], %[d2] row_mirror row_mask:0xf bank_mask:0xf bound_ctrl:1\n\t"
;         "v_fma_f32 %[t1], %[v], %[k1], %[t1]\n\t"
;         "v_fma_f32 %[t2], %[v], %[k2], %[t2]\n\t"
;         "v_fma_f32 %[t3], %[v], %[k3], %[t3]"
;         : [t0] "=&v"(t0), [t1] "=&v"(t1), [t2] "=&v"(t2), [t3] "=&v"(t3), [d1] "+v"(d1), [d2] "+v"(d2)
;         : [s0] "v"(S[0]), [s1] "v"(S[1]), [s2] "v"(S[2]), [s3] "v"(S[3]), [w0] "v"(o.w[0]), [w1] "v"(o.w[1]), [w2] "v"(o.w[2]), [w3] "v"(o.w[3]),
;           [k0] "v"(o.k[0]), [k1] "v"(o.k[1]), [k2] "v"(o.k[2]), [k3] "v"(o.k[3]), [v] "v"(o.q[0]));
;     S[0] = vnfma(d1, o.b[0], t0); S[1] = vnfma(d1, o.b[1], t1); S[2] = vnfma(d1, o.b[2], t2); S[3] = vnfma(d1, o.b[3], t3);
;     return vfma(o.q[0], o.q[2], vnfma(d1, o.q[1], d2));
; }
	v_mul_f32 v188, v159, v188
	v_mul_f32 v192, v159, v192
	v_mul_f32 v189, v164, v189
	v_mul_f32 v193, v164, v193
	v_fma_f32 v188, v165, v190, v188
	v_fma_f32 v192, v165, v194, v192
	v_fma_f32 v189, v167, v191, v189
	v_fma_f32 v193, v167, v195, v193
	v_add_f32 v188, v188, v189
	v_add_f32 v192, v192, v193
	v_mul_f32 v196, v159, v196
	v_mul_f32 v197, v164, v197
	v_add_f32_dpp v188, v188, v188 quad_perm:[1,0,3,2] row_mask:0xf bank_mask:0xf bound_ctrl:1
	v_add_f32_dpp v192, v192, v192 quad_perm:[1,0,3,2] row_mask:0xf bank_mask:0xf bound_ctrl:1
	v_mul_f32 v198, v165, v198
	v_add_f32_dpp v188, v188, v188 quad_perm:[2,3,0,1] row_mask:0xf bank_mask:0xf bound_ctrl:1
	v_add_f32_dpp v192, v192, v192 quad_perm:[2,3,0,1] row_mask:0xf bank_mask:0xf bound_ctrl:1
	v_mul_f32 v199, v167, v199
	v_add_f32_dpp v188, v188, v188 row_half_mirror row_mask:0xf bank_mask:0xf bound_ctrl:1
	v_add_f32_dpp v192, v192, v192 row_half_mirror row_mask:0xf bank_mask:0xf bound_ctrl:1
	v_fma_f32 v196, v208, v204, v196
	v_add_f32_dpp v188, v188, v188 row_mirror row_mask:0xf bank_mask:0xf bound_ctrl:1
	v_add_f32_dpp v192, v192, v192 row_mirror row_mask:0xf bank_mask:0xf bound_ctrl:1
	v_fma_f32 v197, v208, v205, v197
	v_fma_f32 v198, v208, v206, v198
	v_fma_f32 v199, v208, v207, v199
	v_fma_f32 v159, -v188, v200, v196
	v_fma_f32 v164, -v188, v201, v197
	v_fma_f32 v165, -v188, v202, v198
	v_fma_f32 v167, -v188, v203, v199
	v_fma_f32 v192, -v188, v209, v192
	v_fma_f32 v192, v208, v210, v192
	ds_write_b32 v2, v192 offset:1344
	ds_read_b128 v[188:191], v3 offset:35328
	ds_read_b128 v[192:195], v3 offset:35584
	ds_read_b128 v[196:199], v3 offset:35840
	ds_read_b128 v[204:207], v3 offset:36352
	ds_read_b128 v[208:211], v4 offset:35328
	ds_read_b128 v[200:203], v3 offset:36096
	s_waitcnt lgkmcnt(7)
	v_mul_f32 v160, v159, v160
	v_mul_f32 v168, v159, v168
	v_mul_f32 v161, v164, v161
	v_mul_f32 v169, v164, v169
	v_fma_f32 v160, v165, v162, v160
	v_fma_f32 v168, v165, v170, v168
	v_fma_f32 v161, v167, v163, v161
	v_fma_f32 v169, v167, v171, v169
	v_add_f32 v160, v160, v161
	v_add_f32 v168, v168, v169
	v_mul_f32 v172, v159, v172
	v_mul_f32 v173, v164, v173
	v_add_f32_dpp v160, v160, v160 quad_perm:[1,0,3,2] row_mask:0xf bank_mask:0xf bound_ctrl:1
	v_add_f32_dpp v168, v168, v168 quad_perm:[1,0,3,2] row_mask:0xf bank_mask:0xf bound_ctrl:1
	v_mul_f32 v174, v165, v174
	v_add_f32_dpp v160, v160, v160 quad_perm:[2,3,0,1] row_mask:0xf bank_mask:0xf bound_ctrl:1
	v_add_f32_dpp v168, v168, v168 quad_perm:[2,3,0,1] row_mask:0xf bank_mask:0xf bound_ctrl:1
	v_mul_f32 v175, v167, v175
	v_add_f32_dpp v160, v160, v160 row_half_mirror row_mask:0xf bank_mask:0xf bound_ctrl:1
	v_add_f32_dpp v168, v168, v168 row_half_mirror row_mask:0xf bank_mask:0xf bound_ctrl:1
	v_fma_f32 v172, v184, v180, v172
	v_add_f32_dpp v160, v160, v160 row_mirror row_mask:0xf bank_mask:0xf bound_ctrl:1
	v_add_f32_dpp v168, v168, v168 row_mirror row_mask:0xf bank_mask:0xf bound_ctrl:1
	v_fma_f32 v173, v184, v181, v173
	v_fma_f32 v174, v184, v182, v174
	v_fma_f32 v175, v184, v183, v175
	v_fma_f32 v159, -v160, v176, v172
	v_fma_f32 v164, -v160, v177, v173
	v_fma_f32 v165, -v160, v178, v174
	v_fma_f32 v167, -v160, v179, v175
	v_fma_f32 v168, -v160, v185, v168
	v_fma_f32 v168, v184, v186, v168
	ds_write_b32 v2, v168 offset:1408
	ds_read_b128 v[160:163], v3 offset:36864
	ds_read_b128 v[168:171], v3 offset:37120
	ds_read_b128 v[172:175], v3 offset:37376
	ds_read_b128 v[180:183], v3 offset:37888
	ds_read_b128 v[184:187], v4 offset:36864
	ds_read_b128 v[176:179], v3 offset:37632
	s_waitcnt lgkmcnt(7)
	v_mul_f32 v188, v159, v188
	v_mul_f32 v192, v159, v192
	v_mul_f32 v189, v164, v189
	v_mul_f32 v193, v164, v193
	v_fma_f32 v188, v165, v190, v188
	v_fma_f32 v192, v165, v194, v192
	v_fma_f32 v189, v167, v191, v189
	v_fma_f32 v193, v167, v195, v193
	v_add_f32 v188, v188, v189
	v_add_f32 v192, v192, v193
	v_mul_f32 v196, v159, v196
	v_mul_f32 v197, v164, v197
	v_add_f32_dpp v188, v188, v188 quad_perm:[1,0,3,2] row_mask:0xf bank_mask:0xf bound_ctrl:1
	v_add_f32_dpp v192, v192, v192 quad_perm:[1,0,3,2] row_mask:0xf bank_mask:0xf bound_ctrl:1
	v_mul_f32 v198, v165, v198
	v_add_f32_dpp v188, v188, v188 quad_perm:[2,3,0,1] row_mask:0xf bank_mask:0xf bound_ctrl:1
	v_add_f32_dpp v192, v192, v192 quad_perm:[2,3,0,1] row_mask:0xf bank_mask:0xf bound_ctrl:1
	v_mul_f32 v199, v167, v199
	v_add_f32_dpp v188, v188, v188 row_half_mirror row_mask:0xf bank_mask:0xf bound_ctrl:1
	v_add_f32_dpp v192, v192, v192 row_half_mirror row_mask:0xf bank_mask:0xf bound_ctrl:1
	v_fma_f32 v196, v208, v204, v196
	v_add_f32_dpp v188, v188, v188 row_mirror row_mask:0xf bank_mask:0xf bound_ctrl:1
	v_add_f32_dpp v192, v192, v192 row_mirror row_mask:0xf bank_mask:0xf bound_ctrl:1
	v_fma_f32 v197, v208, v205, v197
	v_fma_f32 v198, v208, v206, v198
	v_fma_f32 v199, v208, v207, v199
	v_fma_f32 v159, -v188, v200, v196
	v_fma_f32 v164, -v188, v201, v197
	v_fma_f32 v165, -v188, v202, v198
	v_fma_f32 v167, -v188, v203, v199
	v_fma_f32 v192, -v188, v209, v192
	v_fma_f32 v192, v208, v210, v192
	ds_write_b32 v2, v192 offset:1472
	ds_read_b128 v[188:191], v3 offset:38400
	ds_read_b128 v[192:195], v3 offset:38656
	ds_read_b128 v[196:199], v3 offset:38912
	ds_read_b128 v[204:207], v3 offset:39424
	ds_read_b128 v[208:211], v4 offset:38400
	ds_read_b128 v[200:203], v3 offset:39168
	s_waitcnt lgkmcnt(7)
; __device__ __forceinline__ float vfma(float a, float b, float c) { float d; asm("v_fma_f32 %0, %1, %2, %3" : "=v"(d) : "v"(a), "v"(b), "v"(c)); return d; }
; __device__ __forceinline__ float step_compute(float (&S)[4], const StepOp& o) {
;     float d1 = vmul(S[0], o.kk[0]), d2 = vmul(S[0], o.wr[0]), e1 = vmul(S[1], o.kk[1]), e2 = vmul(S[1], o.wr[1]);
;     d1 = vfma(S[2], o.kk[2], d1); d2 = vfma(S[2], o.wr[2], d2); e1 = vfma(S[3], o.kk[3], e1); e2 = vfma(S[3], o.wr[3], e2);
;     d1 = vadd(d1, e1); d2 = vadd(d2, e2);
;     float t0, t1, t2, t3;
;     asm volatile(
;         "v_mul_f32 %[t0], %[s0], %[w0]\n\t"
;         "v_mul_f32 %[t1], %[s1], %[w1]\n\t"
;         "v_add_f32_dpp %[d1], %[d1], %[d1] quad_perm:[1,0,3,2] row_mask:0xf bank_mask:0xf bound_ctrl:1\n\t"
;         "v_add_f32_dpp %[d2], %[d2], %[d2] quad_perm:[1,0,3,2] row_mask:0xf bank_mask:0xf bound_ctrl:1\n\t"
;         "v_mul_f32 %[t2], %[s2], %[w2]\n\t"
;         "v_add_f32_dpp %[d1], %[d1], %[d1] quad_perm:[2,3,0,1] row_mask:0xf bank_mask:0xf bound_ctrl:1\n\t"
;         "v_add_f32_dpp %[d2], %[d2], %[d2] quad_perm:[2,3,0,1] row_mask:0xf bank_mask:0xf bound_ctrl:1\n\t"
;         "v_mul_f32 %[t3], %[s3], %[w3]\n\t"
;         "v_add_f32_dpp %[d1], %[d1], %[d1] row_half_mirror row_mask:0xf bank_mask:0xf bound_ctrl:1\n\t"
;         "v_add_f32_dpp %[d2], %[d2], %[d2] row_half_mirror row_mask:0xf bank_mask:0xf bound_ctrl:1\n\t"
;         "v_fma_f32 %[t0], %[v], %[k0], %[t0]\n\t"
;         "v_add_f32_dpp %[d1], %[d1], %[d1] row_mirror row_mask:0xf bank_mask:0xf bound_ctrl:1\n\t"
;         "v_add_f32_dpp %[d2], %[d2], %[d2] row_mirror row_mask:0xf bank_mask:0xf bound_ctrl:1\n\t"
;         "v_fma_f32 %[t1], %[v], %[k1], %[t1]\n\t"
;         "v_fma_f32 %[t2], %[v], %[k2], %[t2]\n\t"
;         "v_fma_f32 %[t3], %[v], %[k3], %[t3]"
;         : [t0] "=&v"(t0), [t1] "=&v"(t1), [t2] "=&v"(t2), [t3] "=&v"(t3), [d1] "+v"(d1), [d2] "+v"(d2)
;         : [s0] "v"(S[0]), [s1] "v"(S[1]), [s2] "v"(S[2]), [s3] "v"(S[3]), [w0] "v"(o.w[0]), [w1] "v"(o.w[1]), [w2] "v"(o.w[2]), [w3] "v"(o.w[3]),
;           [k0] "v"(o.k[0]), [k1] "v"(o.k[1]), [k2] "v"(o.k[2]), [k3] "v"(o.k[3]), [v] "v"(o.q[0]));
;     S[0] = vnfma(d1, o.b[0], t0); S[1] = vnfma(d1, o.b[1], t1); S[2] = vnfma(d1, o.b[2], t2); S[3] = vnfma(d1, o.b[3], t3);
;     return vfma(o.q[0], o.q[2], vnfma(d1, o.q[1], d2));
; }
	v_mul_f32 v160, v159, v160
	v_mul_f32 v168, v159, v168
	v_mul_f32 v161, v164, v161
	v_mul_f32 v169, v164, v169
	v_fma_f32 v160, v165, v162, v160
	v_fma_f32 v168, v165, v170, v168
	v_fma_f32 v161, v167, v163, v161
	v_fma_f32 v169, v167, v171, v169
	v_add_f32 v160, v160, v161
	v_add_f32 v168, v168, v169
	v_mul_f32 v172, v159, v172
	v_mul_f32 v173, v164, v173
	v_add_f32_dpp v160, v160, v160 quad_perm:[1,0,3,2] row_mask:0xf bank_mask:0xf bound_ctrl:1
	v_add_f32_dpp v168, v168, v168 quad_perm:[1,0,3,2] row_mask:0xf bank_mask:0xf bound_ctrl:1
	v_mul_f32 v174, v165, v174
	v_add_f32_dpp v160, v160, v160 quad_perm:[2,3,0,1] row_mask:0xf bank_mask:0xf bound_ctrl:1
	v_add_f32_dpp v168, v168, v168 quad_perm:[2,3,0,1] row_mask:0xf bank_mask:0xf bound_ctrl:1
	v_mul_f32 v175, v167, v175
	v_add_f32_dpp v160, v160, v160 row_half_mirror row_mask:0xf bank_mask:0xf bound_ctrl:1
	v_add_f32_dpp v168, v168, v168 row_half_mirror row_mask:0xf bank_mask:0xf bound_ctrl:1
	v_fma_f32 v172, v184, v180, v172
	v_add_f32_dpp v160, v160, v160 row_mirror row_mask:0xf bank_mask:0xf bound_ctrl:1
	v_add_f32_dpp v168, v168, v168 row_mirror row_mask:0xf bank_mask:0xf bound_ctrl:1
	v_fma_f32 v173, v184, v181, v173
	v_fma_f32 v174, v184, v182, v174
	v_fma_f32 v175, v184, v183, v175
	v_fma_f32 v159, -v160, v176, v172
	v_fma_f32 v164, -v160, v177, v173
	v_fma_f32 v165, -v160, v178, v174
	v_fma_f32 v167, -v160, v179, v175
	v_fma_f32 v168, -v160, v185, v168
	v_fma_f32 v168, v184, v186, v168
	ds_write_b32 v2, v168 offset:1536
	ds_read_b128 v[160:163], v3 offset:39936
	ds_read_b128 v[168:171], v3 offset:40192
	ds_read_b128 v[172:175], v3 offset:40448
	ds_read_b128 v[180:183], v3 offset:40960
	ds_read_b128 v[184:187], v4 offset:39936
	ds_read_b128 v[176:179], v3 offset:40704
	s_waitcnt lgkmcnt(7)
	v_mul_f32 v188, v159, v188
	v_mul_f32 v192, v159, v192
	v_mul_f32 v189, v164, v189
	v_mul_f32 v193, v164, v193
	v_fma_f32 v188, v165, v190, v188
	v_fma_f32 v192, v165, v194, v192
	v_fma_f32 v189, v167, v191, v189
	v_fma_f32 v193, v167, v195, v193
	v_add_f32 v188, v188, v189
	v_add_f32 v192, v192, v193
	v_mul_f32 v196, v159, v196
	v_mul_f32 v197, v164, v197
	v_add_f32_dpp v188, v188, v188 quad_perm:[1,0,3,2] row_mask:0xf bank_mask:0xf bound_ctrl:1
	v_add_f32_dpp v192, v192, v192 quad_perm:[1,0,3,2] row_mask:0xf bank_mask:0xf bound_ctrl:1
	v_mul_f32 v198, v165, v198
	v_add_f32_dpp v188, v188, v188 quad_perm:[2,3,0,1] row_mask:0xf bank_mask:0xf bound_ctrl:1
	v_add_f32_dpp v192, v192, v192 quad_perm:[2,3,0,1] row_mask:0xf bank_mask:0xf bound_ctrl:1
	v_mul_f32 v199, v167, v199
	v_add_f32_dpp v188, v188, v188 row_half_mirror row_mask:0xf bank_mask:0xf bound_ctrl:1
	v_add_f32_dpp v192, v192, v192 row_half_mirror row_mask:0xf bank_mask:0xf bound_ctrl:1
	v_fma_f32 v196, v208, v204, v196
	v_add_f32_dpp v188, v188, v188 row_mirror row_mask:0xf bank_mask:0xf bound_ctrl:1
	v_add_f32_dpp v192, v192, v192 row_mirror row_mask:0xf bank_mask:0xf bound_ctrl:1
	v_fma_f32 v197, v208, v205, v197
	v_fma_f32 v198, v208, v206, v198
	v_fma_f32 v199, v208, v207, v199
	v_fma_f32 v159, -v188, v200, v196
	v_fma_f32 v164, -v188, v201, v197
	v_fma_f32 v165, -v188, v202, v198
	v_fma_f32 v167, -v188, v203, v199
	v_fma_f32 v192, -v188, v209, v192
	v_fma_f32 v192, v208, v210, v192
	ds_write_b32 v2, v192 offset:1600
	ds_read_b128 v[188:191], v3 offset:41472
	ds_read_b128 v[192:195], v3 offset:41728
	ds_read_b128 v[196:199], v3 offset:41984
	ds_read_b128 v[204:207], v3 offset:42496
	ds_read_b128 v[208:211], v4 offset:41472
	ds_read_b128 v[200:203], v3 offset:42240
	s_waitcnt lgkmcnt(7)
	v_mul_f32 v160, v159, v160
	v_mul_f32 v168, v159, v168
	v_mul_f32 v161, v164, v161
	v_mul_f32 v169, v164, v169
	v_fma_f32 v160, v165, v162, v160
	v_fma_f32 v168, v165, v170, v168
	v_fma_f32 v161, v167, v163, v161
	v_fma_f32 v169, v167, v171, v169
	v_add_f32 v160, v160, v161
	v_add_f32 v168, v168, v169
	v_mul_f32 v172, v159, v172
	v_mul_f32 v173, v164, v173
	v_add_f32_dpp v160, v160, v160 quad_perm:[1,0,3,2] row_mask:0xf bank_mask:0xf bound_ctrl:1
	v_add_f32_dpp v168, v168, v168 quad_perm:[1,0,3,2] row_mask:0xf bank_mask:0xf bound_ctrl:1
	v_mul_f32 v174, v165, v174
	v_add_f32_dpp v160, v160, v160 quad_perm:[2,3,0,1] row_mask:0xf bank_mask:0xf bound_ctrl:1
	v_add_f32_dpp v168, v168, v168 quad_perm:[2,3,0,1] row_mask:0xf bank_mask:0xf bound_ctrl:1
	v_mul_f32 v175, v167, v175
	v_add_f32_dpp v160, v160, v160 row_half_mirror row_mask:0xf bank_mask:0xf bound_ctrl:1
	v_add_f32_dpp v168, v168, v168 row_half_mirror row_mask:0xf bank_mask:0xf bound_ctrl:1
	v_fma_f32 v172, v184, v180, v172
	v_add_f32_dpp v160, v160, v160 row_mirror row_mask:0xf bank_mask:0xf bound_ctrl:1
	v_add_f32_dpp v168, v168, v168 row_mirror row_mask:0xf bank_mask:0xf bound_ctrl:1
	v_fma_f32 v173, v184, v181, v173
	v_fma_f32 v174, v184, v182, v174
	v_fma_f32 v175, v184, v183, v175
	v_fma_f32 v159, -v160, v176, v172
	v_fma_f32 v164, -v160, v177, v173
	v_fma_f32 v165, -v160, v178, v174
	v_fma_f32 v167, -v160, v179, v175
	v_fma_f32 v168, -v160, v185, v168
	v_fma_f32 v168, v184, v186, v168
	ds_write_b32 v2, v168 offset:1664
	ds_read_b128 v[160:163], v3 offset:43008
	ds_read_b128 v[168:171], v3 offset:43264
	ds_read_b128 v[172:175], v3 offset:43520
	ds_read_b128 v[180:183], v3 offset:44032
	ds_read_b128 v[184:187], v4 offset:43008
	ds_read_b128 v[176:179], v3 offset:43776
	s_waitcnt lgkmcnt(7)
; __device__ __forceinline__ float vfma(float a, float b, float c) { float d; asm("v_fma_f32 %0, %1, %2, %3" : "=v"(d) : "v"(a), "v"(b), "v"(c)); return d; }
; __device__ __forceinline__ float step_compute(float (&S)[4], const StepOp& o) {
;     float d1 = vmul(S[0], o.kk[0]), d2 = vmul(S[0], o.wr[0]), e1 = vmul(S[1], o.kk[1]), e2 = vmul(S[1], o.wr[1]);
;     d1 = vfma(S[2], o.kk[2], d1); d2 = vfma(S[2], o.wr[2], d2); e1 = vfma(S[3], o.kk[3], e1); e2 = vfma(S[3], o.wr[3], e2);
;     d1 = vadd(d1, e1); d2 = vadd(d2, e2);
;     float t0, t1, t2, t3;
;     asm volatile(
;         "v_mul_f32 %[t0], %[s0], %[w0]\n\t"
;         "v_mul_f32 %[t1], %[s1], %[w1]\n\t"
;         "v_add_f32_dpp %[d1], %[d1], %[d1] quad_perm:[1,0,3,2] row_mask:0xf bank_mask:0xf bound_ctrl:1\n\t"
;         "v_add_f32_dpp %[d2], %[d2], %[d2] quad_perm:[1,0,3,2] row_mask:0xf bank_mask:0xf bound_ctrl:1\n\t"
;         "v_mul_f32 %[t2], %[s2], %[w2]\n\t"
;         "v_add_f32_dpp %[d1], %[d1], %[d1] quad_perm:[2,3,0,1] row_mask:0xf bank_mask:0xf bound_ctrl:1\n\t"
;         "v_add_f32_dpp %[d2], %[d2], %[d2] quad_perm:[2,3,0,1] row_mask:0xf bank_mask:0xf bound_ctrl:1\n\t"
;         "v_mul_f32 %[t3], %[s3], %[w3]\n\t"
;         "v_add_f32_dpp %[d1], %[d1], %[d1] row_half_mirror row_mask:0xf bank_mask:0xf bound_ctrl:1\n\t"
;         "v_add_f32_dpp %[d2], %[d2], %[d2] row_half_mirror row_mask:0xf bank_mask:0xf bound_ctrl:1\n\t"
;         "v_fma_f32 %[t0], %[v], %[k0], %[t0]\n\t"
;         "v_add_f32_dpp %[d1], %[d1], %[d1] row_mirror row_mask:0xf bank_mask:0xf bound_ctrl:1\n\t"
;         "v_add_f32_dpp %[d2], %[d2], %[d2] row_mirror row_mask:0xf bank_mask:0xf bound_ctrl:1\n\t"
;         "v_fma_f32 %[t1], %[v], %[k1], %[t1]\n\t"
;         "v_fma_f32 %[t2], %[v], %[k2], %[t2]\n\t"
;         "v_fma_f32 %[t3], %[v], %[k3], %[t3]"
;         : [t0] "=&v"(t0), [t1] "=&v"(t1), [t2] "=&v"(t2), [t3] "=&v"(t3), [d1] "+v"(d1), [d2] "+v"(d2)
;         : [s0] "v"(S[0]), [s1] "v"(S[1]), [s2] "v"(S[2]), [s3] "v"(S[3]), [w0] "v"(o.w[0]), [w1] "v"(o.w[1]), [w2] "v"(o.w[2]), [w3] "v"(o.w[3]),
;           [k0] "v"(o.k[0]), [k1] "v"(o.k[1]), [k2] "v"(o.k[2]), [k3] "v"(o.k[3]), [v] "v"(o.q[0]));
;     S[0] = vnfma(d1, o.b[0], t0); S[1] = vnfma(d1, o.b[1], t1); S[2] = vnfma(d1, o.b[2], t2); S[3] = vnfma(d1, o.b[3], t3);
;     return vfma(o.q[0], o.q[2], vnfma(d1, o.q[1], d2));
; }
	v_mul_f32 v188, v159, v188
	v_mul_f32 v192, v159, v192
	v_mul_f32 v189, v164, v189
	v_mul_f32 v193, v164, v193
	v_fma_f32 v188, v165, v190, v188
	v_fma_f32 v192, v165, v194, v192
	v_fma_f32 v189, v167, v191, v189
	v_fma_f32 v193, v167, v195, v193
	v_add_f32 v188, v188, v189
	v_add_f32 v192, v192, v193
	v_mul_f32 v196, v159, v196
	v_mul_f32 v197, v164, v197
	v_add_f32_dpp v188, v188, v188 quad_perm:[1,0,3,2] row_mask:0xf bank_mask:0xf bound_ctrl:1
	v_add_f32_dpp v192, v192, v192 quad_perm:[1,0,3,2] row_mask:0xf bank_mask:0xf bound_ctrl:1
	v_mul_f32 v198, v165, v198
	v_add_f32_dpp v188, v188, v188 quad_perm:[2,3,0,1] row_mask:0xf bank_mask:0xf bound_ctrl:1
	v_add_f32_dpp v192, v192, v192 quad_perm:[2,3,0,1] row_mask:0xf bank_mask:0xf bound_ctrl:1
	v_mul_f32 v199, v167, v199
	v_add_f32_dpp v188, v188, v188 row_half_mirror row_mask:0xf bank_mask:0xf bound_ctrl:1
	v_add_f32_dpp v192, v192, v192 row_half_mirror row_mask:0xf bank_mask:0xf bound_ctrl:1
	v_fma_f32 v196, v208, v204, v196
	v_add_f32_dpp v188, v188, v188 row_mirror row_mask:0xf bank_mask:0xf bound_ctrl:1
	v_add_f32_dpp v192, v192, v192 row_mirror row_mask:0xf bank_mask:0xf bound_ctrl:1
	v_fma_f32 v197, v208, v205, v197
	v_fma_f32 v198, v208, v206, v198
	v_fma_f32 v199, v208, v207, v199
	v_fma_f32 v159, -v188, v200, v196
	v_fma_f32 v164, -v188, v201, v197
	v_fma_f32 v165, -v188, v202, v198
	v_fma_f32 v167, -v188, v203, v199
	v_fma_f32 v192, -v188, v209, v192
	v_fma_f32 v192, v208, v210, v192
	ds_write_b32 v2, v192 offset:1728
	ds_read_b128 v[188:191], v3 offset:44544
	ds_read_b128 v[192:195], v3 offset:44800
	ds_read_b128 v[196:199], v3 offset:45056
	ds_read_b128 v[204:207], v3 offset:45568
	ds_read_b128 v[208:211], v4 offset:44544
	ds_read_b128 v[200:203], v3 offset:45312
	s_waitcnt lgkmcnt(7)
	v_mul_f32 v160, v159, v160
	v_mul_f32 v168, v159, v168
	v_mul_f32 v161, v164, v161
	v_mul_f32 v169, v164, v169
	v_fma_f32 v160, v165, v162, v160
	v_fma_f32 v168, v165, v170, v168
	v_fma_f32 v161, v167, v163, v161
	v_fma_f32 v169, v167, v171, v169
	v_add_f32 v160, v160, v161
	v_add_f32 v168, v168, v169
	v_mul_f32 v172, v159, v172
	v_mul_f32 v173, v164, v173
	v_add_f32_dpp v160, v160, v160 quad_perm:[1,0,3,2] row_mask:0xf bank_mask:0xf bound_ctrl:1
	v_add_f32_dpp v168, v168, v168 quad_perm:[1,0,3,2] row_mask:0xf bank_mask:0xf bound_ctrl:1
	v_mul_f32 v174, v165, v174
	v_add_f32_dpp v160, v160, v160 quad_perm:[2,3,0,1] row_mask:0xf bank_mask:0xf bound_ctrl:1
	v_add_f32_dpp v168, v168, v168 quad_perm:[2,3,0,1] row_mask:0xf bank_mask:0xf bound_ctrl:1
	v_mul_f32 v175, v167, v175
	v_add_f32_dpp v160, v160, v160 row_half_mirror row_mask:0xf bank_mask:0xf bound_ctrl:1
	v_add_f32_dpp v168, v168, v168 row_half_mirror row_mask:0xf bank_mask:0xf bound_ctrl:1
	v_fma_f32 v172, v184, v180, v172
	v_add_f32_dpp v160, v160, v160 row_mirror row_mask:0xf bank_mask:0xf bound_ctrl:1
	v_add_f32_dpp v168, v168, v168 row_mirror row_mask:0xf bank_mask:0xf bound_ctrl:1
	v_fma_f32 v173, v184, v181, v173
	v_fma_f32 v174, v184, v182, v174
	v_fma_f32 v175, v184, v183, v175
	v_fma_f32 v159, -v160, v176, v172
	v_fma_f32 v164, -v160, v177, v173
	v_fma_f32 v165, -v160, v178, v174
	v_fma_f32 v167, -v160, v179, v175
	v_fma_f32 v168, -v160, v185, v168
	v_fma_f32 v168, v184, v186, v168
	ds_write_b32 v2, v168 offset:1792
	ds_read_b128 v[160:163], v3 offset:46080
	ds_read_b128 v[168:171], v3 offset:46336
	ds_read_b128 v[172:175], v3 offset:46592
	ds_read_b128 v[180:183], v3 offset:47104
	ds_read_b128 v[184:187], v4 offset:46080
	ds_read_b128 v[176:179], v3 offset:46848
	s_waitcnt lgkmcnt(7)
; __device__ __forceinline__ float vfma(float a, float b, float c) { float d; asm("v_fma_f32 %0, %1, %2, %3" : "=v"(d) : "v"(a), "v"(b), "v"(c)); return d; }
; __device__ __forceinline__ float step_compute(float (&S)[4], const StepOp& o) {
;     float d1 = vmul(S[0], o.kk[0]), d2 = vmul(S[0], o.wr[0]), e1 = vmul(S[1], o.kk[1]), e2 = vmul(S[1], o.wr[1]);
;     d1 = vfma(S[2], o.kk[2], d1); d2 = vfma(S[2], o.wr[2], d2); e1 = vfma(S[3], o.kk[3], e1); e2 = vfma(S[3], o.wr[3], e2);
;     d1 = vadd(d1, e1); d2 = vadd(d2, e2);
;     float t0, t1, t2, t3;
;     asm volatile(
;         "v_mul_f32 %[t0], %[s0], %[w0]\n\t"
;         "v_mul_f32 %[t1], %[s1], %[w1]\n\t"
;         "v_add_f32_dpp %[d1], %[d1], %[d1] quad_perm:[1,0,3,2] row_mask:0xf bank_mask:0xf bound_ctrl:1\n\t"
;         "v_add_f32_dpp %[d2], %[d2], %[d2] quad_perm:[1,0,3,2] row_mask:0xf bank_mask:0xf bound_ctrl:1\n\t"
;         "v_mul_f32 %[t2], %[s2], %[w2]\n\t"
;         "v_add_f32_dpp %[d1], %[d1], %[d1] quad_perm:[2,3,0,1] row_mask:0xf bank_mask:0xf bound_ctrl:1\n\t"
;         "v_add_f32_dpp %[d2], %[d2], %[d2] quad_perm:[2,3,0,1] row_mask:0xf bank_mask:0xf bound_ctrl:1\n\t"
;         "v_mul_f32 %[t3], %[s3], %[w3]\n\t"
;         "v_add_f32_dpp %[d1], %[d1], %[d1] row_half_mirror row_mask:0xf bank_mask:0xf bound_ctrl:1\n\t"
;         "v_add_f32_dpp %[d2], %[d2], %[d2] row_half_mirror row_mask:0xf bank_mask:0xf bound_ctrl:1\n\t"
;         "v_fma_f32 %[t0], %[v], %[k0], %[t0]\n\t"
;         "v_add_f32_dpp %[d1], %[d1], %[d1] row_mirror row_mask:0xf bank_mask:0xf bound_ctrl:1\n\t"
;         "v_add_f32_dpp %[d2], %[d2], %[d2] row_mirror row_mask:0xf bank_mask:0xf bound_ctrl:1\n\t"
;         "v_fma_f32 %[t1], %[v], %[k1], %[t1]\n\t"
;         "v_fma_f32 %[t2], %[v], %[k2], %[t2]\n\t"
;         "v_fma_f32 %[t3], %[v], %[k3], %[t3]"
;         : [t0] "=&v"(t0), [t1] "=&v"(t1), [t2] "=&v"(t2), [t3] "=&v"(t3), [d1] "+v"(d1), [d2] "+v"(d2)
;         : [s0] "v"(S[0]), [s1] "v"(S[1]), [s2] "v"(S[2]), [s3] "v"(S[3]), [w0] "v"(o.w[0]), [w1] "v"(o.w[1]), [w2] "v"(o.w[2]), [w3] "v"(o.w[3]),
;           [k0] "v"(o.k[0]), [k1] "v"(o.k[1]), [k2] "v"(o.k[2]), [k3] "v"(o.k[3]), [v] "v"(o.q[0]));
;     S[0] = vnfma(d1, o.b[0], t0); S[1] = vnfma(d1, o.b[1], t1); S[2] = vnfma(d1, o.b[2], t2); S[3] = vnfma(d1, o.b[3], t3);
;     return vfma(o.q[0], o.q[2], vnfma(d1, o.q[1], d2));
; }
	v_mul_f32 v188, v159, v188
	v_mul_f32 v192, v159, v192
	v_mul_f32 v189, v164, v189
	v_mul_f32 v193, v164, v193
	v_fma_f32 v188, v165, v190, v188
	v_fma_f32 v192, v165, v194, v192
	v_fma_f32 v189, v167, v191, v189
	v_fma_f32 v193, v167, v195, v193
	v_add_f32 v188, v188, v189
	v_add_f32 v192, v192, v193
	v_mul_f32 v196, v159, v196
	v_mul_f32 v197, v164, v197
	v_add_f32_dpp v188, v188, v188 quad_perm:[1,0,3,2] row_mask:0xf bank_mask:0xf bound_ctrl:1
	v_add_f32_dpp v192, v192, v192 quad_perm:[1,0,3,2] row_mask:0xf bank_mask:0xf bound_ctrl:1
	v_mul_f32 v198, v165, v198
	v_add_f32_dpp v188, v188, v188 quad_perm:[2,3,0,1] row_mask:0xf bank_mask:0xf bound_ctrl:1
	v_add_f32_dpp v192, v192, v192 quad_perm:[2,3,0,1] row_mask:0xf bank_mask:0xf bound_ctrl:1
	v_mul_f32 v199, v167, v199
	v_add_f32_dpp v188, v188, v188 row_half_mirror row_mask:0xf bank_mask:0xf bound_ctrl:1
	v_add_f32_dpp v192, v192, v192 row_half_mirror row_mask:0xf bank_mask:0xf bound_ctrl:1
	v_fma_f32 v196, v208, v204, v196
	v_add_f32_dpp v188, v188, v188 row_mirror row_mask:0xf bank_mask:0xf bound_ctrl:1
	v_add_f32_dpp v192, v192, v192 row_mirror row_mask:0xf bank_mask:0xf bound_ctrl:1
	v_fma_f32 v197, v208, v205, v197
	v_fma_f32 v198, v208, v206, v198
	v_fma_f32 v199, v208, v207, v199
	v_fma_f32 v159, -v188, v200, v196
	v_fma_f32 v164, -v188, v201, v197
	v_fma_f32 v165, -v188, v202, v198
	v_fma_f32 v167, -v188, v203, v199
	v_fma_f32 v192, -v188, v209, v192
	v_fma_f32 v192, v208, v210, v192
	ds_write_b32 v2, v192 offset:1856
	ds_read_b128 v[188:191], v3 offset:47616
	ds_read_b128 v[192:195], v3 offset:47872
	ds_read_b128 v[196:199], v3 offset:48128
	ds_read_b128 v[204:207], v3 offset:48640
	ds_read_b128 v[208:211], v4 offset:47616
	ds_read_b128 v[200:203], v3 offset:48384
	s_waitcnt lgkmcnt(7)
	v_mul_f32 v160, v159, v160
	v_mul_f32 v168, v159, v168
	v_mul_f32 v161, v164, v161
	v_mul_f32 v169, v164, v169
	v_fma_f32 v160, v165, v162, v160
	v_fma_f32 v168, v165, v170, v168
	v_fma_f32 v161, v167, v163, v161
	v_fma_f32 v169, v167, v171, v169
	v_add_f32 v160, v160, v161
	v_add_f32 v168, v168, v169
	v_mul_f32 v172, v159, v172
	v_mul_f32 v173, v164, v173
	v_add_f32_dpp v160, v160, v160 quad_perm:[1,0,3,2] row_mask:0xf bank_mask:0xf bound_ctrl:1
	v_add_f32_dpp v168, v168, v168 quad_perm:[1,0,3,2] row_mask:0xf bank_mask:0xf bound_ctrl:1
	v_mul_f32 v174, v165, v174
	v_add_f32_dpp v160, v160, v160 quad_perm:[2,3,0,1] row_mask:0xf bank_mask:0xf bound_ctrl:1
	v_add_f32_dpp v168, v168, v168 quad_perm:[2,3,0,1] row_mask:0xf bank_mask:0xf bound_ctrl:1
	v_mul_f32 v175, v167, v175
	v_add_f32_dpp v160, v160, v160 row_half_mirror row_mask:0xf bank_mask:0xf bound_ctrl:1
	v_add_f32_dpp v168, v168, v168 row_half_mirror row_mask:0xf bank_mask:0xf bound_ctrl:1
	v_fma_f32 v172, v184, v180, v172
	v_add_f32_dpp v160, v160, v160 row_mirror row_mask:0xf bank_mask:0xf bound_ctrl:1
	v_add_f32_dpp v168, v168, v168 row_mirror row_mask:0xf bank_mask:0xf bound_ctrl:1
	v_fma_f32 v173, v184, v181, v173
	v_fma_f32 v174, v184, v182, v174
	v_fma_f32 v175, v184, v183, v175
	v_fma_f32 v159, -v160, v176, v172
	v_fma_f32 v164, -v160, v177, v173
	v_fma_f32 v165, -v160, v178, v174
	v_fma_f32 v167, -v160, v179, v175
	v_fma_f32 v168, -v160, v185, v168
	v_fma_f32 v168, v184, v186, v168
	ds_write_b32 v2, v168 offset:1920
	s_waitcnt lgkmcnt(1)
	v_mul_f32 v188, v159, v188
	v_mul_f32 v192, v159, v192
	v_mul_f32 v189, v164, v189
	v_mul_f32 v193, v164, v193
	v_fma_f32 v188, v165, v190, v188
	v_fma_f32 v192, v165, v194, v192
	v_fma_f32 v189, v167, v191, v189
	v_fma_f32 v193, v167, v195, v193
	v_add_f32 v188, v188, v189
	v_add_f32 v192, v192, v193
	v_mul_f32 v196, v159, v196
	v_mul_f32 v197, v164, v197
	v_add_f32_dpp v188, v188, v188 quad_perm:[1,0,3,2] row_mask:0xf bank_mask:0xf bound_ctrl:1
	v_add_f32_dpp v192, v192, v192 quad_perm:[1,0,3,2] row_mask:0xf bank_mask:0xf bound_ctrl:1
	v_mul_f32 v198, v165, v198
	v_add_f32_dpp v188, v188, v188 quad_perm:[2,3,0,1] row_mask:0xf bank_mask:0xf bound_ctrl:1
	v_add_f32_dpp v192, v192, v192 quad_perm:[2,3,0,1] row_mask:0xf bank_mask:0xf bound_ctrl:1
	v_mul_f32 v199, v167, v199
	v_add_f32_dpp v188, v188, v188 row_half_mirror row_mask:0xf bank_mask:0xf bound_ctrl:1
	v_add_f32_dpp v192, v192, v192 row_half_mirror row_mask:0xf bank_mask:0xf bound_ctrl:1
	v_fma_f32 v196, v208, v204, v196
	v_add_f32_dpp v188, v188, v188 row_mirror row_mask:0xf bank_mask:0xf bound_ctrl:1
	v_add_f32_dpp v192, v192, v192 row_mirror row_mask:0xf bank_mask:0xf bound_ctrl:1
	v_fma_f32 v197, v208, v205, v197
	v_fma_f32 v198, v208, v206, v198
	v_fma_f32 v199, v208, v207, v199
	v_fma_f32 v3, -v188, v200, v196
	v_fma_f32 v4, -v188, v201, v197
	v_fma_f32 v115, -v188, v202, v198
	v_fma_f32 v129, -v188, v203, v199
	v_fma_f32 v192, -v188, v209, v192
	v_fma_f32 v192, v208, v210, v192
	ds_write_b32 v2, v192 offset:1984

; __device__ __forceinline__ float vfma(float a, float b, float c) { float d; asm("v_fma_f32 %0, %1, %2, %3" : "=v"(d) : "v"(a), "v"(b), "v"(c)); return d; }
; __device__ __forceinline__ float step_compute(float (&S)[4], const StepOp& o) {
;     float d1 = vmul(S[0], o.kk[0]), d2 = vmul(S[0], o.wr[0]), e1 = vmul(S[1], o.kk[1]), e2 = vmul(S[1], o.wr[1]);
;     d1 = vfma(S[2], o.kk[2], d1); d2 = vfma(S[2], o.wr[2], d2); e1 = vfma(S[3], o.kk[3], e1); e2 = vfma(S[3], o.wr[3], e2);
;     d1 = vadd(d1, e1); d2 = vadd(d2, e2);
;     float t0, t1, t2, t3;
;     asm volatile(
;         "v_mul_f32 %[t0], %[s0], %[w0]\n\t"
;         "v_mul_f32 %[t1], %[s1], %[w1]\n\t"
;         "v_add_f32_dpp %[d1], %[d1], %[d1] quad_perm:[1,0,3,2] row_mask:0xf bank_mask:0xf bound_ctrl:1\n\t"
;         "v_add_f32_dpp %[d2], %[d2], %[d2] quad_perm:[1,0,3,2] row_mask:0xf bank_mask:0xf bound_ctrl:1\n\t"
;         "v_mul_f32 %[t2], %[s2], %[w2]\n\t"
;         "v_add_f32_dpp %[d1], %[d1], %[d1] quad_perm:[2,3,0,1] row_mask:0xf bank_mask:0xf bound_ctrl:1\n\t"
;         "v_add_f32_dpp %[d2], %[d2], %[d2] quad_perm:[2,3,0,1] row_mask:0xf bank_mask:0xf bound_ctrl:1\n\t"
;         "v_mul_f32 %[t3], %[s3], %[w3]\n\t"
;         "v_add_f32_dpp %[d1], %[d1], %[d1] row_half_mirror row_mask:0xf bank_mask:0xf bound_ctrl:1\n\t"
;         "v_add_f32_dpp %[d2], %[d2], %[d2] row_half_mirror row_mask:0xf bank_mask:0xf bound_ctrl:1\n\t"
;         "v_fma_f32 %[t0], %[v], %[k0], %[t0]\n\t"
;         "v_add_f32_dpp %[d1], %[d1], %[d1] row_mirror row_mask:0xf bank_mask:0xf bound_ctrl:1\n\t"
;         "v_add_f32_dpp %[d2], %[d2], %[d2] row_mirror row_mask:0xf bank_mask:0xf bound_ctrl:1\n\t"
;         "v_fma_f32 %[t1], %[v], %[k1], %[t1]\n\t"
;         "v_fma_f32 %[t2], %[v], %[k2], %[t2]\n\t"
;         "v_fma_f32 %[t3], %[v], %[k3], %[t3]"
;         : [t0] "=&v"(t0), [t1] "=&v"(t1), [t2] "=&v"(t2), [t3] "=&v"(t3), [d1] "+v"(d1), [d2] "+v"(d2)
;         : [s0] "v"(S[0]), [s1] "v"(S[1]), [s2] "v"(S[2]), [s3] "v"(S[3]), [w0] "v"(o.w[0]), [w1] "v"(o.w[1]), [w2] "v"(o.w[2]), [w3] "v"(o.w[3]),
;           [k0] "v"(o.k[0]), [k1] "v"(o.k[1]), [k2] "v"(o.k[2]), [k3] "v"(o.k[3]), [v] "v"(o.q[0]));
;     S[0] = vnfma(d1, o.b[0], t0); S[1] = vnfma(d1, o.b[1], t1); S[2] = vnfma(d1, o.b[2], t2); S[3] = vnfma(d1, o.b[3], t3);
;     return vfma(o.q[0], o.q[2], vnfma(d1, o.q[1], d2));
; }
.LBB0_818:
	s_and_b32 s43, s18, 1
	s_cmp_eq_u32 s43, 0
	s_cselect_b64 s[30:31], -1, 0
	s_and_b64 vcc, exec, s[6:7]
	s_mov_b64 s[76:77], -1
	s_cbranch_vccnz .LBB0_820
	s_and_b64 s[76:77], s[30:31], exec
	s_cselect_b32 s76, 0, s91
	v_lshl_add_u32 v2, s43, 11, v148
	v_add_u32_e32 v3, s76, v149
	s_cselect_b32 s43, s93, s92
	v_add_u32_e32 v4, s43, v150
	ds_read_b128 v[160:163], v3 offset:0
	ds_read_b128 v[168:171], v3 offset:256
	ds_read_b128 v[172:175], v3 offset:512
	ds_read_b128 v[180:183], v3 offset:1024
	ds_read_b128 v[184:187], v4
	ds_read_b128 v[176:179], v3 offset:768
	s_mov_b64 s[76:77], 0
	ds_read_b128 v[188:191], v3 offset:1536
	ds_read_b128 v[192:195], v3 offset:1792
	ds_read_b128 v[196:199], v3 offset:2048
	ds_read_b128 v[204:207], v3 offset:2560
	ds_read_b128 v[208:211], v4 offset:1536
	ds_read_b128 v[200:203], v3 offset:2304
	s_waitcnt lgkmcnt(6)
	v_mul_f32 v160, v78, v160
	v_mul_f32 v168, v78, v168
	v_mul_f32 v161, v79, v161
	v_mul_f32 v169, v79, v169
	v_fma_f32 v160, v80, v162, v160
	v_fma_f32 v168, v80, v170, v168
	v_fma_f32 v161, v81, v163, v161
	v_fma_f32 v169, v81, v171, v169
	v_add_f32 v160, v160, v161
	v_add_f32 v168, v168, v169
	v_mul_f32 v172, v78, v172
	v_mul_f32 v173, v79, v173
	v_add_f32_dpp v160, v160, v160 quad_perm:[1,0,3,2] row_mask:0xf bank_mask:0xf bound_ctrl:1
	v_add_f32_dpp v168, v168, v168 quad_perm:[1,0,3,2] row_mask:0xf bank_mask:0xf bound_ctrl:1
	v_mul_f32 v174, v80, v174
	v_add_f32_dpp v160, v160, v160 quad_perm:[2,3,0,1] row_mask:0xf bank_mask:0xf bound_ctrl:1
	v_add_f32_dpp v168, v168, v168 quad_perm:[2,3,0,1] row_mask:0xf bank_mask:0xf bound_ctrl:1
	v_mul_f32 v175, v81, v175
	v_add_f32_dpp v160, v160, v160 row_half_mirror row_mask:0xf bank_mask:0xf bound_ctrl:1
	v_add_f32_dpp v168, v168, v168 row_half_mirror row_mask:0xf bank_mask:0xf bound_ctrl:1
	v_fma_f32 v172, v184, v180, v172
	v_add_f32_dpp v160, v160, v160 row_mirror row_mask:0xf bank_mask:0xf bound_ctrl:1
	v_add_f32_dpp v168, v168, v168 row_mirror row_mask:0xf bank_mask:0xf bound_ctrl:1
	v_fma_f32 v173, v184, v181, v173
	v_fma_f32 v174, v184, v182, v174
	v_fma_f32 v175, v184, v183, v175
	v_fma_f32 v159, -v160, v176, v172
	v_fma_f32 v164, -v160, v177, v173
	v_fma_f32 v165, -v160, v178, v174
	v_fma_f32 v167, -v160, v179, v175
	v_fma_f32 v168, -v160, v185, v168
	v_fma_f32 v168, v184, v186, v168
	ds_write_b32 v2, v168
	ds_read_b128 v[160:163], v3 offset:3072
	ds_read_b128 v[168:171], v3 offset:3328
	ds_read_b128 v[172:175], v3 offset:3584
	ds_read_b128 v[180:183], v3 offset:4096
	ds_read_b128 v[184:187], v4 offset:3072
	ds_read_b128 v[176:179], v3 offset:3840
	s_waitcnt lgkmcnt(7)
	v_mul_f32 v188, v159, v188
	v_mul_f32 v192, v159, v192
	v_mul_f32 v189, v164, v189
	v_mul_f32 v193, v164, v193
	v_fma_f32 v188, v165, v190, v188
	v_fma_f32 v192, v165, v194, v192
	v_fma_f32 v189, v167, v191, v189
	v_fma_f32 v193, v167, v195, v193
	v_add_f32 v188, v188, v189
	v_add_f32 v192, v192, v193
	v_mul_f32 v196, v159, v196
	v_mul_f32 v197, v164, v197
	v_add_f32_dpp v188, v188, v188 quad_perm:[1,0,3,2] row_mask:0xf bank_mask:0xf bound_ctrl:1
	v_add_f32_dpp v192, v192, v192 quad_perm:[1,0,3,2] row_mask:0xf bank_mask:0xf bound_ctrl:1
	v_mul_f32 v198, v165, v198
	v_add_f32_dpp v188, v188, v188 quad_perm:[2,3,0,1] row_mask:0xf bank_mask:0xf bound_ctrl:1
	v_add_f32_dpp v192, v192, v192 quad_perm:[2,3,0,1] row_mask:0xf bank_mask:0xf bound_ctrl:1
	v_mul_f32 v199, v167, v199
	v_add_f32_dpp v188, v188, v188 row_half_mirror row_mask:0xf bank_mask:0xf bound_ctrl:1
	v_add_f32_dpp v192, v192, v192 row_half_mirror row_mask:0xf bank_mask:0xf bound_ctrl:1
	v_fma_f32 v196, v208, v204, v196
	v_add_f32_dpp v188, v188, v188 row_mirror row_mask:0xf bank_mask:0xf bound_ctrl:1
	v_add_f32_dpp v192, v192, v192 row_mirror row_mask:0xf bank_mask:0xf bound_ctrl:1
	v_fma_f32 v197, v208, v205, v197
	v_fma_f32 v198, v208, v206, v198
	v_fma_f32 v199, v208, v207, v199
	v_fma_f32 v159, -v188, v200, v196
	v_fma_f32 v164, -v188, v201, v197
	v_fma_f32 v165, -v188, v202, v198
	v_fma_f32 v167, -v188, v203, v199
	v_fma_f32 v192, -v188, v209, v192
	v_fma_f32 v192, v208, v210, v192
	ds_write_b32 v2, v192 offset:64
	ds_read_b128 v[188:191], v3 offset:4608
	ds_read_b128 v[192:195], v3 offset:4864
	ds_read_b128 v[196:199], v3 offset:5120
	ds_read_b128 v[204:207], v3 offset:5632
	ds_read_b128 v[208:211], v4 offset:4608
	ds_read_b128 v[200:203], v3 offset:5376
	s_waitcnt lgkmcnt(7)
	v_mul_f32 v160, v159, v160
	v_mul_f32 v168, v159, v168
	v_mul_f32 v161, v164, v161
	v_mul_f32 v169, v164, v169
	v_fma_f32 v160, v165, v162, v160
	v_fma_f32 v168, v165, v170, v168
	v_fma_f32 v161, v167, v163, v161
	v_fma_f32 v169, v167, v171, v169
	v_add_f32 v160, v160, v161
	v_add_f32 v168, v168, v169
	v_mul_f32 v172, v159, v172
	v_mul_f32 v173, v164, v173
	v_add_f32_dpp v160, v160, v160 quad_perm:[1,0,3,2] row_mask:0xf bank_mask:0xf bound_ctrl:1
	v_add_f32_dpp v168, v168, v168 quad_perm:[1,0,3,2] row_mask:0xf bank_mask:0xf bound_ctrl:1
	v_mul_f32 v174, v165, v174
	v_add_f32_dpp v160, v160, v160 quad_perm:[2,3,0,1] row_mask:0xf bank_mask:0xf bound_ctrl:1
	v_add_f32_dpp v168, v168, v168 quad_perm:[2,3,0,1] row_mask:0xf bank_mask:0xf bound_ctrl:1
	v_mul_f32 v175, v167, v175
	v_add_f32_dpp v160, v160, v160 row_half_mirror row_mask:0xf bank_mask:0xf bound_ctrl:1
	v_add_f32_dpp v168, v168, v168 row_half_mirror row_mask:0xf bank_mask:0xf bound_ctrl:1
	v_fma_f32 v172, v184, v180, v172
	v_add_f32_dpp v160, v160, v160 row_mirror row_mask:0xf bank_mask:0xf bound_ctrl:1
	v_add_f32_dpp v168, v168, v168 row_mirror row_mask:0xf bank_mask:0xf bound_ctrl:1
	v_fma_f32 v173, v184, v181, v173
	v_fma_f32 v174, v184, v182, v174
	v_fma_f32 v175, v184, v183, v175
	v_fma_f32 v159, -v160, v176, v172
	v_fma_f32 v164, -v160, v177, v173
	v_fma_f32 v165, -v160, v178, v174
	v_fma_f32 v167, -v160, v179, v175
	v_fma_f32 v168, -v160, v185, v168
	v_fma_f32 v168, v184, v186, v168
	ds_write_b32 v2, v168 offset:128
	ds_read_b128 v[160:163], v3 offset:6144
	ds_read_b128 v[168:171], v3 offset:6400
	ds_read_b128 v[172:175], v3 offset:6656
	ds_read_b128 v[180:183], v3 offset:7168
	ds_read_b128 v[184:187], v4 offset:6144
	ds_read_b128 v[176:179], v3 offset:6912
	s_waitcnt lgkmcnt(7)
; __device__ __forceinline__ float vfma(float a, float b, float c) { float d; asm("v_fma_f32 %0, %1, %2, %3" : "=v"(d) : "v"(a), "v"(b), "v"(c)); return d; }
; __device__ __forceinline__ float step_compute(float (&S)[4], const StepOp& o) {
;     float d1 = vmul(S[0], o.kk[0]), d2 = vmul(S[0], o.wr[0]), e1 = vmul(S[1], o.kk[1]), e2 = vmul(S[1], o.wr[1]);
;     d1 = vfma(S[2], o.kk[2], d1); d2 = vfma(S[2], o.wr[2], d2); e1 = vfma(S[3], o.kk[3], e1); e2 = vfma(S[3], o.wr[3], e2);
;     d1 = vadd(d1, e1); d2 = vadd(d2, e2);
;     float t0, t1, t2, t3;
;     asm volatile(
;         "v_mul_f32 %[t0], %[s0], %[w0]\n\t"
;         "v_mul_f32 %[t1], %[s1], %[w1]\n\t"
;         "v_add_f32_dpp %[d1], %[d1], %[d1] quad_perm:[1,0,3,2] row_mask:0xf bank_mask:0xf bound_ctrl:1\n\t"
;         "v_add_f32_dpp %[d2], %[d2], %[d2] quad_perm:[1,0,3,2] row_mask:0xf bank_mask:0xf bound_ctrl:1\n\t"
;         "v_mul_f32 %[t2], %[s2], %[w2]\n\t"
;         "v_add_f32_dpp %[d1], %[d1], %[d1] quad_perm:[2,3,0,1] row_mask:0xf bank_mask:0xf bound_ctrl:1\n\t"
;         "v_add_f32_dpp %[d2], %[d2], %[d2] quad_perm:[2,3,0,1] row_mask:0xf bank_mask:0xf bound_ctrl:1\n\t"
;         "v_mul_f32 %[t3], %[s3], %[w3]\n\t"
;         "v_add_f32_dpp %[d1], %[d1], %[d1] row_half_mirror row_mask:0xf bank_mask:0xf bound_ctrl:1\n\t"
;         "v_add_f32_dpp %[d2], %[d2], %[d2] row_half_mirror row_mask:0xf bank_mask:0xf bound_ctrl:1\n\t"
;         "v_fma_f32 %[t0], %[v], %[k0], %[t0]\n\t"
;         "v_add_f32_dpp %[d1], %[d1], %[d1] row_mirror row_mask:0xf bank_mask:0xf bound_ctrl:1\n\t"
;         "v_add_f32_dpp %[d2], %[d2], %[d2] row_mirror row_mask:0xf bank_mask:0xf bound_ctrl:1\n\t"
;         "v_fma_f32 %[t1], %[v], %[k1], %[t1]\n\t"
;         "v_fma_f32 %[t2], %[v], %[k2], %[t2]\n\t"
;         "v_fma_f32 %[t3], %[v], %[k3], %[t3]"
;         : [t0] "=&v"(t0), [t1] "=&v"(t1), [t2] "=&v"(t2), [t3] "=&v"(t3), [d1] "+v"(d1), [d2] "+v"(d2)
;         : [s0] "v"(S[0]), [s1] "v"(S[1]), [s2] "v"(S[2]), [s3] "v"(S[3]), [w0] "v"(o.w[0]), [w1] "v"(o.w[1]), [w2] "v"(o.w[2]), [w3] "v"(o.w[3]),
;           [k0] "v"(o.k[0]), [k1] "v"(o.k[1]), [k2] "v"(o.k[2]), [k3] "v"(o.k[3]), [v] "v"(o.q[0]));
;     S[0] = vnfma(d1, o.b[0], t0); S[1] = vnfma(d1, o.b[1], t1); S[2] = vnfma(d1, o.b[2], t2); S[3] = vnfma(d1, o.b[3], t3);
;     return vfma(o.q[0], o.q[2], vnfma(d1, o.q[1], d2));
; }
	v_mul_f32 v188, v159, v188
	v_mul_f32 v192, v159, v192
	v_mul_f32 v189, v164, v189
	v_mul_f32 v193, v164, v193
	v_fma_f32 v188, v165, v190, v188
	v_fma_f32 v192, v165, v194, v192
	v_fma_f32 v189, v167, v191, v189
	v_fma_f32 v193, v167, v195, v193
	v_add_f32 v188, v188, v189
	v_add_f32 v192, v192, v193
	v_mul_f32 v196, v159, v196
	v_mul_f32 v197, v164, v197
	v_add_f32_dpp v188, v188, v188 quad_perm:[1,0,3,2] row_mask:0xf bank_mask:0xf bound_ctrl:1
	v_add_f32_dpp v192, v192, v192 quad_perm:[1,0,3,2] row_mask:0xf bank_mask:0xf bound_ctrl:1
	v_mul_f32 v198, v165, v198
	v_add_f32_dpp v188, v188, v188 quad_perm:[2,3,0,1] row_mask:0xf bank_mask:0xf bound_ctrl:1
	v_add_f32_dpp v192, v192, v192 quad_perm:[2,3,0,1] row_mask:0xf bank_mask:0xf bound_ctrl:1
	v_mul_f32 v199, v167, v199
	v_add_f32_dpp v188, v188, v188 row_half_mirror row_mask:0xf bank_mask:0xf bound_ctrl:1
	v_add_f32_dpp v192, v192, v192 row_half_mirror row_mask:0xf bank_mask:0xf bound_ctrl:1
	v_fma_f32 v196, v208, v204, v196
	v_add_f32_dpp v188, v188, v188 row_mirror row_mask:0xf bank_mask:0xf bound_ctrl:1
	v_add_f32_dpp v192, v192, v192 row_mirror row_mask:0xf bank_mask:0xf bound_ctrl:1
	v_fma_f32 v197, v208, v205, v197
	v_fma_f32 v198, v208, v206, v198
	v_fma_f32 v199, v208, v207, v199
	v_fma_f32 v159, -v188, v200, v196
	v_fma_f32 v164, -v188, v201, v197
	v_fma_f32 v165, -v188, v202, v198
	v_fma_f32 v167, -v188, v203, v199
	v_fma_f32 v192, -v188, v209, v192
	v_fma_f32 v192, v208, v210, v192
	ds_write_b32 v2, v192 offset:192
	ds_read_b128 v[188:191], v3 offset:7680
	ds_read_b128 v[192:195], v3 offset:7936
	ds_read_b128 v[196:199], v3 offset:8192
	ds_read_b128 v[204:207], v3 offset:8704
	ds_read_b128 v[208:211], v4 offset:7680
	ds_read_b128 v[200:203], v3 offset:8448
	s_waitcnt lgkmcnt(7)
	v_mul_f32 v160, v159, v160
	v_mul_f32 v168, v159, v168
	v_mul_f32 v161, v164, v161
	v_mul_f32 v169, v164, v169
	v_fma_f32 v160, v165, v162, v160
	v_fma_f32 v168, v165, v170, v168
	v_fma_f32 v161, v167, v163, v161
	v_fma_f32 v169, v167, v171, v169
	v_add_f32 v160, v160, v161
	v_add_f32 v168, v168, v169
	v_mul_f32 v172, v159, v172
	v_mul_f32 v173, v164, v173
	v_add_f32_dpp v160, v160, v160 quad_perm:[1,0,3,2] row_mask:0xf bank_mask:0xf bound_ctrl:1
	v_add_f32_dpp v168, v168, v168 quad_perm:[1,0,3,2] row_mask:0xf bank_mask:0xf bound_ctrl:1
	v_mul_f32 v174, v165, v174
	v_add_f32_dpp v160, v160, v160 quad_perm:[2,3,0,1] row_mask:0xf bank_mask:0xf bound_ctrl:1
	v_add_f32_dpp v168, v168, v168 quad_perm:[2,3,0,1] row_mask:0xf bank_mask:0xf bound_ctrl:1
	v_mul_f32 v175, v167, v175
	v_add_f32_dpp v160, v160, v160 row_half_mirror row_mask:0xf bank_mask:0xf bound_ctrl:1
	v_add_f32_dpp v168, v168, v168 row_half_mirror row_mask:0xf bank_mask:0xf bound_ctrl:1
	v_fma_f32 v172, v184, v180, v172
	v_add_f32_dpp v160, v160, v160 row_mirror row_mask:0xf bank_mask:0xf bound_ctrl:1
	v_add_f32_dpp v168, v168, v168 row_mirror row_mask:0xf bank_mask:0xf bound_ctrl:1
	v_fma_f32 v173, v184, v181, v173
	v_fma_f32 v174, v184, v182, v174
	v_fma_f32 v175, v184, v183, v175
	v_fma_f32 v159, -v160, v176, v172
	v_fma_f32 v164, -v160, v177, v173
	v_fma_f32 v165, -v160, v178, v174
	v_fma_f32 v167, -v160, v179, v175
	v_fma_f32 v168, -v160, v185, v168
	v_fma_f32 v168, v184, v186, v168
	ds_write_b32 v2, v168 offset:256
	ds_read_b128 v[160:163], v3 offset:9216
	ds_read_b128 v[168:171], v3 offset:9472
	ds_read_b128 v[172:175], v3 offset:9728
	ds_read_b128 v[180:183], v3 offset:10240
	ds_read_b128 v[184:187], v4 offset:9216
	ds_read_b128 v[176:179], v3 offset:9984
	s_waitcnt lgkmcnt(7)
	v_mul_f32 v188, v159, v188
	v_mul_f32 v192, v159, v192
	v_mul_f32 v189, v164, v189
	v_mul_f32 v193, v164, v193
	v_fma_f32 v188, v165, v190, v188
	v_fma_f32 v192, v165, v194, v192
	v_fma_f32 v189, v167, v191, v189
	v_fma_f32 v193, v167, v195, v193
	v_add_f32 v188, v188, v189
	v_add_f32 v192, v192, v193
	v_mul_f32 v196, v159, v196
	v_mul_f32 v197, v164, v197
	v_add_f32_dpp v188, v188, v188 quad_perm:[1,0,3,2] row_mask:0xf bank_mask:0xf bound_ctrl:1
	v_add_f32_dpp v192, v192, v192 quad_perm:[1,0,3,2] row_mask:0xf bank_mask:0xf bound_ctrl:1
	v_mul_f32 v198, v165, v198
	v_add_f32_dpp v188, v188, v188 quad_perm:[2,3,0,1] row_mask:0xf bank_mask:0xf bound_ctrl:1
	v_add_f32_dpp v192, v192, v192 quad_perm:[2,3,0,1] row_mask:0xf bank_mask:0xf bound_ctrl:1
	v_mul_f32 v199, v167, v199
	v_add_f32_dpp v188, v188, v188 row_half_mirror row_mask:0xf bank_mask:0xf bound_ctrl:1
	v_add_f32_dpp v192, v192, v192 row_half_mirror row_mask:0xf bank_mask:0xf bound_ctrl:1
	v_fma_f32 v196, v208, v204, v196
	v_add_f32_dpp v188, v188, v188 row_mirror row_mask:0xf bank_mask:0xf bound_ctrl:1
	v_add_f32_dpp v192, v192, v192 row_mirror row_mask:0xf bank_mask:0xf bound_ctrl:1
	v_fma_f32 v197, v208, v205, v197
	v_fma_f32 v198, v208, v206, v198
	v_fma_f32 v199, v208, v207, v199
	v_fma_f32 v159, -v188, v200, v196
	v_fma_f32 v164, -v188, v201, v197
	v_fma_f32 v165, -v188, v202, v198
	v_fma_f32 v167, -v188, v203, v199
	v_fma_f32 v192, -v188, v209, v192
	v_fma_f32 v192, v208, v210, v192
	ds_write_b32 v2, v192 offset:320
	ds_read_b128 v[188:191], v3 offset:10752
	ds_read_b128 v[192:195], v3 offset:11008
	ds_read_b128 v[196:199], v3 offset:11264
	ds_read_b128 v[204:207], v3 offset:11776
	ds_read_b128 v[208:211], v4 offset:10752
	ds_read_b128 v[200:203], v3 offset:11520
	s_waitcnt lgkmcnt(7)
; __device__ __forceinline__ float vfma(float a, float b, float c) { float d; asm("v_fma_f32 %0, %1, %2, %3" : "=v"(d) : "v"(a), "v"(b), "v"(c)); return d; }
; __device__ __forceinline__ float step_compute(float (&S)[4], const StepOp& o) {
;     float d1 = vmul(S[0], o.kk[0]), d2 = vmul(S[0], o.wr[0]), e1 = vmul(S[1], o.kk[1]), e2 = vmul(S[1], o.wr[1]);
;     d1 = vfma(S[2], o.kk[2], d1); d2 = vfma(S[2], o.wr[2], d2); e1 = vfma(S[3], o.kk[3], e1); e2 = vfma(S[3], o.wr[3], e2);
;     d1 = vadd(d1, e1); d2 = vadd(d2, e2);
;     float t0, t1, t2, t3;
;     asm volatile(
;         "v_mul_f32 %[t0], %[s0], %[w0]\n\t"
;         "v_mul_f32 %[t1], %[s1], %[w1]\n\t"
;         "v_add_f32_dpp %[d1], %[d1], %[d1] quad_perm:[1,0,3,2] row_mask:0xf bank_mask:0xf bound_ctrl:1\n\t"
;         "v_add_f32_dpp %[d2], %[d2], %[d2] quad_perm:[1,0,3,2] row_mask:0xf bank_mask:0xf bound_ctrl:1\n\t"
;         "v_mul_f32 %[t2], %[s2], %[w2]\n\t"
;         "v_add_f32_dpp %[d1], %[d1], %[d1] quad_perm:[2,3,0,1] row_mask:0xf bank_mask:0xf bound_ctrl:1\n\t"
;         "v_add_f32_dpp %[d2], %[d2], %[d2] quad_perm:[2,3,0,1] row_mask:0xf bank_mask:0xf bound_ctrl:1\n\t"
;         "v_mul_f32 %[t3], %[s3], %[w3]\n\t"
;         "v_add_f32_dpp %[d1], %[d1], %[d1] row_half_mirror row_mask:0xf bank_mask:0xf bound_ctrl:1\n\t"
;         "v_add_f32_dpp %[d2], %[d2], %[d2] row_half_mirror row_mask:0xf bank_mask:0xf bound_ctrl:1\n\t"
;         "v_fma_f32 %[t0], %[v], %[k0], %[t0]\n\t"
;         "v_add_f32_dpp %[d1], %[d1], %[d1] row_mirror row_mask:0xf bank_mask:0xf bound_ctrl:1\n\t"
;         "v_add_f32_dpp %[d2], %[d2], %[d2] row_mirror row_mask:0xf bank_mask:0xf bound_ctrl:1\n\t"
;         "v_fma_f32 %[t1], %[v], %[k1], %[t1]\n\t"
;         "v_fma_f32 %[t2], %[v], %[k2], %[t2]\n\t"
;         "v_fma_f32 %[t3], %[v], %[k3], %[t3]"
;         : [t0] "=&v"(t0), [t1] "=&v"(t1), [t2] "=&v"(t2), [t3] "=&v"(t3), [d1] "+v"(d1), [d2] "+v"(d2)
;         : [s0] "v"(S[0]), [s1] "v"(S[1]), [s2] "v"(S[2]), [s3] "v"(S[3]), [w0] "v"(o.w[0]), [w1] "v"(o.w[1]), [w2] "v"(o.w[2]), [w3] "v"(o.w[3]),
;           [k0] "v"(o.k[0]), [k1] "v"(o.k[1]), [k2] "v"(o.k[2]), [k3] "v"(o.k[3]), [v] "v"(o.q[0]));
;     S[0] = vnfma(d1, o.b[0], t0); S[1] = vnfma(d1, o.b[1], t1); S[2] = vnfma(d1, o.b[2], t2); S[3] = vnfma(d1, o.b[3], t3);
;     return vfma(o.q[0], o.q[2], vnfma(d1, o.q[1], d2));
; }
	v_mul_f32 v160, v159, v160
	v_mul_f32 v168, v159, v168
	v_mul_f32 v161, v164, v161
	v_mul_f32 v169, v164, v169
	v_fma_f32 v160, v165, v162, v160
	v_fma_f32 v168, v165, v170, v168
	v_fma_f32 v161, v167, v163, v161
	v_fma_f32 v169, v167, v171, v169
	v_add_f32 v160, v160, v161
	v_add_f32 v168, v168, v169
	v_mul_f32 v172, v159, v172
	v_mul_f32 v173, v164, v173
	v_add_f32_dpp v160, v160, v160 quad_perm:[1,0,3,2] row_mask:0xf bank_mask:0xf bound_ctrl:1
	v_add_f32_dpp v168, v168, v168 quad_perm:[1,0,3,2] row_mask:0xf bank_mask:0xf bound_ctrl:1
	v_mul_f32 v174, v165, v174
	v_add_f32_dpp v160, v160, v160 quad_perm:[2,3,0,1] row_mask:0xf bank_mask:0xf bound_ctrl:1
	v_add_f32_dpp v168, v168, v168 quad_perm:[2,3,0,1] row_mask:0xf bank_mask:0xf bound_ctrl:1
	v_mul_f32 v175, v167, v175
	v_add_f32_dpp v160, v160, v160 row_half_mirror row_mask:0xf bank_mask:0xf bound_ctrl:1
	v_add_f32_dpp v168, v168, v168 row_half_mirror row_mask:0xf bank_mask:0xf bound_ctrl:1
	v_fma_f32 v172, v184, v180, v172
	v_add_f32_dpp v160, v160, v160 row_mirror row_mask:0xf bank_mask:0xf bound_ctrl:1
	v_add_f32_dpp v168, v168, v168 row_mirror row_mask:0xf bank_mask:0xf bound_ctrl:1
	v_fma_f32 v173, v184, v181, v173
	v_fma_f32 v174, v184, v182, v174
	v_fma_f32 v175, v184, v183, v175
	v_fma_f32 v159, -v160, v176, v172
	v_fma_f32 v164, -v160, v177, v173
	v_fma_f32 v165, -v160, v178, v174
	v_fma_f32 v167, -v160, v179, v175
	v_fma_f32 v168, -v160, v185, v168
	v_fma_f32 v168, v184, v186, v168
	ds_write_b32 v2, v168 offset:384
	ds_read_b128 v[160:163], v3 offset:12288
	ds_read_b128 v[168:171], v3 offset:12544
	ds_read_b128 v[172:175], v3 offset:12800
	ds_read_b128 v[180:183], v3 offset:13312
	ds_read_b128 v[184:187], v4 offset:12288
	ds_read_b128 v[176:179], v3 offset:13056
	s_waitcnt lgkmcnt(7)
	v_mul_f32 v188, v159, v188
	v_mul_f32 v192, v159, v192
	v_mul_f32 v189, v164, v189
	v_mul_f32 v193, v164, v193
	v_fma_f32 v188, v165, v190, v188
	v_fma_f32 v192, v165, v194, v192
	v_fma_f32 v189, v167, v191, v189
	v_fma_f32 v193, v167, v195, v193
	v_add_f32 v188, v188, v189
	v_add_f32 v192, v192, v193
	v_mul_f32 v196, v159, v196
	v_mul_f32 v197, v164, v197
	v_add_f32_dpp v188, v188, v188 quad_perm:[1,0,3,2] row_mask:0xf bank_mask:0xf bound_ctrl:1
	v_add_f32_dpp v192, v192, v192 quad_perm:[1,0,3,2] row_mask:0xf bank_mask:0xf bound_ctrl:1
	v_mul_f32 v198, v165, v198
	v_add_f32_dpp v188, v188, v188 quad_perm:[2,3,0,1] row_mask:0xf bank_mask:0xf bound_ctrl:1
	v_add_f32_dpp v192, v192, v192 quad_perm:[2,3,0,1] row_mask:0xf bank_mask:0xf bound_ctrl:1
	v_mul_f32 v199, v167, v199
	v_add_f32_dpp v188, v188, v188 row_half_mirror row_mask:0xf bank_mask:0xf bound_ctrl:1
	v_add_f32_dpp v192, v192, v192 row_half_mirror row_mask:0xf bank_mask:0xf bound_ctrl:1
	v_fma_f32 v196, v208, v204, v196
	v_add_f32_dpp v188, v188, v188 row_mirror row_mask:0xf bank_mask:0xf bound_ctrl:1
	v_add_f32_dpp v192, v192, v192 row_mirror row_mask:0xf bank_mask:0xf bound_ctrl:1
	v_fma_f32 v197, v208, v205, v197
	v_fma_f32 v198, v208, v206, v198
	v_fma_f32 v199, v208, v207, v199
	v_fma_f32 v159, -v188, v200, v196
	v_fma_f32 v164, -v188, v201, v197
	v_fma_f32 v165, -v188, v202, v198
	v_fma_f32 v167, -v188, v203, v199
	v_fma_f32 v192, -v188, v209, v192
	v_fma_f32 v192, v208, v210, v192
	ds_write_b32 v2, v192 offset:448
	ds_read_b128 v[188:191], v3 offset:13824
	ds_read_b128 v[192:195], v3 offset:14080
	ds_read_b128 v[196:199], v3 offset:14336
	ds_read_b128 v[204:207], v3 offset:14848
	ds_read_b128 v[208:211], v4 offset:13824
	ds_read_b128 v[200:203], v3 offset:14592
	s_waitcnt lgkmcnt(7)
	v_mul_f32 v160, v159, v160
	v_mul_f32 v168, v159, v168
	v_mul_f32 v161, v164, v161
	v_mul_f32 v169, v164, v169
	v_fma_f32 v160, v165, v162, v160
	v_fma_f32 v168, v165, v170, v168
	v_fma_f32 v161, v167, v163, v161
	v_fma_f32 v169, v167, v171, v169
	v_add_f32 v160, v160, v161
	v_add_f32 v168, v168, v169
	v_mul_f32 v172, v159, v172
	v_mul_f32 v173, v164, v173
	v_add_f32_dpp v160, v160, v160 quad_perm:[1,0,3,2] row_mask:0xf bank_mask:0xf bound_ctrl:1
	v_add_f32_dpp v168, v168, v168 quad_perm:[1,0,3,2] row_mask:0xf bank_mask:0xf bound_ctrl:1
	v_mul_f32 v174, v165, v174
	v_add_f32_dpp v160, v160, v160 quad_perm:[2,3,0,1] row_mask:0xf bank_mask:0xf bound_ctrl:1
	v_add_f32_dpp v168, v168, v168 quad_perm:[2,3,0,1] row_mask:0xf bank_mask:0xf bound_ctrl:1
	v_mul_f32 v175, v167, v175
	v_add_f32_dpp v160, v160, v160 row_half_mirror row_mask:0xf bank_mask:0xf bound_ctrl:1
	v_add_f32_dpp v168, v168, v168 row_half_mirror row_mask:0xf bank_mask:0xf bound_ctrl:1
	v_fma_f32 v172, v184, v180, v172
	v_add_f32_dpp v160, v160, v160 row_mirror row_mask:0xf bank_mask:0xf bound_ctrl:1
	v_add_f32_dpp v168, v168, v168 row_mirror row_mask:0xf bank_mask:0xf bound_ctrl:1
	v_fma_f32 v173, v184, v181, v173
	v_fma_f32 v174, v184, v182, v174
	v_fma_f32 v175, v184, v183, v175
	v_fma_f32 v159, -v160, v176, v172
	v_fma_f32 v164, -v160, v177, v173
	v_fma_f32 v165, -v160, v178, v174
	v_fma_f32 v167, -v160, v179, v175
	v_fma_f32 v168, -v160, v185, v168
	v_fma_f32 v168, v184, v186, v168
	ds_write_b32 v2, v168 offset:512
	ds_read_b128 v[160:163], v3 offset:15360
	ds_read_b128 v[168:171], v3 offset:15616
	ds_read_b128 v[172:175], v3 offset:15872
	ds_read_b128 v[180:183], v3 offset:16384
	ds_read_b128 v[184:187], v4 offset:15360
	ds_read_b128 v[176:179], v3 offset:16128
	s_waitcnt lgkmcnt(7)
; __device__ __forceinline__ float vfma(float a, float b, float c) { float d; asm("v_fma_f32 %0, %1, %2, %3" : "=v"(d) : "v"(a), "v"(b), "v"(c)); return d; }
; __device__ __forceinline__ float step_compute(float (&S)[4], const StepOp& o) {
;     float d1 = vmul(S[0], o.kk[0]), d2 = vmul(S[0], o.wr[0]), e1 = vmul(S[1], o.kk[1]), e2 = vmul(S[1], o.wr[1]);
;     d1 = vfma(S[2], o.kk[2], d1); d2 = vfma(S[2], o.wr[2], d2); e1 = vfma(S[3], o.kk[3], e1); e2 = vfma(S[3], o.wr[3], e2);
;     d1 = vadd(d1, e1); d2 = vadd(d2, e2);
;     float t0, t1, t2, t3;
;     asm volatile(
;         "v_mul_f32 %[t0], %[s0], %[w0]\n\t"
;         "v_mul_f32 %[t1], %[s1], %[w1]\n\t"
;         "v_add_f32_dpp %[d1], %[d1], %[d1] quad_perm:[1,0,3,2] row_mask:0xf bank_mask:0xf bound_ctrl:1\n\t"
;         "v_add_f32_dpp %[d2], %[d2], %[d2] quad_perm:[1,0,3,2] row_mask:0xf bank_mask:0xf bound_ctrl:1\n\t"
;         "v_mul_f32 %[t2], %[s2], %[w2]\n\t"
;         "v_add_f32_dpp %[d1], %[d1], %[d1] quad_perm:[2,3,0,1] row_mask:0xf bank_mask:0xf bound_ctrl:1\n\t"
;         "v_add_f32_dpp %[d2], %[d2], %[d2] quad_perm:[2,3,0,1] row_mask:0xf bank_mask:0xf bound_ctrl:1\n\t"
;         "v_mul_f32 %[t3], %[s3], %[w3]\n\t"
;         "v_add_f32_dpp %[d1], %[d1], %[d1] row_half_mirror row_mask:0xf bank_mask:0xf bound_ctrl:1\n\t"
;         "v_add_f32_dpp %[d2], %[d2], %[d2] row_half_mirror row_mask:0xf bank_mask:0xf bound_ctrl:1\n\t"
;         "v_fma_f32 %[t0], %[v], %[k0], %[t0]\n\t"
;         "v_add_f32_dpp %[d1], %[d1], %[d1] row_mirror row_mask:0xf bank_mask:0xf bound_ctrl:1\n\t"
;         "v_add_f32_dpp %[d2], %[d2], %[d2] row_mirror row_mask:0xf bank_mask:0xf bound_ctrl:1\n\t"
;         "v_fma_f32 %[t1], %[v], %[k1], %[t1]\n\t"
;         "v_fma_f32 %[t2], %[v], %[k2], %[t2]\n\t"
;         "v_fma_f32 %[t3], %[v], %[k3], %[t3]"
;         : [t0] "=&v"(t0), [t1] "=&v"(t1), [t2] "=&v"(t2), [t3] "=&v"(t3), [d1] "+v"(d1), [d2] "+v"(d2)
;         : [s0] "v"(S[0]), [s1] "v"(S[1]), [s2] "v"(S[2]), [s3] "v"(S[3]), [w0] "v"(o.w[0]), [w1] "v"(o.w[1]), [w2] "v"(o.w[2]), [w3] "v"(o.w[3]),
;           [k0] "v"(o.k[0]), [k1] "v"(o.k[1]), [k2] "v"(o.k[2]), [k3] "v"(o.k[3]), [v] "v"(o.q[0]));
;     S[0] = vnfma(d1, o.b[0], t0); S[1] = vnfma(d1, o.b[1], t1); S[2] = vnfma(d1, o.b[2], t2); S[3] = vnfma(d1, o.b[3], t3);
;     return vfma(o.q[0], o.q[2], vnfma(d1, o.q[1], d2));
; }
	v_mul_f32 v188, v159, v188
	v_mul_f32 v192, v159, v192
	v_mul_f32 v189, v164, v189
	v_mul_f32 v193, v164, v193
	v_fma_f32 v188, v165, v190, v188
	v_fma_f32 v192, v165, v194, v192
	v_fma_f32 v189, v167, v191, v189
	v_fma_f32 v193, v167, v195, v193
	v_add_f32 v188, v188, v189
	v_add_f32 v192, v192, v193
	v_mul_f32 v196, v159, v196
	v_mul_f32 v197, v164, v197
	v_add_f32_dpp v188, v188, v188 quad_perm:[1,0,3,2] row_mask:0xf bank_mask:0xf bound_ctrl:1
	v_add_f32_dpp v192, v192, v192 quad_perm:[1,0,3,2] row_mask:0xf bank_mask:0xf bound_ctrl:1
	v_mul_f32 v198, v165, v198
	v_add_f32_dpp v188, v188, v188 quad_perm:[2,3,0,1] row_mask:0xf bank_mask:0xf bound_ctrl:1
	v_add_f32_dpp v192, v192, v192 quad_perm:[2,3,0,1] row_mask:0xf bank_mask:0xf bound_ctrl:1
	v_mul_f32 v199, v167, v199
	v_add_f32_dpp v188, v188, v188 row_half_mirror row_mask:0xf bank_mask:0xf bound_ctrl:1
	v_add_f32_dpp v192, v192, v192 row_half_mirror row_mask:0xf bank_mask:0xf bound_ctrl:1
	v_fma_f32 v196, v208, v204, v196
	v_add_f32_dpp v188, v188, v188 row_mirror row_mask:0xf bank_mask:0xf bound_ctrl:1
	v_add_f32_dpp v192, v192, v192 row_mirror row_mask:0xf bank_mask:0xf bound_ctrl:1
	v_fma_f32 v197, v208, v205, v197
	v_fma_f32 v198, v208, v206, v198
	v_fma_f32 v199, v208, v207, v199
	v_fma_f32 v159, -v188, v200, v196
	v_fma_f32 v164, -v188, v201, v197
	v_fma_f32 v165, -v188, v202, v198
	v_fma_f32 v167, -v188, v203, v199
	v_fma_f32 v192, -v188, v209, v192
	v_fma_f32 v192, v208, v210, v192
	ds_write_b32 v2, v192 offset:576
	ds_read_b128 v[188:191], v3 offset:16896
	ds_read_b128 v[192:195], v3 offset:17152
	ds_read_b128 v[196:199], v3 offset:17408
	ds_read_b128 v[204:207], v3 offset:17920
	ds_read_b128 v[208:211], v4 offset:16896
	ds_read_b128 v[200:203], v3 offset:17664
	s_waitcnt lgkmcnt(7)
	v_mul_f32 v160, v159, v160
	v_mul_f32 v168, v159, v168
	v_mul_f32 v161, v164, v161
	v_mul_f32 v169, v164, v169
	v_fma_f32 v160, v165, v162, v160
	v_fma_f32 v168, v165, v170, v168
	v_fma_f32 v161, v167, v163, v161
	v_fma_f32 v169, v167, v171, v169
	v_add_f32 v160, v160, v161
	v_add_f32 v168, v168, v169
	v_mul_f32 v172, v159, v172
	v_mul_f32 v173, v164, v173
	v_add_f32_dpp v160, v160, v160 quad_perm:[1,0,3,2] row_mask:0xf bank_mask:0xf bound_ctrl:1
	v_add_f32_dpp v168, v168, v168 quad_perm:[1,0,3,2] row_mask:0xf bank_mask:0xf bound_ctrl:1
	v_mul_f32 v174, v165, v174
	v_add_f32_dpp v160, v160, v160 quad_perm:[2,3,0,1] row_mask:0xf bank_mask:0xf bound_ctrl:1
	v_add_f32_dpp v168, v168, v168 quad_perm:[2,3,0,1] row_mask:0xf bank_mask:0xf bound_ctrl:1
	v_mul_f32 v175, v167, v175
	v_add_f32_dpp v160, v160, v160 row_half_mirror row_mask:0xf bank_mask:0xf bound_ctrl:1
	v_add_f32_dpp v168, v168, v168 row_half_mirror row_mask:0xf bank_mask:0xf bound_ctrl:1
	v_fma_f32 v172, v184, v180, v172
	v_add_f32_dpp v160, v160, v160 row_mirror row_mask:0xf bank_mask:0xf bound_ctrl:1
	v_add_f32_dpp v168, v168, v168 row_mirror row_mask:0xf bank_mask:0xf bound_ctrl:1
	v_fma_f32 v173, v184, v181, v173
	v_fma_f32 v174, v184, v182, v174
	v_fma_f32 v175, v184, v183, v175
	v_fma_f32 v159, -v160, v176, v172
	v_fma_f32 v164, -v160, v177, v173
	v_fma_f32 v165, -v160, v178, v174
	v_fma_f32 v167, -v160, v179, v175
	v_fma_f32 v168, -v160, v185, v168
	v_fma_f32 v168, v184, v186, v168
	ds_write_b32 v2, v168 offset:640
	ds_read_b128 v[160:163], v3 offset:18432
	ds_read_b128 v[168:171], v3 offset:18688
	ds_read_b128 v[172:175], v3 offset:18944
	ds_read_b128 v[180:183], v3 offset:19456
	ds_read_b128 v[184:187], v4 offset:18432
	ds_read_b128 v[176:179], v3 offset:19200
	s_waitcnt lgkmcnt(7)
	v_mul_f32 v188, v159, v188
	v_mul_f32 v192, v159, v192
	v_mul_f32 v189, v164, v189
	v_mul_f32 v193, v164, v193
	v_fma_f32 v188, v165, v190, v188
	v_fma_f32 v192, v165, v194, v192
	v_fma_f32 v189, v167, v191, v189
	v_fma_f32 v193, v167, v195, v193
	v_add_f32 v188, v188, v189
	v_add_f32 v192, v192, v193
	v_mul_f32 v196, v159, v196
	v_mul_f32 v197, v164, v197
	v_add_f32_dpp v188, v188, v188 quad_perm:[1,0,3,2] row_mask:0xf bank_mask:0xf bound_ctrl:1
	v_add_f32_dpp v192, v192, v192 quad_perm:[1,0,3,2] row_mask:0xf bank_mask:0xf bound_ctrl:1
	v_mul_f32 v198, v165, v198
	v_add_f32_dpp v188, v188, v188 quad_perm:[2,3,0,1] row_mask:0xf bank_mask:0xf bound_ctrl:1
	v_add_f32_dpp v192, v192, v192 quad_perm:[2,3,0,1] row_mask:0xf bank_mask:0xf bound_ctrl:1
	v_mul_f32 v199, v167, v199
	v_add_f32_dpp v188, v188, v188 row_half_mirror row_mask:0xf bank_mask:0xf bound_ctrl:1
	v_add_f32_dpp v192, v192, v192 row_half_mirror row_mask:0xf bank_mask:0xf bound_ctrl:1
	v_fma_f32 v196, v208, v204, v196
	v_add_f32_dpp v188, v188, v188 row_mirror row_mask:0xf bank_mask:0xf bound_ctrl:1
	v_add_f32_dpp v192, v192, v192 row_mirror row_mask:0xf bank_mask:0xf bound_ctrl:1
	v_fma_f32 v197, v208, v205, v197
	v_fma_f32 v198, v208, v206, v198
	v_fma_f32 v199, v208, v207, v199
	v_fma_f32 v159, -v188, v200, v196
	v_fma_f32 v164, -v188, v201, v197
	v_fma_f32 v165, -v188, v202, v198
	v_fma_f32 v167, -v188, v203, v199
	v_fma_f32 v192, -v188, v209, v192
	v_fma_f32 v192, v208, v210, v192
	ds_write_b32 v2, v192 offset:704
	ds_read_b128 v[188:191], v3 offset:19968
	ds_read_b128 v[192:195], v3 offset:20224
	ds_read_b128 v[196:199], v3 offset:20480
	ds_read_b128 v[204:207], v3 offset:20992
	ds_read_b128 v[208:211], v4 offset:19968
	ds_read_b128 v[200:203], v3 offset:20736
	s_waitcnt lgkmcnt(7)
; __device__ __forceinline__ float vfma(float a, float b, float c) { float d; asm("v_fma_f32 %0, %1, %2, %3" : "=v"(d) : "v"(a), "v"(b), "v"(c)); return d; }
; __device__ __forceinline__ float step_compute(float (&S)[4], const StepOp& o) {
;     float d1 = vmul(S[0], o.kk[0]), d2 = vmul(S[0], o.wr[0]), e1 = vmul(S[1], o.kk[1]), e2 = vmul(S[1], o.wr[1]);
;     d1 = vfma(S[2], o.kk[2], d1); d2 = vfma(S[2], o.wr[2], d2); e1 = vfma(S[3], o.kk[3], e1); e2 = vfma(S[3], o.wr[3], e2);
;     d1 = vadd(d1, e1); d2 = vadd(d2, e2);
;     float t0, t1, t2, t3;
;     asm volatile(
;         "v_mul_f32 %[t0], %[s0], %[w0]\n\t"
;         "v_mul_f32 %[t1], %[s1], %[w1]\n\t"
;         "v_add_f32_dpp %[d1], %[d1], %[d1] quad_perm:[1,0,3,2] row_mask:0xf bank_mask:0xf bound_ctrl:1\n\t"
;         "v_add_f32_dpp %[d2], %[d2], %[d2] quad_perm:[1,0,3,2] row_mask:0xf bank_mask:0xf bound_ctrl:1\n\t"
;         "v_mul_f32 %[t2], %[s2], %[w2]\n\t"
;         "v_add_f32_dpp %[d1], %[d1], %[d1] quad_perm:[2,3,0,1] row_mask:0xf bank_mask:0xf bound_ctrl:1\n\t"
;         "v_add_f32_dpp %[d2], %[d2], %[d2] quad_perm:[2,3,0,1] row_mask:0xf bank_mask:0xf bound_ctrl:1\n\t"
;         "v_mul_f32 %[t3], %[s3], %[w3]\n\t"
;         "v_add_f32_dpp %[d1], %[d1], %[d1] row_half_mirror row_mask:0xf bank_mask:0xf bound_ctrl:1\n\t"
;         "v_add_f32_dpp %[d2], %[d2], %[d2] row_half_mirror row_mask:0xf bank_mask:0xf bound_ctrl:1\n\t"
;         "v_fma_f32 %[t0], %[v], %[k0], %[t0]\n\t"
;         "v_add_f32_dpp %[d1], %[d1], %[d1] row_mirror row_mask:0xf bank_mask:0xf bound_ctrl:1\n\t"
;         "v_add_f32_dpp %[d2], %[d2], %[d2] row_mirror row_mask:0xf bank_mask:0xf bound_ctrl:1\n\t"
;         "v_fma_f32 %[t1], %[v], %[k1], %[t1]\n\t"
;         "v_fma_f32 %[t2], %[v], %[k2], %[t2]\n\t"
;         "v_fma_f32 %[t3], %[v], %[k3], %[t3]"
;         : [t0] "=&v"(t0), [t1] "=&v"(t1), [t2] "=&v"(t2), [t3] "=&v"(t3), [d1] "+v"(d1), [d2] "+v"(d2)
;         : [s0] "v"(S[0]), [s1] "v"(S[1]), [s2] "v"(S[2]), [s3] "v"(S[3]), [w0] "v"(o.w[0]), [w1] "v"(o.w[1]), [w2] "v"(o.w[2]), [w3] "v"(o.w[3]),
;           [k0] "v"(o.k[0]), [k1] "v"(o.k[1]), [k2] "v"(o.k[2]), [k3] "v"(o.k[3]), [v] "v"(o.q[0]));
;     S[0] = vnfma(d1, o.b[0], t0); S[1] = vnfma(d1, o.b[1], t1); S[2] = vnfma(d1, o.b[2], t2); S[3] = vnfma(d1, o.b[3], t3);
;     return vfma(o.q[0], o.q[2], vnfma(d1, o.q[1], d2));
; }
	v_mul_f32 v160, v159, v160
	v_mul_f32 v168, v159, v168
	v_mul_f32 v161, v164, v161
	v_mul_f32 v169, v164, v169
	v_fma_f32 v160, v165, v162, v160
	v_fma_f32 v168, v165, v170, v168
	v_fma_f32 v161, v167, v163, v161
	v_fma_f32 v169, v167, v171, v169
	v_add_f32 v160, v160, v161
	v_add_f32 v168, v168, v169
	v_mul_f32 v172, v159, v172
	v_mul_f32 v173, v164, v173
	v_add_f32_dpp v160, v160, v160 quad_perm:[1,0,3,2] row_mask:0xf bank_mask:0xf bound_ctrl:1
	v_add_f32_dpp v168, v168, v168 quad_perm:[1,0,3,2] row_mask:0xf bank_mask:0xf bound_ctrl:1
	v_mul_f32 v174, v165, v174
	v_add_f32_dpp v160, v160, v160 quad_perm:[2,3,0,1] row_mask:0xf bank_mask:0xf bound_ctrl:1
	v_add_f32_dpp v168, v168, v168 quad_perm:[2,3,0,1] row_mask:0xf bank_mask:0xf bound_ctrl:1
	v_mul_f32 v175, v167, v175
	v_add_f32_dpp v160, v160, v160 row_half_mirror row_mask:0xf bank_mask:0xf bound_ctrl:1
	v_add_f32_dpp v168, v168, v168 row_half_mirror row_mask:0xf bank_mask:0xf bound_ctrl:1
	v_fma_f32 v172, v184, v180, v172
	v_add_f32_dpp v160, v160, v160 row_mirror row_mask:0xf bank_mask:0xf bound_ctrl:1
	v_add_f32_dpp v168, v168, v168 row_mirror row_mask:0xf bank_mask:0xf bound_ctrl:1
	v_fma_f32 v173, v184, v181, v173
	v_fma_f32 v174, v184, v182, v174
	v_fma_f32 v175, v184, v183, v175
	v_fma_f32 v159, -v160, v176, v172
	v_fma_f32 v164, -v160, v177, v173
	v_fma_f32 v165, -v160, v178, v174
	v_fma_f32 v167, -v160, v179, v175
	v_fma_f32 v168, -v160, v185, v168
	v_fma_f32 v168, v184, v186, v168
	ds_write_b32 v2, v168 offset:768
	ds_read_b128 v[160:163], v3 offset:21504
	ds_read_b128 v[168:171], v3 offset:21760
	ds_read_b128 v[172:175], v3 offset:22016
	ds_read_b128 v[180:183], v3 offset:22528
	ds_read_b128 v[184:187], v4 offset:21504
	ds_read_b128 v[176:179], v3 offset:22272
	s_waitcnt lgkmcnt(7)
	v_mul_f32 v188, v159, v188
	v_mul_f32 v192, v159, v192
	v_mul_f32 v189, v164, v189
	v_mul_f32 v193, v164, v193
	v_fma_f32 v188, v165, v190, v188
	v_fma_f32 v192, v165, v194, v192
	v_fma_f32 v189, v167, v191, v189
	v_fma_f32 v193, v167, v195, v193
	v_add_f32 v188, v188, v189
	v_add_f32 v192, v192, v193
	v_mul_f32 v196, v159, v196
	v_mul_f32 v197, v164, v197
	v_add_f32_dpp v188, v188, v188 quad_perm:[1,0,3,2] row_mask:0xf bank_mask:0xf bound_ctrl:1
	v_add_f32_dpp v192, v192, v192 quad_perm:[1,0,3,2] row_mask:0xf bank_mask:0xf bound_ctrl:1
	v_mul_f32 v198, v165, v198
	v_add_f32_dpp v188, v188, v188 quad_perm:[2,3,0,1] row_mask:0xf bank_mask:0xf bound_ctrl:1
	v_add_f32_dpp v192, v192, v192 quad_perm:[2,3,0,1] row_mask:0xf bank_mask:0xf bound_ctrl:1
	v_mul_f32 v199, v167, v199
	v_add_f32_dpp v188, v188, v188 row_half_mirror row_mask:0xf bank_mask:0xf bound_ctrl:1
	v_add_f32_dpp v192, v192, v192 row_half_mirror row_mask:0xf bank_mask:0xf bound_ctrl:1
	v_fma_f32 v196, v208, v204, v196
	v_add_f32_dpp v188, v188, v188 row_mirror row_mask:0xf bank_mask:0xf bound_ctrl:1
	v_add_f32_dpp v192, v192, v192 row_mirror row_mask:0xf bank_mask:0xf bound_ctrl:1
	v_fma_f32 v197, v208, v205, v197
	v_fma_f32 v198, v208, v206, v198
	v_fma_f32 v199, v208, v207, v199
	v_fma_f32 v159, -v188, v200, v196
	v_fma_f32 v164, -v188, v201, v197
	v_fma_f32 v165, -v188, v202, v198
	v_fma_f32 v167, -v188, v203, v199
	v_fma_f32 v192, -v188, v209, v192
	v_fma_f32 v192, v208, v210, v192
	ds_write_b32 v2, v192 offset:832
	ds_read_b128 v[188:191], v3 offset:23040
	ds_read_b128 v[192:195], v3 offset:23296
	ds_read_b128 v[196:199], v3 offset:23552
	ds_read_b128 v[204:207], v3 offset:24064
	ds_read_b128 v[208:211], v4 offset:23040
	ds_read_b128 v[200:203], v3 offset:23808
	s_waitcnt lgkmcnt(7)
	v_mul_f32 v160, v159, v160
	v_mul_f32 v168, v159, v168
	v_mul_f32 v161, v164, v161
	v_mul_f32 v169, v164, v169
	v_fma_f32 v160, v165, v162, v160
	v_fma_f32 v168, v165, v170, v168
	v_fma_f32 v161, v167, v163, v161
	v_fma_f32 v169, v167, v171, v169
	v_add_f32 v160, v160, v161
	v_add_f32 v168, v168, v169
	v_mul_f32 v172, v159, v172
	v_mul_f32 v173, v164, v173
	v_add_f32_dpp v160, v160, v160 quad_perm:[1,0,3,2] row_mask:0xf bank_mask:0xf bound_ctrl:1
	v_add_f32_dpp v168, v168, v168 quad_perm:[1,0,3,2] row_mask:0xf bank_mask:0xf bound_ctrl:1
	v_mul_f32 v174, v165, v174
	v_add_f32_dpp v160, v160, v160 quad_perm:[2,3,0,1] row_mask:0xf bank_mask:0xf bound_ctrl:1
	v_add_f32_dpp v168, v168, v168 quad_perm:[2,3,0,1] row_mask:0xf bank_mask:0xf bound_ctrl:1
	v_mul_f32 v175, v167, v175
	v_add_f32_dpp v160, v160, v160 row_half_mirror row_mask:0xf bank_mask:0xf bound_ctrl:1
	v_add_f32_dpp v168, v168, v168 row_half_mirror row_mask:0xf bank_mask:0xf bound_ctrl:1
	v_fma_f32 v172, v184, v180, v172
	v_add_f32_dpp v160, v160, v160 row_mirror row_mask:0xf bank_mask:0xf bound_ctrl:1
	v_add_f32_dpp v168, v168, v168 row_mirror row_mask:0xf bank_mask:0xf bound_ctrl:1
	v_fma_f32 v173, v184, v181, v173
	v_fma_f32 v174, v184, v182, v174
	v_fma_f32 v175, v184, v183, v175
	v_fma_f32 v159, -v160, v176, v172
	v_fma_f32 v164, -v160, v177, v173
	v_fma_f32 v165, -v160, v178, v174
	v_fma_f32 v167, -v160, v179, v175
	v_fma_f32 v168, -v160, v185, v168
	v_fma_f32 v168, v184, v186, v168
	ds_write_b32 v2, v168 offset:896
	ds_read_b128 v[160:163], v3 offset:24576
	ds_read_b128 v[168:171], v3 offset:24832
	ds_read_b128 v[172:175], v3 offset:25088
	ds_read_b128 v[180:183], v3 offset:25600
	ds_read_b128 v[184:187], v4 offset:24576
	ds_read_b128 v[176:179], v3 offset:25344
	s_waitcnt lgkmcnt(7)
; __device__ __forceinline__ float vfma(float a, float b, float c) { float d; asm("v_fma_f32 %0, %1, %2, %3" : "=v"(d) : "v"(a), "v"(b), "v"(c)); return d; }
; __device__ __forceinline__ float step_compute(float (&S)[4], const StepOp& o) {
;     float d1 = vmul(S[0], o.kk[0]), d2 = vmul(S[0], o.wr[0]), e1 = vmul(S[1], o.kk[1]), e2 = vmul(S[1], o.wr[1]);
;     d1 = vfma(S[2], o.kk[2], d1); d2 = vfma(S[2], o.wr[2], d2); e1 = vfma(S[3], o.kk[3], e1); e2 = vfma(S[3], o.wr[3], e2);
;     d1 = vadd(d1, e1); d2 = vadd(d2, e2);
;     float t0, t1, t2, t3;
;     asm volatile(
;         "v_mul_f32 %[t0], %[s0], %[w0]\n\t"
;         "v_mul_f32 %[t1], %[s1], %[w1]\n\t"
;         "v_add_f32_dpp %[d1], %[d1], %[d1] quad_perm:[1,0,3,2] row_mask:0xf bank_mask:0xf bound_ctrl:1\n\t"
;         "v_add_f32_dpp %[d2], %[d2], %[d2] quad_perm:[1,0,3,2] row_mask:0xf bank_mask:0xf bound_ctrl:1\n\t"
;         "v_mul_f32 %[t2], %[s2], %[w2]\n\t"
;         "v_add_f32_dpp %[d1], %[d1], %[d1] quad_perm:[2,3,0,1] row_mask:0xf bank_mask:0xf bound_ctrl:1\n\t"
;         "v_add_f32_dpp %[d2], %[d2], %[d2] quad_perm:[2,3,0,1] row_mask:0xf bank_mask:0xf bound_ctrl:1\n\t"
;         "v_mul_f32 %[t3], %[s3], %[w3]\n\t"
;         "v_add_f32_dpp %[d1], %[d1], %[d1] row_half_mirror row_mask:0xf bank_mask:0xf bound_ctrl:1\n\t"
;         "v_add_f32_dpp %[d2], %[d2], %[d2] row_half_mirror row_mask:0xf bank_mask:0xf bound_ctrl:1\n\t"
;         "v_fma_f32 %[t0], %[v], %[k0], %[t0]\n\t"
;         "v_add_f32_dpp %[d1], %[d1], %[d1] row_mirror row_mask:0xf bank_mask:0xf bound_ctrl:1\n\t"
;         "v_add_f32_dpp %[d2], %[d2], %[d2] row_mirror row_mask:0xf bank_mask:0xf bound_ctrl:1\n\t"
;         "v_fma_f32 %[t1], %[v], %[k1], %[t1]\n\t"
;         "v_fma_f32 %[t2], %[v], %[k2], %[t2]\n\t"
;         "v_fma_f32 %[t3], %[v], %[k3], %[t3]"
;         : [t0] "=&v"(t0), [t1] "=&v"(t1), [t2] "=&v"(t2), [t3] "=&v"(t3), [d1] "+v"(d1), [d2] "+v"(d2)
;         : [s0] "v"(S[0]), [s1] "v"(S[1]), [s2] "v"(S[2]), [s3] "v"(S[3]), [w0] "v"(o.w[0]), [w1] "v"(o.w[1]), [w2] "v"(o.w[2]), [w3] "v"(o.w[3]),
;           [k0] "v"(o.k[0]), [k1] "v"(o.k[1]), [k2] "v"(o.k[2]), [k3] "v"(o.k[3]), [v] "v"(o.q[0]));
;     S[0] = vnfma(d1, o.b[0], t0); S[1] = vnfma(d1, o.b[1], t1); S[2] = vnfma(d1, o.b[2], t2); S[3] = vnfma(d1, o.b[3], t3);
;     return vfma(o.q[0], o.q[2], vnfma(d1, o.q[1], d2));
; }
	v_mul_f32 v188, v159, v188
	v_mul_f32 v192, v159, v192
	v_mul_f32 v189, v164, v189
	v_mul_f32 v193, v164, v193
	v_fma_f32 v188, v165, v190, v188
	v_fma_f32 v192, v165, v194, v192
	v_fma_f32 v189, v167, v191, v189
	v_fma_f32 v193, v167, v195, v193
	v_add_f32 v188, v188, v189
	v_add_f32 v192, v192, v193
	v_mul_f32 v196, v159, v196
	v_mul_f32 v197, v164, v197
	v_add_f32_dpp v188, v188, v188 quad_perm:[1,0,3,2] row_mask:0xf bank_mask:0xf bound_ctrl:1
	v_add_f32_dpp v192, v192, v192 quad_perm:[1,0,3,2] row_mask:0xf bank_mask:0xf bound_ctrl:1
	v_mul_f32 v198, v165, v198
	v_add_f32_dpp v188, v188, v188 quad_perm:[2,3,0,1] row_mask:0xf bank_mask:0xf bound_ctrl:1
	v_add_f32_dpp v192, v192, v192 quad_perm:[2,3,0,1] row_mask:0xf bank_mask:0xf bound_ctrl:1
	v_mul_f32 v199, v167, v199
	v_add_f32_dpp v188, v188, v188 row_half_mirror row_mask:0xf bank_mask:0xf bound_ctrl:1
	v_add_f32_dpp v192, v192, v192 row_half_mirror row_mask:0xf bank_mask:0xf bound_ctrl:1
	v_fma_f32 v196, v208, v204, v196
	v_add_f32_dpp v188, v188, v188 row_mirror row_mask:0xf bank_mask:0xf bound_ctrl:1
	v_add_f32_dpp v192, v192, v192 row_mirror row_mask:0xf bank_mask:0xf bound_ctrl:1
	v_fma_f32 v197, v208, v205, v197
	v_fma_f32 v198, v208, v206, v198
	v_fma_f32 v199, v208, v207, v199
	v_fma_f32 v159, -v188, v200, v196
	v_fma_f32 v164, -v188, v201, v197
	v_fma_f32 v165, -v188, v202, v198
	v_fma_f32 v167, -v188, v203, v199
	v_fma_f32 v192, -v188, v209, v192
	v_fma_f32 v192, v208, v210, v192
	ds_write_b32 v2, v192 offset:960
	ds_read_b128 v[188:191], v3 offset:26112
	ds_read_b128 v[192:195], v3 offset:26368
	ds_read_b128 v[196:199], v3 offset:26624
	ds_read_b128 v[204:207], v3 offset:27136
	ds_read_b128 v[208:211], v4 offset:26112
	ds_read_b128 v[200:203], v3 offset:26880
	s_waitcnt lgkmcnt(7)
	v_mul_f32 v160, v159, v160
	v_mul_f32 v168, v159, v168
	v_mul_f32 v161, v164, v161
	v_mul_f32 v169, v164, v169
	v_fma_f32 v160, v165, v162, v160
	v_fma_f32 v168, v165, v170, v168
	v_fma_f32 v161, v167, v163, v161
	v_fma_f32 v169, v167, v171, v169
	v_add_f32 v160, v160, v161
	v_add_f32 v168, v168, v169
	v_mul_f32 v172, v159, v172
	v_mul_f32 v173, v164, v173
	v_add_f32_dpp v160, v160, v160 quad_perm:[1,0,3,2] row_mask:0xf bank_mask:0xf bound_ctrl:1
	v_add_f32_dpp v168, v168, v168 quad_perm:[1,0,3,2] row_mask:0xf bank_mask:0xf bound_ctrl:1
	v_mul_f32 v174, v165, v174
	v_add_f32_dpp v160, v160, v160 quad_perm:[2,3,0,1] row_mask:0xf bank_mask:0xf bound_ctrl:1
	v_add_f32_dpp v168, v168, v168 quad_perm:[2,3,0,1] row_mask:0xf bank_mask:0xf bound_ctrl:1
	v_mul_f32 v175, v167, v175
	v_add_f32_dpp v160, v160, v160 row_half_mirror row_mask:0xf bank_mask:0xf bound_ctrl:1
	v_add_f32_dpp v168, v168, v168 row_half_mirror row_mask:0xf bank_mask:0xf bound_ctrl:1
	v_fma_f32 v172, v184, v180, v172
	v_add_f32_dpp v160, v160, v160 row_mirror row_mask:0xf bank_mask:0xf bound_ctrl:1
	v_add_f32_dpp v168, v168, v168 row_mirror row_mask:0xf bank_mask:0xf bound_ctrl:1
	v_fma_f32 v173, v184, v181, v173
	v_fma_f32 v174, v184, v182, v174
	v_fma_f32 v175, v184, v183, v175
	v_fma_f32 v159, -v160, v176, v172
	v_fma_f32 v164, -v160, v177, v173
	v_fma_f32 v165, -v160, v178, v174
	v_fma_f32 v167, -v160, v179, v175
	v_fma_f32 v168, -v160, v185, v168
	v_fma_f32 v168, v184, v186, v168
	ds_write_b32 v2, v168 offset:1024
	ds_read_b128 v[160:163], v3 offset:27648
	ds_read_b128 v[168:171], v3 offset:27904
	ds_read_b128 v[172:175], v3 offset:28160
	ds_read_b128 v[180:183], v3 offset:28672
	ds_read_b128 v[184:187], v4 offset:27648
	ds_read_b128 v[176:179], v3 offset:28416
	s_waitcnt lgkmcnt(7)
	v_mul_f32 v188, v159, v188
	v_mul_f32 v192, v159, v192
	v_mul_f32 v189, v164, v189
	v_mul_f32 v193, v164, v193
	v_fma_f32 v188, v165, v190, v188
	v_fma_f32 v192, v165, v194, v192
	v_fma_f32 v189, v167, v191, v189
	v_fma_f32 v193, v167, v195, v193
	v_add_f32 v188, v188, v189
	v_add_f32 v192, v192, v193
	v_mul_f32 v196, v159, v196
	v_mul_f32 v197, v164, v197
	v_add_f32_dpp v188, v188, v188 quad_perm:[1,0,3,2] row_mask:0xf bank_mask:0xf bound_ctrl:1
	v_add_f32_dpp v192, v192, v192 quad_perm:[1,0,3,2] row_mask:0xf bank_mask:0xf bound_ctrl:1
	v_mul_f32 v198, v165, v198
	v_add_f32_dpp v188, v188, v188 quad_perm:[2,3,0,1] row_mask:0xf bank_mask:0xf bound_ctrl:1
	v_add_f32_dpp v192, v192, v192 quad_perm:[2,3,0,1] row_mask:0xf bank_mask:0xf bound_ctrl:1
	v_mul_f32 v199, v167, v199
	v_add_f32_dpp v188, v188, v188 row_half_mirror row_mask:0xf bank_mask:0xf bound_ctrl:1
	v_add_f32_dpp v192, v192, v192 row_half_mirror row_mask:0xf bank_mask:0xf bound_ctrl:1
	v_fma_f32 v196, v208, v204, v196
	v_add_f32_dpp v188, v188, v188 row_mirror row_mask:0xf bank_mask:0xf bound_ctrl:1
	v_add_f32_dpp v192, v192, v192 row_mirror row_mask:0xf bank_mask:0xf bound_ctrl:1
	v_fma_f32 v197, v208, v205, v197
	v_fma_f32 v198, v208, v206, v198
	v_fma_f32 v199, v208, v207, v199
	v_fma_f32 v159, -v188, v200, v196
	v_fma_f32 v164, -v188, v201, v197
	v_fma_f32 v165, -v188, v202, v198
	v_fma_f32 v167, -v188, v203, v199
	v_fma_f32 v192, -v188, v209, v192
	v_fma_f32 v192, v208, v210, v192
	ds_write_b32 v2, v192 offset:1088
	ds_read_b128 v[188:191], v3 offset:29184
	ds_read_b128 v[192:195], v3 offset:29440
	ds_read_b128 v[196:199], v3 offset:29696
	ds_read_b128 v[204:207], v3 offset:30208
	ds_read_b128 v[208:211], v4 offset:29184
	ds_read_b128 v[200:203], v3 offset:29952
	s_waitcnt lgkmcnt(7)
; __device__ __forceinline__ float vfma(float a, float b, float c) { float d; asm("v_fma_f32 %0, %1, %2, %3" : "=v"(d) : "v"(a), "v"(b), "v"(c)); return d; }
; __device__ __forceinline__ float step_compute(float (&S)[4], const StepOp& o) {
;     float d1 = vmul(S[0], o.kk[0]), d2 = vmul(S[0], o.wr[0]), e1 = vmul(S[1], o.kk[1]), e2 = vmul(S[1], o.wr[1]);
;     d1 = vfma(S[2], o.kk[2], d1); d2 = vfma(S[2], o.wr[2], d2); e1 = vfma(S[3], o.kk[3], e1); e2 = vfma(S[3], o.wr[3], e2);
;     d1 = vadd(d1, e1); d2 = vadd(d2, e2);
;     float t0, t1, t2, t3;
;     asm volatile(
;         "v_mul_f32 %[t0], %[s0], %[w0]\n\t"
;         "v_mul_f32 %[t1], %[s1], %[w1]\n\t"
;         "v_add_f32_dpp %[d1], %[d1], %[d1] quad_perm:[1,0,3,2] row_mask:0xf bank_mask:0xf bound_ctrl:1\n\t"
;         "v_add_f32_dpp %[d2], %[d2], %[d2] quad_perm:[1,0,3,2] row_mask:0xf bank_mask:0xf bound_ctrl:1\n\t"
;         "v_mul_f32 %[t2], %[s2], %[w2]\n\t"
;         "v_add_f32_dpp %[d1], %[d1], %[d1] quad_perm:[2,3,0,1] row_mask:0xf bank_mask:0xf bound_ctrl:1\n\t"
;         "v_add_f32_dpp %[d2], %[d2], %[d2] quad_perm:[2,3,0,1] row_mask:0xf bank_mask:0xf bound_ctrl:1\n\t"
;         "v_mul_f32 %[t3], %[s3], %[w3]\n\t"
;         "v_add_f32_dpp %[d1], %[d1], %[d1] row_half_mirror row_mask:0xf bank_mask:0xf bound_ctrl:1\n\t"
;         "v_add_f32_dpp %[d2], %[d2], %[d2] row_half_mirror row_mask:0xf bank_mask:0xf bound_ctrl:1\n\t"
;         "v_fma_f32 %[t0], %[v], %[k0], %[t0]\n\t"
;         "v_add_f32_dpp %[d1], %[d1], %[d1] row_mirror row_mask:0xf bank_mask:0xf bound_ctrl:1\n\t"
;         "v_add_f32_dpp %[d2], %[d2], %[d2] row_mirror row_mask:0xf bank_mask:0xf bound_ctrl:1\n\t"
;         "v_fma_f32 %[t1], %[v], %[k1], %[t1]\n\t"
;         "v_fma_f32 %[t2], %[v], %[k2], %[t2]\n\t"
;         "v_fma_f32 %[t3], %[v], %[k3], %[t3]"
;         : [t0] "=&v"(t0), [t1] "=&v"(t1), [t2] "=&v"(t2), [t3] "=&v"(t3), [d1] "+v"(d1), [d2] "+v"(d2)
;         : [s0] "v"(S[0]), [s1] "v"(S[1]), [s2] "v"(S[2]), [s3] "v"(S[3]), [w0] "v"(o.w[0]), [w1] "v"(o.w[1]), [w2] "v"(o.w[2]), [w3] "v"(o.w[3]),
;           [k0] "v"(o.k[0]), [k1] "v"(o.k[1]), [k2] "v"(o.k[2]), [k3] "v"(o.k[3]), [v] "v"(o.q[0]));
;     S[0] = vnfma(d1, o.b[0], t0); S[1] = vnfma(d1, o.b[1], t1); S[2] = vnfma(d1, o.b[2], t2); S[3] = vnfma(d1, o.b[3], t3);
;     return vfma(o.q[0], o.q[2], vnfma(d1, o.q[1], d2));
; }
	v_mul_f32 v160, v159, v160
	v_mul_f32 v168, v159, v168
	v_mul_f32 v161, v164, v161
	v_mul_f32 v169, v164, v169
	v_fma_f32 v160, v165, v162, v160
	v_fma_f32 v168, v165, v170, v168
	v_fma_f32 v161, v167, v163, v161
	v_fma_f32 v169, v167, v171, v169
	v_add_f32 v160, v160, v161
	v_add_f32 v168, v168, v169
	v_mul_f32 v172, v159, v172
	v_mul_f32 v173, v164, v173
	v_add_f32_dpp v160, v160, v160 quad_perm:[1,0,3,2] row_mask:0xf bank_mask:0xf bound_ctrl:1
	v_add_f32_dpp v168, v168, v168 quad_perm:[1,0,3,2] row_mask:0xf bank_mask:0xf bound_ctrl:1
	v_mul_f32 v174, v165, v174
	v_add_f32_dpp v160, v160, v160 quad_perm:[2,3,0,1] row_mask:0xf bank_mask:0xf bound_ctrl:1
	v_add_f32_dpp v168, v168, v168 quad_perm:[2,3,0,1] row_mask:0xf bank_mask:0xf bound_ctrl:1
	v_mul_f32 v175, v167, v175
	v_add_f32_dpp v160, v160, v160 row_half_mirror row_mask:0xf bank_mask:0xf bound_ctrl:1
	v_add_f32_dpp v168, v168, v168 row_half_mirror row_mask:0xf bank_mask:0xf bound_ctrl:1
	v_fma_f32 v172, v184, v180, v172
	v_add_f32_dpp v160, v160, v160 row_mirror row_mask:0xf bank_mask:0xf bound_ctrl:1
	v_add_f32_dpp v168, v168, v168 row_mirror row_mask:0xf bank_mask:0xf bound_ctrl:1
	v_fma_f32 v173, v184, v181, v173
	v_fma_f32 v174, v184, v182, v174
	v_fma_f32 v175, v184, v183, v175
	v_fma_f32 v159, -v160, v176, v172
	v_fma_f32 v164, -v160, v177, v173
	v_fma_f32 v165, -v160, v178, v174
	v_fma_f32 v167, -v160, v179, v175
	v_fma_f32 v168, -v160, v185, v168
	v_fma_f32 v168, v184, v186, v168
	ds_write_b32 v2, v168 offset:1152
	ds_read_b128 v[160:163], v3 offset:30720
	ds_read_b128 v[168:171], v3 offset:30976
	ds_read_b128 v[172:175], v3 offset:31232
	ds_read_b128 v[180:183], v3 offset:31744
	ds_read_b128 v[184:187], v4 offset:30720
	ds_read_b128 v[176:179], v3 offset:31488
	s_waitcnt lgkmcnt(7)
	v_mul_f32 v188, v159, v188
	v_mul_f32 v192, v159, v192
	v_mul_f32 v189, v164, v189
	v_mul_f32 v193, v164, v193
	v_fma_f32 v188, v165, v190, v188
	v_fma_f32 v192, v165, v194, v192
	v_fma_f32 v189, v167, v191, v189
	v_fma_f32 v193, v167, v195, v193
	v_add_f32 v188, v188, v189
	v_add_f32 v192, v192, v193
	v_mul_f32 v196, v159, v196
	v_mul_f32 v197, v164, v197
	v_add_f32_dpp v188, v188, v188 quad_perm:[1,0,3,2] row_mask:0xf bank_mask:0xf bound_ctrl:1
	v_add_f32_dpp v192, v192, v192 quad_perm:[1,0,3,2] row_mask:0xf bank_mask:0xf bound_ctrl:1
	v_mul_f32 v198, v165, v198
	v_add_f32_dpp v188, v188, v188 quad_perm:[2,3,0,1] row_mask:0xf bank_mask:0xf bound_ctrl:1
	v_add_f32_dpp v192, v192, v192 quad_perm:[2,3,0,1] row_mask:0xf bank_mask:0xf bound_ctrl:1
	v_mul_f32 v199, v167, v199
	v_add_f32_dpp v188, v188, v188 row_half_mirror row_mask:0xf bank_mask:0xf bound_ctrl:1
	v_add_f32_dpp v192, v192, v192 row_half_mirror row_mask:0xf bank_mask:0xf bound_ctrl:1
	v_fma_f32 v196, v208, v204, v196
	v_add_f32_dpp v188, v188, v188 row_mirror row_mask:0xf bank_mask:0xf bound_ctrl:1
	v_add_f32_dpp v192, v192, v192 row_mirror row_mask:0xf bank_mask:0xf bound_ctrl:1
	v_fma_f32 v197, v208, v205, v197
	v_fma_f32 v198, v208, v206, v198
	v_fma_f32 v199, v208, v207, v199
	v_fma_f32 v159, -v188, v200, v196
	v_fma_f32 v164, -v188, v201, v197
	v_fma_f32 v165, -v188, v202, v198
	v_fma_f32 v167, -v188, v203, v199
	v_fma_f32 v192, -v188, v209, v192
	v_fma_f32 v192, v208, v210, v192
	ds_write_b32 v2, v192 offset:1216
	ds_read_b128 v[188:191], v3 offset:32256
	ds_read_b128 v[192:195], v3 offset:32512
	ds_read_b128 v[196:199], v3 offset:32768
	ds_read_b128 v[204:207], v3 offset:33280
	ds_read_b128 v[208:211], v4 offset:32256
	ds_read_b128 v[200:203], v3 offset:33024
	s_waitcnt lgkmcnt(7)
	v_mul_f32 v160, v159, v160
	v_mul_f32 v168, v159, v168
	v_mul_f32 v161, v164, v161
	v_mul_f32 v169, v164, v169
	v_fma_f32 v160, v165, v162, v160
	v_fma_f32 v168, v165, v170, v168
	v_fma_f32 v161, v167, v163, v161
	v_fma_f32 v169, v167, v171, v169
	v_add_f32 v160, v160, v161
	v_add_f32 v168, v168, v169
	v_mul_f32 v172, v159, v172
	v_mul_f32 v173, v164, v173
	v_add_f32_dpp v160, v160, v160 quad_perm:[1,0,3,2] row_mask:0xf bank_mask:0xf bound_ctrl:1
	v_add_f32_dpp v168, v168, v168 quad_perm:[1,0,3,2] row_mask:0xf bank_mask:0xf bound_ctrl:1
	v_mul_f32 v174, v165, v174
	v_add_f32_dpp v160, v160, v160 quad_perm:[2,3,0,1] row_mask:0xf bank_mask:0xf bound_ctrl:1
	v_add_f32_dpp v168, v168, v168 quad_perm:[2,3,0,1] row_mask:0xf bank_mask:0xf bound_ctrl:1
	v_mul_f32 v175, v167, v175
	v_add_f32_dpp v160, v160, v160 row_half_mirror row_mask:0xf bank_mask:0xf bound_ctrl:1
	v_add_f32_dpp v168, v168, v168 row_half_mirror row_mask:0xf bank_mask:0xf bound_ctrl:1
	v_fma_f32 v172, v184, v180, v172
	v_add_f32_dpp v160, v160, v160 row_mirror row_mask:0xf bank_mask:0xf bound_ctrl:1
	v_add_f32_dpp v168, v168, v168 row_mirror row_mask:0xf bank_mask:0xf bound_ctrl:1
	v_fma_f32 v173, v184, v181, v173
	v_fma_f32 v174, v184, v182, v174
	v_fma_f32 v175, v184, v183, v175
	v_fma_f32 v159, -v160, v176, v172
	v_fma_f32 v164, -v160, v177, v173
	v_fma_f32 v165, -v160, v178, v174
	v_fma_f32 v167, -v160, v179, v175
	v_fma_f32 v168, -v160, v185, v168
	v_fma_f32 v168, v184, v186, v168
	ds_write_b32 v2, v168 offset:1280
	ds_read_b128 v[160:163], v3 offset:33792
	ds_read_b128 v[168:171], v3 offset:34048
	ds_read_b128 v[172:175], v3 offset:34304
	ds_read_b128 v[180:183], v3 offset:34816
	ds_read_b128 v[184:187], v4 offset:33792
	ds_read_b128 v[176:179], v3 offset:34560
	s_waitcnt lgkmcnt(7)
; __device__ __forceinline__ float vfma(float a, float b, float c) { float d; asm("v_fma_f32 %0, %1, %2, %3" : "=v"(d) : "v"(a), "v"(b), "v"(c)); return d; }
; __device__ __forceinline__ float step_compute(float (&S)[4], const StepOp& o) {
;     float d1 = vmul(S[0], o.kk[0]), d2 = vmul(S[0], o.wr[0]), e1 = vmul(S[1], o.kk[1]), e2 = vmul(S[1], o.wr[1]);
;     d1 = vfma(S[2], o.kk[2], d1); d2 = vfma(S[2], o.wr[2], d2); e1 = vfma(S[3], o.kk[3], e1); e2 = vfma(S[3], o.wr[3], e2);
;     d1 = vadd(d1, e1); d2 = vadd(d2, e2);
;     float t0, t1, t2, t3;
;     asm volatile(
;         "v_mul_f32 %[t0], %[s0], %[w0]\n\t"
;         "v_mul_f32 %[t1], %[s1], %[w1]\n\t"
;         "v_add_f32_dpp %[d1], %[d1], %[d1] quad_perm:[1,0,3,2] row_mask:0xf bank_mask:0xf bound_ctrl:1\n\t"
;         "v_add_f32_dpp %[d2], %[d2], %[d2] quad_perm:[1,0,3,2] row_mask:0xf bank_mask:0xf bound_ctrl:1\n\t"
;         "v_mul_f32 %[t2], %[s2], %[w2]\n\t"
;         "v_add_f32_dpp %[d1], %[d1], %[d1] quad_perm:[2,3,0,1] row_mask:0xf bank_mask:0xf bound_ctrl:1\n\t"
;         "v_add_f32_dpp %[d2], %[d2], %[d2] quad_perm:[2,3,0,1] row_mask:0xf bank_mask:0xf bound_ctrl:1\n\t"
;         "v_mul_f32 %[t3], %[s3], %[w3]\n\t"
;         "v_add_f32_dpp %[d1], %[d1], %[d1] row_half_mirror row_mask:0xf bank_mask:0xf bound_ctrl:1\n\t"
;         "v_add_f32_dpp %[d2], %[d2], %[d2] row_half_mirror row_mask:0xf bank_mask:0xf bound_ctrl:1\n\t"
;         "v_fma_f32 %[t0], %[v], %[k0], %[t0]\n\t"
;         "v_add_f32_dpp %[d1], %[d1], %[d1] row_mirror row_mask:0xf bank_mask:0xf bound_ctrl:1\n\t"
;         "v_add_f32_dpp %[d2], %[d2], %[d2] row_mirror row_mask:0xf bank_mask:0xf bound_ctrl:1\n\t"
;         "v_fma_f32 %[t1], %[v], %[k1], %[t1]\n\t"
;         "v_fma_f32 %[t2], %[v], %[k2], %[t2]\n\t"
;         "v_fma_f32 %[t3], %[v], %[k3], %[t3]"
;         : [t0] "=&v"(t0), [t1] "=&v"(t1), [t2] "=&v"(t2), [t3] "=&v"(t3), [d1] "+v"(d1), [d2] "+v"(d2)
;         : [s0] "v"(S[0]), [s1] "v"(S[1]), [s2] "v"(S[2]), [s3] "v"(S[3]), [w0] "v"(o.w[0]), [w1] "v"(o.w[1]), [w2] "v"(o.w[2]), [w3] "v"(o.w[3]),
;           [k0] "v"(o.k[0]), [k1] "v"(o.k[1]), [k2] "v"(o.k[2]), [k3] "v"(o.k[3]), [v] "v"(o.q[0]));
;     S[0] = vnfma(d1, o.b[0], t0); S[1] = vnfma(d1, o.b[1], t1); S[2] = vnfma(d1, o.b[2], t2); S[3] = vnfma(d1, o.b[3], t3);
;     return vfma(o.q[0], o.q[2], vnfma(d1, o.q[1], d2));
; }
	v_mul_f32 v188, v159, v188
	v_mul_f32 v192, v159, v192
	v_mul_f32 v189, v164, v189
	v_mul_f32 v193, v164, v193
	v_fma_f32 v188, v165, v190, v188
	v_fma_f32 v192, v165, v194, v192
	v_fma_f32 v189, v167, v191, v189
	v_fma_f32 v193, v167, v195, v193
	v_add_f32 v188, v188, v189
	v_add_f32 v192, v192, v193
	v_mul_f32 v196, v159, v196
	v_mul_f32 v197, v164, v197
	v_add_f32_dpp v188, v188, v188 quad_perm:[1,0,3,2] row_mask:0xf bank_mask:0xf bound_ctrl:1
	v_add_f32_dpp v192, v192, v192 quad_perm:[1,0,3,2] row_mask:0xf bank_mask:0xf bound_ctrl:1
	v_mul_f32 v198, v165, v198
	v_add_f32_dpp v188, v188, v188 quad_perm:[2,3,0,1] row_mask:0xf bank_mask:0xf bound_ctrl:1
	v_add_f32_dpp v192, v192, v192 quad_perm:[2,3,0,1] row_mask:0xf bank_mask:0xf bound_ctrl:1
	v_mul_f32 v199, v167, v199
	v_add_f32_dpp v188, v188, v188 row_half_mirror row_mask:0xf bank_mask:0xf bound_ctrl:1
	v_add_f32_dpp v192, v192, v192 row_half_mirror row_mask:0xf bank_mask:0xf bound_ctrl:1
	v_fma_f32 v196, v208, v204, v196
	v_add_f32_dpp v188, v188, v188 row_mirror row_mask:0xf bank_mask:0xf bound_ctrl:1
	v_add_f32_dpp v192, v192, v192 row_mirror row_mask:0xf bank_mask:0xf bound_ctrl:1
	v_fma_f32 v197, v208, v205, v197
	v_fma_f32 v198, v208, v206, v198
	v_fma_f32 v199, v208, v207, v199
	v_fma_f32 v159, -v188, v200, v196
	v_fma_f32 v164, -v188, v201, v197
	v_fma_f32 v165, -v188, v202, v198
	v_fma_f32 v167, -v188, v203, v199
	v_fma_f32 v192, -v188, v209, v192
	v_fma_f32 v192, v208, v210, v192
	ds_write_b32 v2, v192 offset:1344
	ds_read_b128 v[188:191], v3 offset:35328
	ds_read_b128 v[192:195], v3 offset:35584
	ds_read_b128 v[196:199], v3 offset:35840
	ds_read_b128 v[204:207], v3 offset:36352
	ds_read_b128 v[208:211], v4 offset:35328
	ds_read_b128 v[200:203], v3 offset:36096
	s_waitcnt lgkmcnt(7)
	v_mul_f32 v160, v159, v160
	v_mul_f32 v168, v159, v168
	v_mul_f32 v161, v164, v161
	v_mul_f32 v169, v164, v169
	v_fma_f32 v160, v165, v162, v160
	v_fma_f32 v168, v165, v170, v168
	v_fma_f32 v161, v167, v163, v161
	v_fma_f32 v169, v167, v171, v169
	v_add_f32 v160, v160, v161
	v_add_f32 v168, v168, v169
	v_mul_f32 v172, v159, v172
	v_mul_f32 v173, v164, v173
	v_add_f32_dpp v160, v160, v160 quad_perm:[1,0,3,2] row_mask:0xf bank_mask:0xf bound_ctrl:1
	v_add_f32_dpp v168, v168, v168 quad_perm:[1,0,3,2] row_mask:0xf bank_mask:0xf bound_ctrl:1
	v_mul_f32 v174, v165, v174
	v_add_f32_dpp v160, v160, v160 quad_perm:[2,3,0,1] row_mask:0xf bank_mask:0xf bound_ctrl:1
	v_add_f32_dpp v168, v168, v168 quad_perm:[2,3,0,1] row_mask:0xf bank_mask:0xf bound_ctrl:1
	v_mul_f32 v175, v167, v175
	v_add_f32_dpp v160, v160, v160 row_half_mirror row_mask:0xf bank_mask:0xf bound_ctrl:1
	v_add_f32_dpp v168, v168, v168 row_half_mirror row_mask:0xf bank_mask:0xf bound_ctrl:1
	v_fma_f32 v172, v184, v180, v172
	v_add_f32_dpp v160, v160, v160 row_mirror row_mask:0xf bank_mask:0xf bound_ctrl:1
	v_add_f32_dpp v168, v168, v168 row_mirror row_mask:0xf bank_mask:0xf bound_ctrl:1
	v_fma_f32 v173, v184, v181, v173
	v_fma_f32 v174, v184, v182, v174
	v_fma_f32 v175, v184, v183, v175
	v_fma_f32 v159, -v160, v176, v172
	v_fma_f32 v164, -v160, v177, v173
	v_fma_f32 v165, -v160, v178, v174
	v_fma_f32 v167, -v160, v179, v175
	v_fma_f32 v168, -v160, v185, v168
	v_fma_f32 v168, v184, v186, v168
	ds_write_b32 v2, v168 offset:1408
	ds_read_b128 v[160:163], v3 offset:36864
	ds_read_b128 v[168:171], v3 offset:37120
	ds_read_b128 v[172:175], v3 offset:37376
	ds_read_b128 v[180:183], v3 offset:37888
	ds_read_b128 v[184:187], v4 offset:36864
	ds_read_b128 v[176:179], v3 offset:37632
	s_waitcnt lgkmcnt(7)
	v_mul_f32 v188, v159, v188
	v_mul_f32 v192, v159, v192
	v_mul_f32 v189, v164, v189
	v_mul_f32 v193, v164, v193
	v_fma_f32 v188, v165, v190, v188
	v_fma_f32 v192, v165, v194, v192
	v_fma_f32 v189, v167, v191, v189
	v_fma_f32 v193, v167, v195, v193
	v_add_f32 v188, v188, v189
	v_add_f32 v192, v192, v193
	v_mul_f32 v196, v159, v196
	v_mul_f32 v197, v164, v197
	v_add_f32_dpp v188, v188, v188 quad_perm:[1,0,3,2] row_mask:0xf bank_mask:0xf bound_ctrl:1
	v_add_f32_dpp v192, v192, v192 quad_perm:[1,0,3,2] row_mask:0xf bank_mask:0xf bound_ctrl:1
	v_mul_f32 v198, v165, v198
	v_add_f32_dpp v188, v188, v188 quad_perm:[2,3,0,1] row_mask:0xf bank_mask:0xf bound_ctrl:1
	v_add_f32_dpp v192, v192, v192 quad_perm:[2,3,0,1] row_mask:0xf bank_mask:0xf bound_ctrl:1
	v_mul_f32 v199, v167, v199
	v_add_f32_dpp v188, v188, v188 row_half_mirror row_mask:0xf bank_mask:0xf bound_ctrl:1
	v_add_f32_dpp v192, v192, v192 row_half_mirror row_mask:0xf bank_mask:0xf bound_ctrl:1
	v_fma_f32 v196, v208, v204, v196
	v_add_f32_dpp v188, v188, v188 row_mirror row_mask:0xf bank_mask:0xf bound_ctrl:1
	v_add_f32_dpp v192, v192, v192 row_mirror row_mask:0xf bank_mask:0xf bound_ctrl:1
	v_fma_f32 v197, v208, v205, v197
	v_fma_f32 v198, v208, v206, v198
	v_fma_f32 v199, v208, v207, v199
	v_fma_f32 v159, -v188, v200, v196
	v_fma_f32 v164, -v188, v201, v197
	v_fma_f32 v165, -v188, v202, v198
	v_fma_f32 v167, -v188, v203, v199
	v_fma_f32 v192, -v188, v209, v192
	v_fma_f32 v192, v208, v210, v192
	ds_write_b32 v2, v192 offset:1472
	ds_read_b128 v[188:191], v3 offset:38400
	ds_read_b128 v[192:195], v3 offset:38656
	ds_read_b128 v[196:199], v3 offset:38912
	ds_read_b128 v[204:207], v3 offset:39424
	ds_read_b128 v[208:211], v4 offset:38400
	ds_read_b128 v[200:203], v3 offset:39168
	s_waitcnt lgkmcnt(7)
; __device__ __forceinline__ float vfma(float a, float b, float c) { float d; asm("v_fma_f32 %0, %1, %2, %3" : "=v"(d) : "v"(a), "v"(b), "v"(c)); return d; }
; __device__ __forceinline__ float step_compute(float (&S)[4], const StepOp& o) {
;     float d1 = vmul(S[0], o.kk[0]), d2 = vmul(S[0], o.wr[0]), e1 = vmul(S[1], o.kk[1]), e2 = vmul(S[1], o.wr[1]);
;     d1 = vfma(S[2], o.kk[2], d1); d2 = vfma(S[2], o.wr[2], d2); e1 = vfma(S[3], o.kk[3], e1); e2 = vfma(S[3], o.wr[3], e2);
;     d1 = vadd(d1, e1); d2 = vadd(d2, e2);
;     float t0, t1, t2, t3;
;     asm volatile(
;         "v_mul_f32 %[t0], %[s0], %[w0]\n\t"
;         "v_mul_f32 %[t1], %[s1], %[w1]\n\t"
;         "v_add_f32_dpp %[d1], %[d1], %[d1] quad_perm:[1,0,3,2] row_mask:0xf bank_mask:0xf bound_ctrl:1\n\t"
;         "v_add_f32_dpp %[d2], %[d2], %[d2] quad_perm:[1,0,3,2] row_mask:0xf bank_mask:0xf bound_ctrl:1\n\t"
;         "v_mul_f32 %[t2], %[s2], %[w2]\n\t"
;         "v_add_f32_dpp %[d1], %[d1], %[d1] quad_perm:[2,3,0,1] row_mask:0xf bank_mask:0xf bound_ctrl:1\n\t"
;         "v_add_f32_dpp %[d2], %[d2], %[d2] quad_perm:[2,3,0,1] row_mask:0xf bank_mask:0xf bound_ctrl:1\n\t"
;         "v_mul_f32 %[t3], %[s3], %[w3]\n\t"
;         "v_add_f32_dpp %[d1], %[d1], %[d1] row_half_mirror row_mask:0xf bank_mask:0xf bound_ctrl:1\n\t"
;         "v_add_f32_dpp %[d2], %[d2], %[d2] row_half_mirror row_mask:0xf bank_mask:0xf bound_ctrl:1\n\t"
;         "v_fma_f32 %[t0], %[v], %[k0], %[t0]\n\t"
;         "v_add_f32_dpp %[d1], %[d1], %[d1] row_mirror row_mask:0xf bank_mask:0xf bound_ctrl:1\n\t"
;         "v_add_f32_dpp %[d2], %[d2], %[d2] row_mirror row_mask:0xf bank_mask:0xf bound_ctrl:1\n\t"
;         "v_fma_f32 %[t1], %[v], %[k1], %[t1]\n\t"
;         "v_fma_f32 %[t2], %[v], %[k2], %[t2]\n\t"
;         "v_fma_f32 %[t3], %[v], %[k3], %[t3]"
;         : [t0] "=&v"(t0), [t1] "=&v"(t1), [t2] "=&v"(t2), [t3] "=&v"(t3), [d1] "+v"(d1), [d2] "+v"(d2)
;         : [s0] "v"(S[0]), [s1] "v"(S[1]), [s2] "v"(S[2]), [s3] "v"(S[3]), [w0] "v"(o.w[0]), [w1] "v"(o.w[1]), [w2] "v"(o.w[2]), [w3] "v"(o.w[3]),
;           [k0] "v"(o.k[0]), [k1] "v"(o.k[1]), [k2] "v"(o.k[2]), [k3] "v"(o.k[3]), [v] "v"(o.q[0]));
;     S[0] = vnfma(d1, o.b[0], t0); S[1] = vnfma(d1, o.b[1], t1); S[2] = vnfma(d1, o.b[2], t2); S[3] = vnfma(d1, o.b[3], t3);
;     return vfma(o.q[0], o.q[2], vnfma(d1, o.q[1], d2));
; }
	v_mul_f32 v160, v159, v160
	v_mul_f32 v168, v159, v168
	v_mul_f32 v161, v164, v161
	v_mul_f32 v169, v164, v169
	v_fma_f32 v160, v165, v162, v160
	v_fma_f32 v168, v165, v170, v168
	v_fma_f32 v161, v167, v163, v161
	v_fma_f32 v169, v167, v171, v169
	v_add_f32 v160, v160, v161
	v_add_f32 v168, v168, v169
	v_mul_f32 v172, v159, v172
	v_mul_f32 v173, v164, v173
	v_add_f32_dpp v160, v160, v160 quad_perm:[1,0,3,2] row_mask:0xf bank_mask:0xf bound_ctrl:1
	v_add_f32_dpp v168, v168, v168 quad_perm:[1,0,3,2] row_mask:0xf bank_mask:0xf bound_ctrl:1
	v_mul_f32 v174, v165, v174
	v_add_f32_dpp v160, v160, v160 quad_perm:[2,3,0,1] row_mask:0xf bank_mask:0xf bound_ctrl:1
	v_add_f32_dpp v168, v168, v168 quad_perm:[2,3,0,1] row_mask:0xf bank_mask:0xf bound_ctrl:1
	v_mul_f32 v175, v167, v175
	v_add_f32_dpp v160, v160, v160 row_half_mirror row_mask:0xf bank_mask:0xf bound_ctrl:1
	v_add_f32_dpp v168, v168, v168 row_half_mirror row_mask:0xf bank_mask:0xf bound_ctrl:1
	v_fma_f32 v172, v184, v180, v172
	v_add_f32_dpp v160, v160, v160 row_mirror row_mask:0xf bank_mask:0xf bound_ctrl:1
	v_add_f32_dpp v168, v168, v168 row_mirror row_mask:0xf bank_mask:0xf bound_ctrl:1
	v_fma_f32 v173, v184, v181, v173
	v_fma_f32 v174, v184, v182, v174
	v_fma_f32 v175, v184, v183, v175
	v_fma_f32 v159, -v160, v176, v172
	v_fma_f32 v164, -v160, v177, v173
	v_fma_f32 v165, -v160, v178, v174
	v_fma_f32 v167, -v160, v179, v175
	v_fma_f32 v168, -v160, v185, v168
	v_fma_f32 v168, v184, v186, v168
	ds_write_b32 v2, v168 offset:1536
	ds_read_b128 v[160:163], v3 offset:39936
	ds_read_b128 v[168:171], v3 offset:40192
	ds_read_b128 v[172:175], v3 offset:40448
	ds_read_b128 v[180:183], v3 offset:40960
	ds_read_b128 v[184:187], v4 offset:39936
	ds_read_b128 v[176:179], v3 offset:40704
	s_waitcnt lgkmcnt(7)
	v_mul_f32 v188, v159, v188
	v_mul_f32 v192, v159, v192
	v_mul_f32 v189, v164, v189
	v_mul_f32 v193, v164, v193
	v_fma_f32 v188, v165, v190, v188
	v_fma_f32 v192, v165, v194, v192
	v_fma_f32 v189, v167, v191, v189
	v_fma_f32 v193, v167, v195, v193
	v_add_f32 v188, v188, v189
	v_add_f32 v192, v192, v193
	v_mul_f32 v196, v159, v196
	v_mul_f32 v197, v164, v197
	v_add_f32_dpp v188, v188, v188 quad_perm:[1,0,3,2] row_mask:0xf bank_mask:0xf bound_ctrl:1
	v_add_f32_dpp v192, v192, v192 quad_perm:[1,0,3,2] row_mask:0xf bank_mask:0xf bound_ctrl:1
	v_mul_f32 v198, v165, v198
	v_add_f32_dpp v188, v188, v188 quad_perm:[2,3,0,1] row_mask:0xf bank_mask:0xf bound_ctrl:1
	v_add_f32_dpp v192, v192, v192 quad_perm:[2,3,0,1] row_mask:0xf bank_mask:0xf bound_ctrl:1
	v_mul_f32 v199, v167, v199
	v_add_f32_dpp v188, v188, v188 row_half_mirror row_mask:0xf bank_mask:0xf bound_ctrl:1
	v_add_f32_dpp v192, v192, v192 row_half_mirror row_mask:0xf bank_mask:0xf bound_ctrl:1
	v_fma_f32 v196, v208, v204, v196
	v_add_f32_dpp v188, v188, v188 row_mirror row_mask:0xf bank_mask:0xf bound_ctrl:1
	v_add_f32_dpp v192, v192, v192 row_mirror row_mask:0xf bank_mask:0xf bound_ctrl:1
	v_fma_f32 v197, v208, v205, v197
	v_fma_f32 v198, v208, v206, v198
	v_fma_f32 v199, v208, v207, v199
	v_fma_f32 v159, -v188, v200, v196
	v_fma_f32 v164, -v188, v201, v197
	v_fma_f32 v165, -v188, v202, v198
	v_fma_f32 v167, -v188, v203, v199
	v_fma_f32 v192, -v188, v209, v192
	v_fma_f32 v192, v208, v210, v192
	ds_write_b32 v2, v192 offset:1600
	ds_read_b128 v[188:191], v3 offset:41472
	ds_read_b128 v[192:195], v3 offset:41728
	ds_read_b128 v[196:199], v3 offset:41984
	ds_read_b128 v[204:207], v3 offset:42496
	ds_read_b128 v[208:211], v4 offset:41472
	ds_read_b128 v[200:203], v3 offset:42240
	s_waitcnt lgkmcnt(7)
	v_mul_f32 v160, v159, v160
	v_mul_f32 v168, v159, v168
	v_mul_f32 v161, v164, v161
	v_mul_f32 v169, v164, v169
	v_fma_f32 v160, v165, v162, v160
	v_fma_f32 v168, v165, v170, v168
	v_fma_f32 v161, v167, v163, v161
	v_fma_f32 v169, v167, v171, v169
	v_add_f32 v160, v160, v161
	v_add_f32 v168, v168, v169
	v_mul_f32 v172, v159, v172
	v_mul_f32 v173, v164, v173
	v_add_f32_dpp v160, v160, v160 quad_perm:[1,0,3,2] row_mask:0xf bank_mask:0xf bound_ctrl:1
	v_add_f32_dpp v168, v168, v168 quad_perm:[1,0,3,2] row_mask:0xf bank_mask:0xf bound_ctrl:1
	v_mul_f32 v174, v165, v174
	v_add_f32_dpp v160, v160, v160 quad_perm:[2,3,0,1] row_mask:0xf bank_mask:0xf bound_ctrl:1
	v_add_f32_dpp v168, v168, v168 quad_perm:[2,3,0,1] row_mask:0xf bank_mask:0xf bound_ctrl:1
	v_mul_f32 v175, v167, v175
	v_add_f32_dpp v160, v160, v160 row_half_mirror row_mask:0xf bank_mask:0xf bound_ctrl:1
	v_add_f32_dpp v168, v168, v168 row_half_mirror row_mask:0xf bank_mask:0xf bound_ctrl:1
	v_fma_f32 v172, v184, v180, v172
	v_add_f32_dpp v160, v160, v160 row_mirror row_mask:0xf bank_mask:0xf bound_ctrl:1
	v_add_f32_dpp v168, v168, v168 row_mirror row_mask:0xf bank_mask:0xf bound_ctrl:1
	v_fma_f32 v173, v184, v181, v173
	v_fma_f32 v174, v184, v182, v174
	v_fma_f32 v175, v184, v183, v175
	v_fma_f32 v159, -v160, v176, v172
	v_fma_f32 v164, -v160, v177, v173
	v_fma_f32 v165, -v160, v178, v174
	v_fma_f32 v167, -v160, v179, v175
	v_fma_f32 v168, -v160, v185, v168
	v_fma_f32 v168, v184, v186, v168
	ds_write_b32 v2, v168 offset:1664
	ds_read_b128 v[160:163], v3 offset:43008
	ds_read_b128 v[168:171], v3 offset:43264
	ds_read_b128 v[172:175], v3 offset:43520
	ds_read_b128 v[180:183], v3 offset:44032
	ds_read_b128 v[184:187], v4 offset:43008
	ds_read_b128 v[176:179], v3 offset:43776
	s_waitcnt lgkmcnt(7)
; __device__ __forceinline__ float vfma(float a, float b, float c) { float d; asm("v_fma_f32 %0, %1, %2, %3" : "=v"(d) : "v"(a), "v"(b), "v"(c)); return d; }
; __device__ __forceinline__ float step_compute(float (&S)[4], const StepOp& o) {
;     float d1 = vmul(S[0], o.kk[0]), d2 = vmul(S[0], o.wr[0]), e1 = vmul(S[1], o.kk[1]), e2 = vmul(S[1], o.wr[1]);
;     d1 = vfma(S[2], o.kk[2], d1); d2 = vfma(S[2], o.wr[2], d2); e1 = vfma(S[3], o.kk[3], e1); e2 = vfma(S[3], o.wr[3], e2);
;     d1 = vadd(d1, e1); d2 = vadd(d2, e2);
;     float t0, t1, t2, t3;
;     asm volatile(
;         "v_mul_f32 %[t0], %[s0], %[w0]\n\t"
;         "v_mul_f32 %[t1], %[s1], %[w1]\n\t"
;         "v_add_f32_dpp %[d1], %[d1], %[d1] quad_perm:[1,0,3,2] row_mask:0xf bank_mask:0xf bound_ctrl:1\n\t"
;         "v_add_f32_dpp %[d2], %[d2], %[d2] quad_perm:[1,0,3,2] row_mask:0xf bank_mask:0xf bound_ctrl:1\n\t"
;         "v_mul_f32 %[t2], %[s2], %[w2]\n\t"
;         "v_add_f32_dpp %[d1], %[d1], %[d1] quad_perm:[2,3,0,1] row_mask:0xf bank_mask:0xf bound_ctrl:1\n\t"
;         "v_add_f32_dpp %[d2], %[d2], %[d2] quad_perm:[2,3,0,1] row_mask:0xf bank_mask:0xf bound_ctrl:1\n\t"
;         "v_mul_f32 %[t3], %[s3], %[w3]\n\t"
;         "v_add_f32_dpp %[d1], %[d1], %[d1] row_half_mirror row_mask:0xf bank_mask:0xf bound_ctrl:1\n\t"
;         "v_add_f32_dpp %[d2], %[d2], %[d2] row_half_mirror row_mask:0xf bank_mask:0xf bound_ctrl:1\n\t"
;         "v_fma_f32 %[t0], %[v], %[k0], %[t0]\n\t"
;         "v_add_f32_dpp %[d1], %[d1], %[d1] row_mirror row_mask:0xf bank_mask:0xf bound_ctrl:1\n\t"
;         "v_add_f32_dpp %[d2], %[d2], %[d2] row_mirror row_mask:0xf bank_mask:0xf bound_ctrl:1\n\t"
;         "v_fma_f32 %[t1], %[v], %[k1], %[t1]\n\t"
;         "v_fma_f32 %[t2], %[v], %[k2], %[t2]\n\t"
;         "v_fma_f32 %[t3], %[v], %[k3], %[t3]"
;         : [t0] "=&v"(t0), [t1] "=&v"(t1), [t2] "=&v"(t2), [t3] "=&v"(t3), [d1] "+v"(d1), [d2] "+v"(d2)
;         : [s0] "v"(S[0]), [s1] "v"(S[1]), [s2] "v"(S[2]), [s3] "v"(S[3]), [w0] "v"(o.w[0]), [w1] "v"(o.w[1]), [w2] "v"(o.w[2]), [w3] "v"(o.w[3]),
;           [k0] "v"(o.k[0]), [k1] "v"(o.k[1]), [k2] "v"(o.k[2]), [k3] "v"(o.k[3]), [v] "v"(o.q[0]));
;     S[0] = vnfma(d1, o.b[0], t0); S[1] = vnfma(d1, o.b[1], t1); S[2] = vnfma(d1, o.b[2], t2); S[3] = vnfma(d1, o.b[3], t3);
;     return vfma(o.q[0], o.q[2], vnfma(d1, o.q[1], d2));
; }
	v_mul_f32 v188, v159, v188
	v_mul_f32 v192, v159, v192
	v_mul_f32 v189, v164, v189
	v_mul_f32 v193, v164, v193
	v_fma_f32 v188, v165, v190, v188
	v_fma_f32 v192, v165, v194, v192
	v_fma_f32 v189, v167, v191, v189
	v_fma_f32 v193, v167, v195, v193
	v_add_f32 v188, v188, v189
	v_add_f32 v192, v192, v193
	v_mul_f32 v196, v159, v196
	v_mul_f32 v197, v164, v197
	v_add_f32_dpp v188, v188, v188 quad_perm:[1,0,3,2] row_mask:0xf bank_mask:0xf bound_ctrl:1
	v_add_f32_dpp v192, v192, v192 quad_perm:[1,0,3,2] row_mask:0xf bank_mask:0xf bound_ctrl:1
	v_mul_f32 v198, v165, v198
	v_add_f32_dpp v188, v188, v188 quad_perm:[2,3,0,1] row_mask:0xf bank_mask:0xf bound_ctrl:1
	v_add_f32_dpp v192, v192, v192 quad_perm:[2,3,0,1] row_mask:0xf bank_mask:0xf bound_ctrl:1
	v_mul_f32 v199, v167, v199
	v_add_f32_dpp v188, v188, v188 row_half_mirror row_mask:0xf bank_mask:0xf bound_ctrl:1
	v_add_f32_dpp v192, v192, v192 row_half_mirror row_mask:0xf bank_mask:0xf bound_ctrl:1
	v_fma_f32 v196, v208, v204, v196
	v_add_f32_dpp v188, v188, v188 row_mirror row_mask:0xf bank_mask:0xf bound_ctrl:1
	v_add_f32_dpp v192, v192, v192 row_mirror row_mask:0xf bank_mask:0xf bound_ctrl:1
	v_fma_f32 v197, v208, v205, v197
	v_fma_f32 v198, v208, v206, v198
	v_fma_f32 v199, v208, v207, v199
	v_fma_f32 v159, -v188, v200, v196
	v_fma_f32 v164, -v188, v201, v197
	v_fma_f32 v165, -v188, v202, v198
	v_fma_f32 v167, -v188, v203, v199
	v_fma_f32 v192, -v188, v209, v192
	v_fma_f32 v192, v208, v210, v192
	ds_write_b32 v2, v192 offset:1728
	ds_read_b128 v[188:191], v3 offset:44544
	ds_read_b128 v[192:195], v3 offset:44800
	ds_read_b128 v[196:199], v3 offset:45056
	ds_read_b128 v[204:207], v3 offset:45568
	ds_read_b128 v[208:211], v4 offset:44544
	ds_read_b128 v[200:203], v3 offset:45312
	s_waitcnt lgkmcnt(7)
	v_mul_f32 v160, v159, v160
	v_mul_f32 v168, v159, v168
	v_mul_f32 v161, v164, v161
	v_mul_f32 v169, v164, v169
	v_fma_f32 v160, v165, v162, v160
	v_fma_f32 v168, v165, v170, v168
	v_fma_f32 v161, v167, v163, v161
	v_fma_f32 v169, v167, v171, v169
	v_add_f32 v160, v160, v161
	v_add_f32 v168, v168, v169
	v_mul_f32 v172, v159, v172
	v_mul_f32 v173, v164, v173
	v_add_f32_dpp v160, v160, v160 quad_perm:[1,0,3,2] row_mask:0xf bank_mask:0xf bound_ctrl:1
	v_add_f32_dpp v168, v168, v168 quad_perm:[1,0,3,2] row_mask:0xf bank_mask:0xf bound_ctrl:1
	v_mul_f32 v174, v165, v174
	v_add_f32_dpp v160, v160, v160 quad_perm:[2,3,0,1] row_mask:0xf bank_mask:0xf bound_ctrl:1
	v_add_f32_dpp v168, v168, v168 quad_perm:[2,3,0,1] row_mask:0xf bank_mask:0xf bound_ctrl:1
	v_mul_f32 v175, v167, v175
	v_add_f32_dpp v160, v160, v160 row_half_mirror row_mask:0xf bank_mask:0xf bound_ctrl:1
	v_add_f32_dpp v168, v168, v168 row_half_mirror row_mask:0xf bank_mask:0xf bound_ctrl:1
	v_fma_f32 v172, v184, v180, v172
	v_add_f32_dpp v160, v160, v160 row_mirror row_mask:0xf bank_mask:0xf bound_ctrl:1
	v_add_f32_dpp v168, v168, v168 row_mirror row_mask:0xf bank_mask:0xf bound_ctrl:1
	v_fma_f32 v173, v184, v181, v173
	v_fma_f32 v174, v184, v182, v174
	v_fma_f32 v175, v184, v183, v175
	v_fma_f32 v159, -v160, v176, v172
	v_fma_f32 v164, -v160, v177, v173
	v_fma_f32 v165, -v160, v178, v174
	v_fma_f32 v167, -v160, v179, v175
	v_fma_f32 v168, -v160, v185, v168
	v_fma_f32 v168, v184, v186, v168
	ds_write_b32 v2, v168 offset:1792
	ds_read_b128 v[160:163], v3 offset:46080
	ds_read_b128 v[168:171], v3 offset:46336
	ds_read_b128 v[172:175], v3 offset:46592
	ds_read_b128 v[180:183], v3 offset:47104
	ds_read_b128 v[184:187], v4 offset:46080
	ds_read_b128 v[176:179], v3 offset:46848
	s_waitcnt lgkmcnt(7)
; __device__ __forceinline__ float vfma(float a, float b, float c) { float d; asm("v_fma_f32 %0, %1, %2, %3" : "=v"(d) : "v"(a), "v"(b), "v"(c)); return d; }
; __device__ __forceinline__ float step_compute(float (&S)[4], const StepOp& o) {
;     float d1 = vmul(S[0], o.kk[0]), d2 = vmul(S[0], o.wr[0]), e1 = vmul(S[1], o.kk[1]), e2 = vmul(S[1], o.wr[1]);
;     d1 = vfma(S[2], o.kk[2], d1); d2 = vfma(S[2], o.wr[2], d2); e1 = vfma(S[3], o.kk[3], e1); e2 = vfma(S[3], o.wr[3], e2);
;     d1 = vadd(d1, e1); d2 = vadd(d2, e2);
;     float t0, t1, t2, t3;
;     asm volatile(
;         "v_mul_f32 %[t0], %[s0], %[w0]\n\t"
;         "v_mul_f32 %[t1], %[s1], %[w1]\n\t"
;         "v_add_f32_dpp %[d1], %[d1], %[d1] quad_perm:[1,0,3,2] row_mask:0xf bank_mask:0xf bound_ctrl:1\n\t"
;         "v_add_f32_dpp %[d2], %[d2], %[d2] quad_perm:[1,0,3,2] row_mask:0xf bank_mask:0xf bound_ctrl:1\n\t"
;         "v_mul_f32 %[t2], %[s2], %[w2]\n\t"
;         "v_add_f32_dpp %[d1], %[d1], %[d1] quad_perm:[2,3,0,1] row_mask:0xf bank_mask:0xf bound_ctrl:1\n\t"
;         "v_add_f32_dpp %[d2], %[d2], %[d2] quad_perm:[2,3,0,1] row_mask:0xf bank_mask:0xf bound_ctrl:1\n\t"
;         "v_mul_f32 %[t3], %[s3], %[w3]\n\t"
;         "v_add_f32_dpp %[d1], %[d1], %[d1] row_half_mirror row_mask:0xf bank_mask:0xf bound_ctrl:1\n\t"
;         "v_add_f32_dpp %[d2], %[d2], %[d2] row_half_mirror row_mask:0xf bank_mask:0xf bound_ctrl:1\n\t"
;         "v_fma_f32 %[t0], %[v], %[k0], %[t0]\n\t"
;         "v_add_f32_dpp %[d1], %[d1], %[d1] row_mirror row_mask:0xf bank_mask:0xf bound_ctrl:1\n\t"
;         "v_add_f32_dpp %[d2], %[d2], %[d2] row_mirror row_mask:0xf bank_mask:0xf bound_ctrl:1\n\t"
;         "v_fma_f32 %[t1], %[v], %[k1], %[t1]\n\t"
;         "v_fma_f32 %[t2], %[v], %[k2], %[t2]\n\t"
;         "v_fma_f32 %[t3], %[v], %[k3], %[t3]"
;         : [t0] "=&v"(t0), [t1] "=&v"(t1), [t2] "=&v"(t2), [t3] "=&v"(t3), [d1] "+v"(d1), [d2] "+v"(d2)
;         : [s0] "v"(S[0]), [s1] "v"(S[1]), [s2] "v"(S[2]), [s3] "v"(S[3]), [w0] "v"(o.w[0]), [w1] "v"(o.w[1]), [w2] "v"(o.w[2]), [w3] "v"(o.w[3]),
;           [k0] "v"(o.k[0]), [k1] "v"(o.k[1]), [k2] "v"(o.k[2]), [k3] "v"(o.k[3]), [v] "v"(o.q[0]));
;     S[0] = vnfma(d1, o.b[0], t0); S[1] = vnfma(d1, o.b[1], t1); S[2] = vnfma(d1, o.b[2], t2); S[3] = vnfma(d1, o.b[3], t3);
;     return vfma(o.q[0], o.q[2], vnfma(d1, o.q[1], d2));
; }
	v_mul_f32 v188, v159, v188
	v_mul_f32 v192, v159, v192
	v_mul_f32 v189, v164, v189
	v_mul_f32 v193, v164, v193
	v_fma_f32 v188, v165, v190, v188
	v_fma_f32 v192, v165, v194, v192
	v_fma_f32 v189, v167, v191, v189
	v_fma_f32 v193, v167, v195, v193
	v_add_f32 v188, v188, v189
	v_add_f32 v192, v192, v193
	v_mul_f32 v196, v159, v196
	v_mul_f32 v197, v164, v197
	v_add_f32_dpp v188, v188, v188 quad_perm:[1,0,3,2] row_mask:0xf bank_mask:0xf bound_ctrl:1
	v_add_f32_dpp v192, v192, v192 quad_perm:[1,0,3,2] row_mask:0xf bank_mask:0xf bound_ctrl:1
	v_mul_f32 v198, v165, v198
	v_add_f32_dpp v188, v188, v188 quad_perm:[2,3,0,1] row_mask:0xf bank_mask:0xf bound_ctrl:1
	v_add_f32_dpp v192, v192, v192 quad_perm:[2,3,0,1] row_mask:0xf bank_mask:0xf bound_ctrl:1
	v_mul_f32 v199, v167, v199
	v_add_f32_dpp v188, v188, v188 row_half_mirror row_mask:0xf bank_mask:0xf bound_ctrl:1
	v_add_f32_dpp v192, v192, v192 row_half_mirror row_mask:0xf bank_mask:0xf bound_ctrl:1
	v_fma_f32 v196, v208, v204, v196
	v_add_f32_dpp v188, v188, v188 row_mirror row_mask:0xf bank_mask:0xf bound_ctrl:1
	v_add_f32_dpp v192, v192, v192 row_mirror row_mask:0xf bank_mask:0xf bound_ctrl:1
	v_fma_f32 v197, v208, v205, v197
	v_fma_f32 v198, v208, v206, v198
	v_fma_f32 v199, v208, v207, v199
	v_fma_f32 v159, -v188, v200, v196
	v_fma_f32 v164, -v188, v201, v197
	v_fma_f32 v165, -v188, v202, v198
	v_fma_f32 v167, -v188, v203, v199
	v_fma_f32 v192, -v188, v209, v192
	v_fma_f32 v192, v208, v210, v192
	ds_write_b32 v2, v192 offset:1856
	ds_read_b128 v[188:191], v3 offset:47616
	ds_read_b128 v[192:195], v3 offset:47872
	ds_read_b128 v[196:199], v3 offset:48128
	ds_read_b128 v[204:207], v3 offset:48640
	ds_read_b128 v[208:211], v4 offset:47616
	ds_read_b128 v[200:203], v3 offset:48384
	s_waitcnt lgkmcnt(7)
	v_mul_f32 v160, v159, v160
	v_mul_f32 v168, v159, v168
	v_mul_f32 v161, v164, v161
	v_mul_f32 v169, v164, v169
	v_fma_f32 v160, v165, v162, v160
	v_fma_f32 v168, v165, v170, v168
	v_fma_f32 v161, v167, v163, v161
	v_fma_f32 v169, v167, v171, v169
	v_add_f32 v160, v160, v161
	v_add_f32 v168, v168, v169
	v_mul_f32 v172, v159, v172
	v_mul_f32 v173, v164, v173
	v_add_f32_dpp v160, v160, v160 quad_perm:[1,0,3,2] row_mask:0xf bank_mask:0xf bound_ctrl:1
	v_add_f32_dpp v168, v168, v168 quad_perm:[1,0,3,2] row_mask:0xf bank_mask:0xf bound_ctrl:1
	v_mul_f32 v174, v165, v174
	v_add_f32_dpp v160, v160, v160 quad_perm:[2,3,0,1] row_mask:0xf bank_mask:0xf bound_ctrl:1
	v_add_f32_dpp v168, v168, v168 quad_perm:[2,3,0,1] row_mask:0xf bank_mask:0xf bound_ctrl:1
	v_mul_f32 v175, v167, v175
	v_add_f32_dpp v160, v160, v160 row_half_mirror row_mask:0xf bank_mask:0xf bound_ctrl:1
	v_add_f32_dpp v168, v168, v168 row_half_mirror row_mask:0xf bank_mask:0xf bound_ctrl:1
	v_fma_f32 v172, v184, v180, v172
	v_add_f32_dpp v160, v160, v160 row_mirror row_mask:0xf bank_mask:0xf bound_ctrl:1
	v_add_f32_dpp v168, v168, v168 row_mirror row_mask:0xf bank_mask:0xf bound_ctrl:1
	v_fma_f32 v173, v184, v181, v173
	v_fma_f32 v174, v184, v182, v174
	v_fma_f32 v175, v184, v183, v175
	v_fma_f32 v159, -v160, v176, v172
	v_fma_f32 v164, -v160, v177, v173
	v_fma_f32 v165, -v160, v178, v174
	v_fma_f32 v167, -v160, v179, v175
	v_fma_f32 v168, -v160, v185, v168
	v_fma_f32 v168, v184, v186, v168
	ds_write_b32 v2, v168 offset:1920
	s_waitcnt lgkmcnt(1)
	v_mul_f32 v188, v159, v188
	v_mul_f32 v192, v159, v192
	v_mul_f32 v189, v164, v189
	v_mul_f32 v193, v164, v193
	v_fma_f32 v188, v165, v190, v188
	v_fma_f32 v192, v165, v194, v192
	v_fma_f32 v189, v167, v191, v189
	v_fma_f32 v193, v167, v195, v193
	v_add_f32 v188, v188, v189
	v_add_f32 v192, v192, v193
	v_mul_f32 v196, v159, v196
	v_mul_f32 v197, v164, v197
	v_add_f32_dpp v188, v188, v188 quad_perm:[1,0,3,2] row_mask:0xf bank_mask:0xf bound_ctrl:1
	v_add_f32_dpp v192, v192, v192 quad_perm:[1,0,3,2] row_mask:0xf bank_mask:0xf bound_ctrl:1
	v_mul_f32 v198, v165, v198
	v_add_f32_dpp v188, v188, v188 quad_perm:[2,3,0,1] row_mask:0xf bank_mask:0xf bound_ctrl:1
	v_add_f32_dpp v192, v192, v192 quad_perm:[2,3,0,1] row_mask:0xf bank_mask:0xf bound_ctrl:1
	v_mul_f32 v199, v167, v199
	v_add_f32_dpp v188, v188, v188 row_half_mirror row_mask:0xf bank_mask:0xf bound_ctrl:1
	v_add_f32_dpp v192, v192, v192 row_half_mirror row_mask:0xf bank_mask:0xf bound_ctrl:1
	v_fma_f32 v196, v208, v204, v196
	v_add_f32_dpp v188, v188, v188 row_mirror row_mask:0xf bank_mask:0xf bound_ctrl:1
	v_add_f32_dpp v192, v192, v192 row_mirror row_mask:0xf bank_mask:0xf bound_ctrl:1
	v_fma_f32 v197, v208, v205, v197
	v_fma_f32 v198, v208, v206, v198
	v_fma_f32 v199, v208, v207, v199
	v_fma_f32 v3, -v188, v200, v196
	v_fma_f32 v4, -v188, v201, v197
	v_fma_f32 v115, -v188, v202, v198
	v_fma_f32 v159, -v188, v203, v199
	v_fma_f32 v192, -v188, v209, v192
	v_fma_f32 v192, v208, v210, v192
	ds_write_b32 v2, v192 offset:1984
